# v3 + 32-MFMA Gray-path order per super-phase, transposed traversal (m-major), accumulate pairs back to back
# speedup vs baseline: 1.0008x; 1.0008x over previous
.LBB0_472:
	ds_read_b128 v[152:155], v148
	ds_read_b128 v[156:159], v148 offset:1024
	ds_read_b128 v[166:169], v148 offset:2048
	ds_read_b128 v[170:173], v148 offset:3072
	ds_read_b128 v[174:177], v149
	ds_read_b128 v[178:181], v149 offset:1024
	ds_read_b128 v[182:185], v149 offset:2048
	ds_read_b128 v[186:189], v149 offset:3072
	s_add_u32 s44, s54, 0xfff00080
	s_addc_u32 s56, s55, -1
	s_cmp_eq_u32 s72, 60
	s_cselect_b32 s59, s17, s56
	s_cselect_b32 s58, s68, s44
	s_cselect_b32 s57, s15, s71
	s_cselect_b32 s56, s69, s70
	v_lshl_add_u64 v[160:161], s[54:55], 0, v[138:139]
	s_add_i32 m0, s41, 0xc000
	ds_read_b128 v[190:193], v150
	ds_read_b128 v[194:197], v150 offset:1024
	ds_read_b128 v[198:201], v150 offset:2048
	ds_read_b128 v[202:205], v150 offset:3072
	ds_read_b128 v[206:209], v150 offset:4096
	ds_read_b128 v[210:213], v150 offset:5120
	ds_read_b128 v[214:217], v150 offset:6144
	ds_read_b128 v[218:221], v150 offset:7168
	global_load_lds_dwordx4 v[160:161], off
	v_lshl_add_u64 v[160:161], s[54:55], 0, v[140:141]
	s_add_i32 m0, s41, 0xe000
	s_nop 0
	global_load_lds_dwordx4 v[160:161], off
	s_waitcnt vmcnt(8)
	s_waitcnt lgkmcnt(0)
	s_barrier
	s_setprio 1
	s_waitcnt lgkmcnt(0)
	v_mfma_f32_16x16x32_bf16 v[126:129], v[152:155], v[190:193], v[126:129]
	v_mfma_f32_16x16x32_bf16 v[126:129], v[156:159], v[194:197], v[126:129]
	v_mfma_f32_16x16x32_bf16 v[118:121], v[156:159], v[202:205], v[118:121]
	v_mfma_f32_16x16x32_bf16 v[118:121], v[152:155], v[198:201], v[118:121]
	v_mfma_f32_16x16x32_bf16 v[102:105], v[152:155], v[206:209], v[102:105]
	v_mfma_f32_16x16x32_bf16 v[102:105], v[156:159], v[210:213], v[102:105]
	v_mfma_f32_16x16x32_bf16 v[86:89], v[156:159], v[218:221], v[86:89]
	v_mfma_f32_16x16x32_bf16 v[86:89], v[152:155], v[214:217], v[86:89]
	v_mfma_f32_16x16x32_bf16 v[78:81], v[166:169], v[214:217], v[78:81]
	v_mfma_f32_16x16x32_bf16 v[78:81], v[170:173], v[218:221], v[78:81]
	v_mfma_f32_16x16x32_bf16 v[94:97], v[170:173], v[210:213], v[94:97]
	v_mfma_f32_16x16x32_bf16 v[94:97], v[166:169], v[206:209], v[94:97]
	v_mfma_f32_16x16x32_bf16 v[110:113], v[166:169], v[198:201], v[110:113]
	v_mfma_f32_16x16x32_bf16 v[110:113], v[170:173], v[202:205], v[110:113]
	v_mfma_f32_16x16x32_bf16 v[122:125], v[170:173], v[194:197], v[122:125]
	v_mfma_f32_16x16x32_bf16 v[122:125], v[166:169], v[190:193], v[122:125]
	v_mfma_f32_16x16x32_bf16 v[114:117], v[174:177], v[190:193], v[114:117]
	v_mfma_f32_16x16x32_bf16 v[114:117], v[178:181], v[194:197], v[114:117]
	v_mfma_f32_16x16x32_bf16 v[98:101], v[178:181], v[202:205], v[98:101]
	v_mfma_f32_16x16x32_bf16 v[98:101], v[174:177], v[198:201], v[98:101]
	v_mfma_f32_16x16x32_bf16 v[82:85], v[174:177], v[206:209], v[82:85]
	v_mfma_f32_16x16x32_bf16 v[82:85], v[178:181], v[210:213], v[82:85]
	v_mfma_f32_16x16x32_bf16 v[70:73], v[178:181], v[218:221], v[70:73]
	v_mfma_f32_16x16x32_bf16 v[70:73], v[174:177], v[214:217], v[70:73]
	v_mfma_f32_16x16x32_bf16 v[66:69], v[182:185], v[214:217], v[66:69]
	v_mfma_f32_16x16x32_bf16 v[66:69], v[186:189], v[218:221], v[66:69]
	v_mfma_f32_16x16x32_bf16 v[74:77], v[186:189], v[210:213], v[74:77]
	v_mfma_f32_16x16x32_bf16 v[74:77], v[182:185], v[206:209], v[74:77]
	v_mfma_f32_16x16x32_bf16 v[90:93], v[182:185], v[198:201], v[90:93]
	v_mfma_f32_16x16x32_bf16 v[90:93], v[186:189], v[202:205], v[90:93]
	v_mfma_f32_16x16x32_bf16 v[106:109], v[186:189], v[194:197], v[106:109]
	v_mfma_f32_16x16x32_bf16 v[106:109], v[182:185], v[190:193], v[106:109]
	s_setprio 0
	s_barrier
	s_add_i32 s44, s64, s27
	v_lshl_add_u64 v[160:161], s[56:57], 0, v[134:135]
	s_mov_b32 m0, s44
	ds_read_b128 v[190:193], v150 offset:16384
	ds_read_b128 v[194:197], v150 offset:17408
	ds_read_b128 v[198:201], v150 offset:18432
	ds_read_b128 v[202:205], v150 offset:19456
	ds_read_b128 v[206:209], v150 offset:20480
	ds_read_b128 v[210:213], v150 offset:21504
	ds_read_b128 v[214:217], v150 offset:22528
	ds_read_b128 v[218:221], v150 offset:23552
	global_load_lds_dwordx4 v[160:161], off
	s_add_i32 m0, s44, 0x2000
	s_add_u32 s74, s56, 0x100000
	v_lshl_add_u64 v[222:223], s[56:57], 0, v[130:131]
	s_addc_u32 s75, s57, 0
	s_add_i32 s44, s65, s27
	global_load_lds_dwordx4 v[222:223], off
	v_lshl_add_u64 v[224:225], s[74:75], 0, v[134:135]
	s_mov_b32 m0, s44
	v_lshl_add_u64 v[226:227], s[58:59], 0, v[132:133]
	global_load_lds_dwordx4 v[224:225], off
	v_lshl_add_u64 v[224:225], s[74:75], 0, v[130:131]
	s_add_i32 m0, s44, 0x2000
	s_nop 0
	global_load_lds_dwordx4 v[224:225], off
	v_lshl_add_u64 v[224:225], s[58:59], 0, v[136:137]
	s_mov_b32 m0, s41
	s_nop 0
	global_load_lds_dwordx4 v[224:225], off
	s_mov_b32 m0, s43
	s_nop 0
	global_load_lds_dwordx4 v[226:227], off
	s_waitcnt vmcnt(8)
	s_waitcnt lgkmcnt(0)
	s_barrier
	s_setprio 1
	s_waitcnt lgkmcnt(0)
	v_mfma_f32_16x16x32_bf16 v[62:65], v[152:155], v[190:193], v[62:65]
	v_mfma_f32_16x16x32_bf16 v[62:65], v[156:159], v[194:197], v[62:65]
	v_mfma_f32_16x16x32_bf16 v[54:57], v[156:159], v[202:205], v[54:57]
	v_mfma_f32_16x16x32_bf16 v[54:57], v[152:155], v[198:201], v[54:57]
	v_mfma_f32_16x16x32_bf16 v[38:41], v[152:155], v[206:209], v[38:41]
	v_mfma_f32_16x16x32_bf16 v[38:41], v[156:159], v[210:213], v[38:41]
	v_mfma_f32_16x16x32_bf16 v[22:25], v[156:159], v[218:221], v[22:25]
	v_mfma_f32_16x16x32_bf16 v[22:25], v[152:155], v[214:217], v[22:25]
	v_mfma_f32_16x16x32_bf16 v[14:17], v[166:169], v[214:217], v[14:17]
	v_mfma_f32_16x16x32_bf16 v[14:17], v[170:173], v[218:221], v[14:17]
	v_mfma_f32_16x16x32_bf16 v[30:33], v[170:173], v[210:213], v[30:33]
	v_mfma_f32_16x16x32_bf16 v[30:33], v[166:169], v[206:209], v[30:33]
	v_mfma_f32_16x16x32_bf16 v[46:49], v[166:169], v[198:201], v[46:49]
	v_mfma_f32_16x16x32_bf16 v[46:49], v[170:173], v[202:205], v[46:49]
	v_mfma_f32_16x16x32_bf16 v[58:61], v[170:173], v[194:197], v[58:61]
	v_mfma_f32_16x16x32_bf16 v[58:61], v[166:169], v[190:193], v[58:61]
	v_mfma_f32_16x16x32_bf16 v[50:53], v[174:177], v[190:193], v[50:53]
	v_mfma_f32_16x16x32_bf16 v[50:53], v[178:181], v[194:197], v[50:53]
	v_mfma_f32_16x16x32_bf16 v[34:37], v[178:181], v[202:205], v[34:37]
	v_mfma_f32_16x16x32_bf16 v[34:37], v[174:177], v[198:201], v[34:37]
	v_mfma_f32_16x16x32_bf16 v[18:21], v[174:177], v[206:209], v[18:21]
	v_mfma_f32_16x16x32_bf16 v[18:21], v[178:181], v[210:213], v[18:21]
	v_mfma_f32_16x16x32_bf16 v[6:9], v[178:181], v[218:221], v[6:9]
	v_mfma_f32_16x16x32_bf16 v[6:9], v[174:177], v[214:217], v[6:9]
	v_mfma_f32_16x16x32_bf16 v[2:5], v[182:185], v[214:217], v[2:5]
	v_mfma_f32_16x16x32_bf16 v[2:5], v[186:189], v[218:221], v[2:5]
	v_mfma_f32_16x16x32_bf16 v[10:13], v[186:189], v[210:213], v[10:13]
	v_mfma_f32_16x16x32_bf16 v[10:13], v[182:185], v[206:209], v[10:13]
	v_mfma_f32_16x16x32_bf16 v[26:29], v[182:185], v[198:201], v[26:29]
	v_mfma_f32_16x16x32_bf16 v[26:29], v[186:189], v[202:205], v[26:29]
	v_mfma_f32_16x16x32_bf16 v[42:45], v[186:189], v[194:197], v[42:45]
	v_mfma_f32_16x16x32_bf16 v[42:45], v[182:185], v[190:193], v[42:45]
	s_setprio 0
	s_barrier
	s_add_i32 s44, 0, 0x18000
	v_add_u32_e32 v151, s44, v146
	s_add_i32 s73, 0, 0x1c000
	ds_read_b128 v[152:155], v151
	ds_read_b128 v[156:159], v151 offset:1024
	ds_read_b128 v[166:169], v151 offset:2048
	ds_read_b128 v[170:173], v151 offset:3072
	v_add_u32_e32 v151, s73, v146
	ds_read_b128 v[174:177], v151
	ds_read_b128 v[178:181], v151 offset:1024
	ds_read_b128 v[182:185], v151 offset:2048
	ds_read_b128 v[186:189], v151 offset:3072
	s_add_u32 s58, s58, 0x100000
	s_addc_u32 s59, s59, 0
	s_mov_b32 m0, s45
	v_lshl_add_u64 v[228:229], s[58:59], 0, v[136:137]
	ds_read_b128 v[190:193], v150 offset:32768
	ds_read_b128 v[194:197], v150 offset:33792
	ds_read_b128 v[198:201], v150 offset:34816
	ds_read_b128 v[202:205], v150 offset:35840
	ds_read_b128 v[206:209], v150 offset:36864
	ds_read_b128 v[210:213], v150 offset:37888
	ds_read_b128 v[214:217], v150 offset:38912
	ds_read_b128 v[218:221], v150 offset:39936
	global_load_lds_dwordx4 v[228:229], off
	v_lshl_add_u64 v[228:229], s[58:59], 0, v[132:133]
	s_mov_b32 m0, s53
	s_nop 0
	global_load_lds_dwordx4 v[228:229], off
	s_waitcnt vmcnt(8)
	s_waitcnt lgkmcnt(0)
	s_barrier
	s_setprio 1
	s_waitcnt lgkmcnt(0)
	v_mfma_f32_16x16x32_bf16 v[126:129], v[152:155], v[190:193], v[126:129]
	v_mfma_f32_16x16x32_bf16 v[126:129], v[156:159], v[194:197], v[126:129]
	v_mfma_f32_16x16x32_bf16 v[118:121], v[156:159], v[202:205], v[118:121]
	v_mfma_f32_16x16x32_bf16 v[118:121], v[152:155], v[198:201], v[118:121]
	v_mfma_f32_16x16x32_bf16 v[102:105], v[152:155], v[206:209], v[102:105]
	v_mfma_f32_16x16x32_bf16 v[102:105], v[156:159], v[210:213], v[102:105]
	v_mfma_f32_16x16x32_bf16 v[86:89], v[156:159], v[218:221], v[86:89]
	v_mfma_f32_16x16x32_bf16 v[86:89], v[152:155], v[214:217], v[86:89]
	v_mfma_f32_16x16x32_bf16 v[78:81], v[166:169], v[214:217], v[78:81]
	v_mfma_f32_16x16x32_bf16 v[78:81], v[170:173], v[218:221], v[78:81]
	v_mfma_f32_16x16x32_bf16 v[94:97], v[170:173], v[210:213], v[94:97]
	v_mfma_f32_16x16x32_bf16 v[94:97], v[166:169], v[206:209], v[94:97]
	v_mfma_f32_16x16x32_bf16 v[110:113], v[166:169], v[198:201], v[110:113]
	v_mfma_f32_16x16x32_bf16 v[110:113], v[170:173], v[202:205], v[110:113]
	v_mfma_f32_16x16x32_bf16 v[122:125], v[170:173], v[194:197], v[122:125]
	v_mfma_f32_16x16x32_bf16 v[122:125], v[166:169], v[190:193], v[122:125]
	v_mfma_f32_16x16x32_bf16 v[114:117], v[174:177], v[190:193], v[114:117]
	v_mfma_f32_16x16x32_bf16 v[114:117], v[178:181], v[194:197], v[114:117]
	v_mfma_f32_16x16x32_bf16 v[98:101], v[178:181], v[202:205], v[98:101]
	v_mfma_f32_16x16x32_bf16 v[98:101], v[174:177], v[198:201], v[98:101]
	v_mfma_f32_16x16x32_bf16 v[82:85], v[174:177], v[206:209], v[82:85]
	v_mfma_f32_16x16x32_bf16 v[82:85], v[178:181], v[210:213], v[82:85]
	v_mfma_f32_16x16x32_bf16 v[70:73], v[178:181], v[218:221], v[70:73]
	v_mfma_f32_16x16x32_bf16 v[70:73], v[174:177], v[214:217], v[70:73]
	v_mfma_f32_16x16x32_bf16 v[66:69], v[182:185], v[214:217], v[66:69]
	v_mfma_f32_16x16x32_bf16 v[66:69], v[186:189], v[218:221], v[66:69]
	v_mfma_f32_16x16x32_bf16 v[74:77], v[186:189], v[210:213], v[74:77]
	v_mfma_f32_16x16x32_bf16 v[74:77], v[182:185], v[206:209], v[74:77]
	v_mfma_f32_16x16x32_bf16 v[90:93], v[182:185], v[198:201], v[90:93]
	v_mfma_f32_16x16x32_bf16 v[90:93], v[186:189], v[202:205], v[90:93]
	v_mfma_f32_16x16x32_bf16 v[106:109], v[186:189], v[194:197], v[106:109]
	v_mfma_f32_16x16x32_bf16 v[106:109], v[182:185], v[190:193], v[106:109]
	s_setprio 0
	s_barrier
	s_add_i32 s44, s44, s27
	v_lshl_add_u64 v[160:161], v[160:161], 0, s[10:11]
	s_mov_b32 m0, s44
	ds_read_b128 v[190:193], v150 offset:49152
	ds_read_b128 v[194:197], v150 offset:50176
	ds_read_b128 v[198:201], v150 offset:51200
	ds_read_b128 v[202:205], v150 offset:52224
	ds_read_b128 v[206:209], v150 offset:53248
	ds_read_b128 v[210:213], v150 offset:54272
	ds_read_b128 v[214:217], v150 offset:55296
	ds_read_b128 v[218:221], v150 offset:56320
	global_load_lds_dwordx4 v[160:161], off
	s_add_i32 m0, s44, 0x2000
	s_add_u32 s56, s56, 0x100080
	v_lshl_add_u64 v[160:161], v[222:223], 0, s[10:11]
	s_addc_u32 s57, s57, 0
	s_add_i32 s44, s73, s27
	global_load_lds_dwordx4 v[160:161], off
	v_lshl_add_u64 v[160:161], s[56:57], 0, v[134:135]
	s_mov_b32 m0, s44
	s_nop 0
	global_load_lds_dwordx4 v[160:161], off
	v_lshl_add_u64 v[160:161], s[56:57], 0, v[130:131]
	s_add_i32 m0, s44, 0x2000
	s_nop 0
	global_load_lds_dwordx4 v[160:161], off
	v_lshl_add_u64 v[160:161], v[224:225], 0, s[10:11]
	s_mov_b32 m0, s61
	s_nop 0
	global_load_lds_dwordx4 v[160:161], off
	v_lshl_add_u64 v[160:161], v[226:227], 0, s[10:11]
	s_mov_b32 m0, s62
	s_nop 0
	global_load_lds_dwordx4 v[160:161], off
	s_waitcnt vmcnt(8)
	s_waitcnt lgkmcnt(0)
	s_barrier
	s_setprio 1
	s_waitcnt lgkmcnt(0)
	v_mfma_f32_16x16x32_bf16 v[62:65], v[152:155], v[190:193], v[62:65]
	v_mfma_f32_16x16x32_bf16 v[62:65], v[156:159], v[194:197], v[62:65]
	v_mfma_f32_16x16x32_bf16 v[54:57], v[156:159], v[202:205], v[54:57]
	v_mfma_f32_16x16x32_bf16 v[54:57], v[152:155], v[198:201], v[54:57]
	v_mfma_f32_16x16x32_bf16 v[38:41], v[152:155], v[206:209], v[38:41]
	v_mfma_f32_16x16x32_bf16 v[38:41], v[156:159], v[210:213], v[38:41]
	v_mfma_f32_16x16x32_bf16 v[22:25], v[156:159], v[218:221], v[22:25]
	v_mfma_f32_16x16x32_bf16 v[22:25], v[152:155], v[214:217], v[22:25]
	v_mfma_f32_16x16x32_bf16 v[14:17], v[166:169], v[214:217], v[14:17]
	v_mfma_f32_16x16x32_bf16 v[14:17], v[170:173], v[218:221], v[14:17]
	v_mfma_f32_16x16x32_bf16 v[30:33], v[170:173], v[210:213], v[30:33]
	v_mfma_f32_16x16x32_bf16 v[30:33], v[166:169], v[206:209], v[30:33]
	v_mfma_f32_16x16x32_bf16 v[46:49], v[166:169], v[198:201], v[46:49]
	v_mfma_f32_16x16x32_bf16 v[46:49], v[170:173], v[202:205], v[46:49]
	v_mfma_f32_16x16x32_bf16 v[58:61], v[170:173], v[194:197], v[58:61]
	v_mfma_f32_16x16x32_bf16 v[58:61], v[166:169], v[190:193], v[58:61]
	v_mfma_f32_16x16x32_bf16 v[50:53], v[174:177], v[190:193], v[50:53]
	v_mfma_f32_16x16x32_bf16 v[50:53], v[178:181], v[194:197], v[50:53]
	v_mfma_f32_16x16x32_bf16 v[34:37], v[178:181], v[202:205], v[34:37]
	v_mfma_f32_16x16x32_bf16 v[34:37], v[174:177], v[198:201], v[34:37]
	v_mfma_f32_16x16x32_bf16 v[18:21], v[174:177], v[206:209], v[18:21]
	v_mfma_f32_16x16x32_bf16 v[18:21], v[178:181], v[210:213], v[18:21]
	v_mfma_f32_16x16x32_bf16 v[6:9], v[178:181], v[218:221], v[6:9]
	v_mfma_f32_16x16x32_bf16 v[6:9], v[174:177], v[214:217], v[6:9]
	v_mfma_f32_16x16x32_bf16 v[2:5], v[182:185], v[214:217], v[2:5]
	v_mfma_f32_16x16x32_bf16 v[2:5], v[186:189], v[218:221], v[2:5]
	v_mfma_f32_16x16x32_bf16 v[10:13], v[186:189], v[210:213], v[10:13]
	v_mfma_f32_16x16x32_bf16 v[10:13], v[182:185], v[206:209], v[10:13]
	v_mfma_f32_16x16x32_bf16 v[26:29], v[182:185], v[198:201], v[26:29]
	v_mfma_f32_16x16x32_bf16 v[26:29], v[186:189], v[202:205], v[26:29]
	v_mfma_f32_16x16x32_bf16 v[42:45], v[186:189], v[194:197], v[42:45]
	v_mfma_f32_16x16x32_bf16 v[42:45], v[182:185], v[190:193], v[42:45]
	s_setprio 0
	s_barrier
	s_add_i32 s72, s72, 2
	s_add_u32 s54, s54, 0x100
	s_addc_u32 s55, s55, 0
	s_add_u32 s70, s70, 0x100
	s_addc_u32 s71, s71, 0
	s_cmp_gt_u32 s72, 61
	s_cbranch_scc0 .LBB0_472
	s_and_b64 vcc, exec, s[12:13]
	s_cbranch_vccz .LBB0_475
	s_barrier

.LBB0_706:
	s_add_u32 s72, s60, s44
	s_addc_u32 s73, s61, 0
	s_add_u32 s68, s72, 0x100
	s_addc_u32 s69, s73, 0
	s_and_b64 s[66:67], s[64:65], exec
	s_cselect_b32 s69, s17, s69
	s_cselect_b32 s68, s86, s68
	s_add_u32 s44, s56, s44
	s_addc_u32 s66, s57, 0
	s_add_u32 s44, s44, 0x100
	s_addc_u32 s66, s66, 0
	s_and_b64 s[64:65], s[64:65], exec
	s_cselect_b32 s71, s15, s66
	s_cselect_b32 s70, s87, s44
	s_add_u32 s74, s72, 0x10080
	s_addc_u32 s75, s73, 0
	s_add_i32 vcc_hi, s82, s27
	ds_read_b128 v[150:153], v147
	ds_read_b128 v[154:157], v147 offset:1024
	ds_read_b128 v[158:161], v147 offset:2048
	ds_read_b128 v[166:169], v147 offset:3072
	ds_read_b128 v[170:173], v148
	ds_read_b128 v[174:177], v148 offset:1024
	ds_read_b128 v[178:181], v148 offset:2048
	ds_read_b128 v[182:185], v148 offset:3072
	s_add_i32 m0, s36, 0xc000
	s_add_i32 s45, s36, 0xe000
	s_add_i32 s96, vcc_hi, 0x2000
	s_add_u32 s72, s70, 0x10000
	s_addc_u32 s73, s71, 0
	s_add_i32 vcc_lo, s83, s27
	s_add_i32 s97, vcc_lo, 0x2000
	s_add_i32 s95, 0, 0x18000
	s_add_i32 s94, 0, 0x1c000
	s_add_u32 s66, s68, 0x10000
	s_addc_u32 s67, s69, 0
	s_add_i32 s93, s95, s27
	s_add_i32 s89, s93, 0x2000
	s_add_u32 s64, s70, 0x10080
	s_addc_u32 s65, s71, 0
	s_add_i32 s92, s94, s27
	s_add_i32 s44, s92, 0x2000
	v_lshl_add_u64 v[198:199], s[74:75], 0, v[130:131]
	ds_read_b128 v[186:189], v149
	ds_read_b128 v[190:193], v149 offset:1024
	ds_read_b128 v[194:197], v149 offset:2048
	ds_read_b128 v[202:205], v149 offset:3072
	ds_read_b128 v[206:209], v149 offset:4096
	ds_read_b128 v[210:213], v149 offset:5120
	ds_read_b128 v[214:217], v149 offset:6144
	ds_read_b128 v[218:221], v149 offset:7168
	global_load_lds_dwordx4 v[198:199], off
	v_lshl_add_u64 v[198:199], s[74:75], 0, v[134:135]
	s_mov_b32 m0, s45
	s_nop 0
	global_load_lds_dwordx4 v[198:199], off
	s_waitcnt vmcnt(8)
	s_waitcnt lgkmcnt(0)
	s_barrier
	s_setprio 1
	s_waitcnt lgkmcnt(0)
	v_mfma_f32_16x16x32_bf16 v[126:129], v[150:153], v[186:189], v[126:129]
	v_mfma_f32_16x16x32_bf16 v[126:129], v[154:157], v[190:193], v[126:129]
	v_mfma_f32_16x16x32_bf16 v[118:121], v[154:157], v[202:205], v[118:121]
	v_mfma_f32_16x16x32_bf16 v[118:121], v[150:153], v[194:197], v[118:121]
	v_mfma_f32_16x16x32_bf16 v[102:105], v[150:153], v[206:209], v[102:105]
	v_mfma_f32_16x16x32_bf16 v[102:105], v[154:157], v[210:213], v[102:105]
	v_mfma_f32_16x16x32_bf16 v[86:89], v[154:157], v[218:221], v[86:89]
	v_mfma_f32_16x16x32_bf16 v[86:89], v[150:153], v[214:217], v[86:89]
	v_mfma_f32_16x16x32_bf16 v[78:81], v[158:161], v[214:217], v[78:81]
	v_mfma_f32_16x16x32_bf16 v[78:81], v[166:169], v[218:221], v[78:81]
	v_mfma_f32_16x16x32_bf16 v[94:97], v[166:169], v[210:213], v[94:97]
	v_mfma_f32_16x16x32_bf16 v[94:97], v[158:161], v[206:209], v[94:97]
	v_mfma_f32_16x16x32_bf16 v[110:113], v[158:161], v[194:197], v[110:113]
	v_mfma_f32_16x16x32_bf16 v[110:113], v[166:169], v[202:205], v[110:113]
	v_mfma_f32_16x16x32_bf16 v[122:125], v[166:169], v[190:193], v[122:125]
	v_mfma_f32_16x16x32_bf16 v[122:125], v[158:161], v[186:189], v[122:125]
	v_mfma_f32_16x16x32_bf16 v[114:117], v[170:173], v[186:189], v[114:117]
	v_mfma_f32_16x16x32_bf16 v[114:117], v[174:177], v[190:193], v[114:117]
	v_mfma_f32_16x16x32_bf16 v[98:101], v[174:177], v[202:205], v[98:101]
	v_mfma_f32_16x16x32_bf16 v[98:101], v[170:173], v[194:197], v[98:101]
	v_mfma_f32_16x16x32_bf16 v[82:85], v[170:173], v[206:209], v[82:85]
	v_mfma_f32_16x16x32_bf16 v[82:85], v[174:177], v[210:213], v[82:85]
	v_mfma_f32_16x16x32_bf16 v[70:73], v[174:177], v[218:221], v[70:73]
	v_mfma_f32_16x16x32_bf16 v[70:73], v[170:173], v[214:217], v[70:73]
	v_mfma_f32_16x16x32_bf16 v[66:69], v[178:181], v[214:217], v[66:69]
	v_mfma_f32_16x16x32_bf16 v[66:69], v[182:185], v[218:221], v[66:69]
	v_mfma_f32_16x16x32_bf16 v[74:77], v[182:185], v[210:213], v[74:77]
	v_mfma_f32_16x16x32_bf16 v[74:77], v[178:181], v[206:209], v[74:77]
	v_mfma_f32_16x16x32_bf16 v[90:93], v[178:181], v[194:197], v[90:93]
	v_mfma_f32_16x16x32_bf16 v[90:93], v[182:185], v[202:205], v[90:93]
	v_mfma_f32_16x16x32_bf16 v[106:109], v[182:185], v[190:193], v[106:109]
	v_mfma_f32_16x16x32_bf16 v[106:109], v[178:181], v[186:189], v[106:109]
	s_setprio 0
	s_barrier
	s_mov_b32 m0, vcc_hi
	v_lshl_add_u64 v[198:199], s[70:71], 0, v[132:133]
	ds_read_b128 v[186:189], v149 offset:16384
	ds_read_b128 v[190:193], v149 offset:17408
	ds_read_b128 v[194:197], v149 offset:18432
	ds_read_b128 v[202:205], v149 offset:19456
	ds_read_b128 v[206:209], v149 offset:20480
	ds_read_b128 v[210:213], v149 offset:21504
	ds_read_b128 v[214:217], v149 offset:22528
	ds_read_b128 v[218:221], v149 offset:23552
	global_load_lds_dwordx4 v[198:199], off
	v_lshl_add_u64 v[222:223], s[70:71], 0, v[136:137]
	s_mov_b32 m0, s96
	v_lshl_add_u64 v[224:225], s[72:73], 0, v[132:133]
	global_load_lds_dwordx4 v[222:223], off
	s_mov_b32 m0, vcc_lo
	v_lshl_add_u64 v[226:227], s[68:69], 0, v[134:135]
	global_load_lds_dwordx4 v[224:225], off
	v_lshl_add_u64 v[224:225], s[72:73], 0, v[136:137]
	s_mov_b32 m0, s97
	s_nop 0
	global_load_lds_dwordx4 v[224:225], off
	v_lshl_add_u64 v[224:225], s[68:69], 0, v[130:131]
	s_mov_b32 m0, s36
	s_nop 0
	global_load_lds_dwordx4 v[224:225], off
	s_mov_b32 m0, s55
	s_nop 0
	global_load_lds_dwordx4 v[226:227], off
	s_waitcnt vmcnt(8)
	s_waitcnt lgkmcnt(0)
	s_barrier
	s_setprio 1
	s_waitcnt lgkmcnt(0)
	v_mfma_f32_16x16x32_bf16 v[62:65], v[150:153], v[186:189], v[62:65]
	v_mfma_f32_16x16x32_bf16 v[62:65], v[154:157], v[190:193], v[62:65]
	v_mfma_f32_16x16x32_bf16 v[54:57], v[154:157], v[202:205], v[54:57]
	v_mfma_f32_16x16x32_bf16 v[54:57], v[150:153], v[194:197], v[54:57]
	v_mfma_f32_16x16x32_bf16 v[38:41], v[150:153], v[206:209], v[38:41]
	v_mfma_f32_16x16x32_bf16 v[38:41], v[154:157], v[210:213], v[38:41]
	v_mfma_f32_16x16x32_bf16 v[22:25], v[154:157], v[218:221], v[22:25]
	v_mfma_f32_16x16x32_bf16 v[22:25], v[150:153], v[214:217], v[22:25]
	v_mfma_f32_16x16x32_bf16 v[14:17], v[158:161], v[214:217], v[14:17]
	v_mfma_f32_16x16x32_bf16 v[14:17], v[166:169], v[218:221], v[14:17]
	v_mfma_f32_16x16x32_bf16 v[30:33], v[166:169], v[210:213], v[30:33]
	v_mfma_f32_16x16x32_bf16 v[30:33], v[158:161], v[206:209], v[30:33]
	v_mfma_f32_16x16x32_bf16 v[46:49], v[158:161], v[194:197], v[46:49]
	v_mfma_f32_16x16x32_bf16 v[46:49], v[166:169], v[202:205], v[46:49]
	v_mfma_f32_16x16x32_bf16 v[58:61], v[166:169], v[190:193], v[58:61]
	v_mfma_f32_16x16x32_bf16 v[58:61], v[158:161], v[186:189], v[58:61]
	v_mfma_f32_16x16x32_bf16 v[50:53], v[170:173], v[186:189], v[50:53]
	v_mfma_f32_16x16x32_bf16 v[50:53], v[174:177], v[190:193], v[50:53]
	v_mfma_f32_16x16x32_bf16 v[34:37], v[174:177], v[202:205], v[34:37]
	v_mfma_f32_16x16x32_bf16 v[34:37], v[170:173], v[194:197], v[34:37]
	v_mfma_f32_16x16x32_bf16 v[18:21], v[170:173], v[206:209], v[18:21]
	v_mfma_f32_16x16x32_bf16 v[18:21], v[174:177], v[210:213], v[18:21]
	v_mfma_f32_16x16x32_bf16 v[6:9], v[174:177], v[218:221], v[6:9]
	v_mfma_f32_16x16x32_bf16 v[6:9], v[170:173], v[214:217], v[6:9]
	v_mfma_f32_16x16x32_bf16 v[2:5], v[178:181], v[214:217], v[2:5]
	v_mfma_f32_16x16x32_bf16 v[2:5], v[182:185], v[218:221], v[2:5]
	v_mfma_f32_16x16x32_bf16 v[10:13], v[182:185], v[210:213], v[10:13]
	v_mfma_f32_16x16x32_bf16 v[10:13], v[178:181], v[206:209], v[10:13]
	v_mfma_f32_16x16x32_bf16 v[26:29], v[178:181], v[194:197], v[26:29]
	v_mfma_f32_16x16x32_bf16 v[26:29], v[182:185], v[202:205], v[26:29]
	v_mfma_f32_16x16x32_bf16 v[42:45], v[182:185], v[190:193], v[42:45]
	v_mfma_f32_16x16x32_bf16 v[42:45], v[178:181], v[186:189], v[42:45]
	s_setprio 0
	s_barrier
	v_add_u32_e32 v166, s95, v145
	v_add_u32_e32 v182, s94, v145
	ds_read_b128 v[150:153], v166
	ds_read_b128 v[154:157], v166 offset:1024
	ds_read_b128 v[158:161], v166 offset:2048
	ds_read_b128 v[166:169], v166 offset:3072
	ds_read_b128 v[170:173], v182
	ds_read_b128 v[174:177], v182 offset:1024
	ds_read_b128 v[178:181], v182 offset:2048
	ds_read_b128 v[182:185], v182 offset:3072
	s_mov_b32 m0, s76
	v_lshl_add_u64 v[228:229], s[66:67], 0, v[130:131]
	ds_read_b128 v[186:189], v149 offset:32768
	ds_read_b128 v[190:193], v149 offset:33792
	ds_read_b128 v[194:197], v149 offset:34816
	ds_read_b128 v[202:205], v149 offset:35840
	ds_read_b128 v[206:209], v149 offset:36864
	ds_read_b128 v[210:213], v149 offset:37888
	ds_read_b128 v[214:217], v149 offset:38912
	ds_read_b128 v[218:221], v149 offset:39936
	global_load_lds_dwordx4 v[228:229], off
	v_lshl_add_u64 v[228:229], s[66:67], 0, v[134:135]
	s_mov_b32 m0, s77
	s_nop 0
	global_load_lds_dwordx4 v[228:229], off
	s_waitcnt vmcnt(8)
	s_waitcnt lgkmcnt(0)
	s_barrier
	s_setprio 1
	s_waitcnt lgkmcnt(0)
	v_mfma_f32_16x16x32_bf16 v[126:129], v[150:153], v[186:189], v[126:129]
	v_mfma_f32_16x16x32_bf16 v[126:129], v[154:157], v[190:193], v[126:129]
	v_mfma_f32_16x16x32_bf16 v[118:121], v[154:157], v[202:205], v[118:121]
	v_mfma_f32_16x16x32_bf16 v[118:121], v[150:153], v[194:197], v[118:121]
	v_mfma_f32_16x16x32_bf16 v[102:105], v[150:153], v[206:209], v[102:105]
	v_mfma_f32_16x16x32_bf16 v[102:105], v[154:157], v[210:213], v[102:105]
	v_mfma_f32_16x16x32_bf16 v[86:89], v[154:157], v[218:221], v[86:89]
	v_mfma_f32_16x16x32_bf16 v[86:89], v[150:153], v[214:217], v[86:89]
	v_mfma_f32_16x16x32_bf16 v[78:81], v[158:161], v[214:217], v[78:81]
	v_mfma_f32_16x16x32_bf16 v[78:81], v[166:169], v[218:221], v[78:81]
	v_mfma_f32_16x16x32_bf16 v[94:97], v[166:169], v[210:213], v[94:97]
	v_mfma_f32_16x16x32_bf16 v[94:97], v[158:161], v[206:209], v[94:97]
	v_mfma_f32_16x16x32_bf16 v[110:113], v[158:161], v[194:197], v[110:113]
	v_mfma_f32_16x16x32_bf16 v[110:113], v[166:169], v[202:205], v[110:113]
	v_mfma_f32_16x16x32_bf16 v[122:125], v[166:169], v[190:193], v[122:125]
	v_mfma_f32_16x16x32_bf16 v[122:125], v[158:161], v[186:189], v[122:125]
	v_mfma_f32_16x16x32_bf16 v[114:117], v[170:173], v[186:189], v[114:117]
	v_mfma_f32_16x16x32_bf16 v[114:117], v[174:177], v[190:193], v[114:117]
	v_mfma_f32_16x16x32_bf16 v[98:101], v[174:177], v[202:205], v[98:101]
	v_mfma_f32_16x16x32_bf16 v[98:101], v[170:173], v[194:197], v[98:101]
	v_mfma_f32_16x16x32_bf16 v[82:85], v[170:173], v[206:209], v[82:85]
	v_mfma_f32_16x16x32_bf16 v[82:85], v[174:177], v[210:213], v[82:85]
	v_mfma_f32_16x16x32_bf16 v[70:73], v[174:177], v[218:221], v[70:73]
	v_mfma_f32_16x16x32_bf16 v[70:73], v[170:173], v[214:217], v[70:73]
	v_mfma_f32_16x16x32_bf16 v[66:69], v[178:181], v[214:217], v[66:69]
	v_mfma_f32_16x16x32_bf16 v[66:69], v[182:185], v[218:221], v[66:69]
	v_mfma_f32_16x16x32_bf16 v[74:77], v[182:185], v[210:213], v[74:77]
	v_mfma_f32_16x16x32_bf16 v[74:77], v[178:181], v[206:209], v[74:77]
	v_mfma_f32_16x16x32_bf16 v[90:93], v[178:181], v[194:197], v[90:93]
	v_mfma_f32_16x16x32_bf16 v[90:93], v[182:185], v[202:205], v[90:93]
	v_mfma_f32_16x16x32_bf16 v[106:109], v[182:185], v[190:193], v[106:109]
	v_mfma_f32_16x16x32_bf16 v[106:109], v[178:181], v[186:189], v[106:109]
	s_setprio 0
	s_barrier
	s_mov_b32 m0, s93
	v_lshl_add_u64 v[198:199], v[198:199], 0, s[10:11]
	ds_read_b128 v[186:189], v149 offset:49152
	ds_read_b128 v[190:193], v149 offset:50176
	ds_read_b128 v[194:197], v149 offset:51200
	ds_read_b128 v[202:205], v149 offset:52224
	ds_read_b128 v[206:209], v149 offset:53248
	ds_read_b128 v[210:213], v149 offset:54272
	ds_read_b128 v[214:217], v149 offset:55296
	ds_read_b128 v[218:221], v149 offset:56320
	global_load_lds_dwordx4 v[198:199], off
	v_lshl_add_u64 v[198:199], v[222:223], 0, s[10:11]
	s_mov_b32 m0, s89
	s_nop 0
	global_load_lds_dwordx4 v[198:199], off
	v_lshl_add_u64 v[198:199], s[64:65], 0, v[132:133]
	s_mov_b32 m0, s92
	s_nop 0
	global_load_lds_dwordx4 v[198:199], off
	v_lshl_add_u64 v[198:199], s[64:65], 0, v[136:137]
	s_mov_b32 m0, s44
	s_nop 0
	global_load_lds_dwordx4 v[198:199], off
	v_lshl_add_u64 v[198:199], v[224:225], 0, s[10:11]
	s_mov_b32 m0, s79
	s_nop 0
	global_load_lds_dwordx4 v[198:199], off
	v_lshl_add_u64 v[198:199], v[226:227], 0, s[10:11]
	s_mov_b32 m0, s80
	s_nop 0
	global_load_lds_dwordx4 v[198:199], off
	s_waitcnt vmcnt(8)
	s_waitcnt lgkmcnt(0)
	s_barrier
	s_setprio 1
	s_waitcnt lgkmcnt(0)
	v_mfma_f32_16x16x32_bf16 v[62:65], v[150:153], v[186:189], v[62:65]
	v_mfma_f32_16x16x32_bf16 v[62:65], v[154:157], v[190:193], v[62:65]
	v_mfma_f32_16x16x32_bf16 v[54:57], v[154:157], v[202:205], v[54:57]
	v_mfma_f32_16x16x32_bf16 v[54:57], v[150:153], v[194:197], v[54:57]
	v_mfma_f32_16x16x32_bf16 v[38:41], v[150:153], v[206:209], v[38:41]
	v_mfma_f32_16x16x32_bf16 v[38:41], v[154:157], v[210:213], v[38:41]
	v_mfma_f32_16x16x32_bf16 v[22:25], v[154:157], v[218:221], v[22:25]
	v_mfma_f32_16x16x32_bf16 v[22:25], v[150:153], v[214:217], v[22:25]
	v_mfma_f32_16x16x32_bf16 v[14:17], v[158:161], v[214:217], v[14:17]
	v_mfma_f32_16x16x32_bf16 v[14:17], v[166:169], v[218:221], v[14:17]
	v_mfma_f32_16x16x32_bf16 v[30:33], v[166:169], v[210:213], v[30:33]
	v_mfma_f32_16x16x32_bf16 v[30:33], v[158:161], v[206:209], v[30:33]
	v_mfma_f32_16x16x32_bf16 v[46:49], v[158:161], v[194:197], v[46:49]
	v_mfma_f32_16x16x32_bf16 v[46:49], v[166:169], v[202:205], v[46:49]
	v_mfma_f32_16x16x32_bf16 v[58:61], v[166:169], v[190:193], v[58:61]
	v_mfma_f32_16x16x32_bf16 v[58:61], v[158:161], v[186:189], v[58:61]
	v_mfma_f32_16x16x32_bf16 v[50:53], v[170:173], v[186:189], v[50:53]
	v_mfma_f32_16x16x32_bf16 v[50:53], v[174:177], v[190:193], v[50:53]
	v_mfma_f32_16x16x32_bf16 v[34:37], v[174:177], v[202:205], v[34:37]
	v_mfma_f32_16x16x32_bf16 v[34:37], v[170:173], v[194:197], v[34:37]
	v_mfma_f32_16x16x32_bf16 v[18:21], v[170:173], v[206:209], v[18:21]
	v_mfma_f32_16x16x32_bf16 v[18:21], v[174:177], v[210:213], v[18:21]
	v_mfma_f32_16x16x32_bf16 v[6:9], v[174:177], v[218:221], v[6:9]
	v_mfma_f32_16x16x32_bf16 v[6:9], v[170:173], v[214:217], v[6:9]
	v_mfma_f32_16x16x32_bf16 v[2:5], v[178:181], v[214:217], v[2:5]
	v_mfma_f32_16x16x32_bf16 v[2:5], v[182:185], v[218:221], v[2:5]
	v_mfma_f32_16x16x32_bf16 v[10:13], v[182:185], v[210:213], v[10:13]
	v_mfma_f32_16x16x32_bf16 v[10:13], v[178:181], v[206:209], v[10:13]
	v_mfma_f32_16x16x32_bf16 v[26:29], v[178:181], v[194:197], v[26:29]
	v_mfma_f32_16x16x32_bf16 v[26:29], v[182:185], v[202:205], v[26:29]
	v_mfma_f32_16x16x32_bf16 v[42:45], v[182:185], v[190:193], v[42:45]
	v_mfma_f32_16x16x32_bf16 v[42:45], v[178:181], v[186:189], v[42:45]
	s_setprio 0
	s_barrier
	s_movk_i32 s44, 0x100
	s_andn2_b64 vcc, exec, s[62:63]
	s_mov_b64 s[64:65], -1
	s_mov_b64 s[62:63], 0
	s_cbranch_vccz .LBB0_706
	s_and_b64 vcc, exec, s[12:13]
	s_cbranch_vccz .LBB0_709
	s_barrier

.LBB0_722:
	s_add_u32 s36, s56, s44
	s_addc_u32 s37, s57, 0
	s_add_u32 s66, s36, 0x100
	s_addc_u32 s67, s37, 0
	s_and_b64 s[64:65], s[62:63], exec
	s_cselect_b32 s67, s17, s67
	s_cselect_b32 s66, s83, s66
	s_add_u32 s44, s54, s44
	s_addc_u32 s64, s55, 0
	s_add_u32 s44, s44, 0x100
	s_addc_u32 s64, s64, 0
	s_and_b64 s[62:63], s[62:63], exec
	s_cselect_b32 s69, s15, s64
	s_cselect_b32 s68, s84, s44
	s_add_u32 s72, s36, 0x10080
	s_addc_u32 s73, s37, 0
	s_add_i32 s96, s79, s27
	ds_read_b128 v[148:151], v143
	ds_read_b128 v[152:155], v143 offset:1024
	ds_read_b128 v[156:159], v143 offset:2048
	ds_read_b128 v[166:169], v143 offset:3072
	ds_read_b128 v[170:173], v145
	ds_read_b128 v[174:177], v145 offset:1024
	ds_read_b128 v[178:181], v145 offset:2048
	ds_read_b128 v[182:185], v145 offset:3072
	s_add_i32 m0, s43, 0xc000
	s_add_i32 s97, s43, 0xe000
	s_add_i32 s93, s96, 0x2000
	s_add_u32 s70, s68, 0x10000
	s_addc_u32 s71, s69, 0
	s_add_i32 s95, s80, s27
	s_add_i32 s94, s95, 0x2000
	s_add_i32 s92, 0, 0x18000
	s_add_i32 s89, 0, 0x1c000
	s_add_u32 s64, s66, 0x10000
	s_addc_u32 s65, s67, 0
	s_add_i32 s87, s92, s27
	s_add_i32 s85, s87, 0x2000
	s_add_u32 s62, s68, 0x10080
	s_addc_u32 s63, s69, 0
	s_add_i32 s86, s89, s27
	s_add_i32 s44, s86, 0x2000
	v_lshl_add_u64 v[160:161], s[72:73], 0, v[130:131]
	ds_read_b128 v[186:189], v146
	ds_read_b128 v[190:193], v146 offset:1024
	ds_read_b128 v[194:197], v146 offset:2048
	ds_read_b128 v[202:205], v146 offset:3072
	ds_read_b128 v[206:209], v146 offset:4096
	ds_read_b128 v[210:213], v146 offset:5120
	ds_read_b128 v[214:217], v146 offset:6144
	ds_read_b128 v[218:221], v146 offset:7168
	global_load_lds_dwordx4 v[160:161], off
	v_lshl_add_u64 v[160:161], s[72:73], 0, v[134:135]
	s_mov_b32 m0, s97
	s_nop 0
	global_load_lds_dwordx4 v[160:161], off
	s_waitcnt vmcnt(8)
	s_waitcnt lgkmcnt(0)
	s_barrier
	s_setprio 1
	s_waitcnt lgkmcnt(0)
	v_mfma_f32_16x16x32_bf16 v[126:129], v[148:151], v[186:189], v[126:129]
	v_mfma_f32_16x16x32_bf16 v[126:129], v[152:155], v[190:193], v[126:129]
	v_mfma_f32_16x16x32_bf16 v[118:121], v[152:155], v[202:205], v[118:121]
	v_mfma_f32_16x16x32_bf16 v[118:121], v[148:151], v[194:197], v[118:121]
	v_mfma_f32_16x16x32_bf16 v[102:105], v[148:151], v[206:209], v[102:105]
	v_mfma_f32_16x16x32_bf16 v[102:105], v[152:155], v[210:213], v[102:105]
	v_mfma_f32_16x16x32_bf16 v[86:89], v[152:155], v[218:221], v[86:89]
	v_mfma_f32_16x16x32_bf16 v[86:89], v[148:151], v[214:217], v[86:89]
	v_mfma_f32_16x16x32_bf16 v[78:81], v[156:159], v[214:217], v[78:81]
	v_mfma_f32_16x16x32_bf16 v[78:81], v[166:169], v[218:221], v[78:81]
	v_mfma_f32_16x16x32_bf16 v[94:97], v[166:169], v[210:213], v[94:97]
	v_mfma_f32_16x16x32_bf16 v[94:97], v[156:159], v[206:209], v[94:97]
	v_mfma_f32_16x16x32_bf16 v[110:113], v[156:159], v[194:197], v[110:113]
	v_mfma_f32_16x16x32_bf16 v[110:113], v[166:169], v[202:205], v[110:113]
	v_mfma_f32_16x16x32_bf16 v[122:125], v[166:169], v[190:193], v[122:125]
	v_mfma_f32_16x16x32_bf16 v[122:125], v[156:159], v[186:189], v[122:125]
	v_mfma_f32_16x16x32_bf16 v[114:117], v[170:173], v[186:189], v[114:117]
	v_mfma_f32_16x16x32_bf16 v[114:117], v[174:177], v[190:193], v[114:117]
	v_mfma_f32_16x16x32_bf16 v[98:101], v[174:177], v[202:205], v[98:101]
	v_mfma_f32_16x16x32_bf16 v[98:101], v[170:173], v[194:197], v[98:101]
	v_mfma_f32_16x16x32_bf16 v[82:85], v[170:173], v[206:209], v[82:85]
	v_mfma_f32_16x16x32_bf16 v[82:85], v[174:177], v[210:213], v[82:85]
	v_mfma_f32_16x16x32_bf16 v[70:73], v[174:177], v[218:221], v[70:73]
	v_mfma_f32_16x16x32_bf16 v[70:73], v[170:173], v[214:217], v[70:73]
	v_mfma_f32_16x16x32_bf16 v[66:69], v[178:181], v[214:217], v[66:69]
	v_mfma_f32_16x16x32_bf16 v[66:69], v[182:185], v[218:221], v[66:69]
	v_mfma_f32_16x16x32_bf16 v[74:77], v[182:185], v[210:213], v[74:77]
	v_mfma_f32_16x16x32_bf16 v[74:77], v[178:181], v[206:209], v[74:77]
	v_mfma_f32_16x16x32_bf16 v[90:93], v[178:181], v[194:197], v[90:93]
	v_mfma_f32_16x16x32_bf16 v[90:93], v[182:185], v[202:205], v[90:93]
	v_mfma_f32_16x16x32_bf16 v[106:109], v[182:185], v[190:193], v[106:109]
	v_mfma_f32_16x16x32_bf16 v[106:109], v[178:181], v[186:189], v[106:109]
	s_setprio 0
	s_barrier
	s_mov_b32 m0, s96
	v_lshl_add_u64 v[160:161], s[68:69], 0, v[132:133]
	ds_read_b128 v[186:189], v146 offset:16384
	ds_read_b128 v[190:193], v146 offset:17408
	ds_read_b128 v[194:197], v146 offset:18432
	ds_read_b128 v[202:205], v146 offset:19456
	ds_read_b128 v[206:209], v146 offset:20480
	ds_read_b128 v[210:213], v146 offset:21504
	ds_read_b128 v[214:217], v146 offset:22528
	ds_read_b128 v[218:221], v146 offset:23552
	global_load_lds_dwordx4 v[160:161], off
	v_lshl_add_u64 v[198:199], s[68:69], 0, v[136:137]
	s_mov_b32 m0, s93
	v_lshl_add_u64 v[222:223], s[70:71], 0, v[132:133]
	global_load_lds_dwordx4 v[198:199], off
	s_mov_b32 m0, s95
	v_lshl_add_u64 v[224:225], s[66:67], 0, v[134:135]
	global_load_lds_dwordx4 v[222:223], off
	v_lshl_add_u64 v[222:223], s[70:71], 0, v[136:137]
	s_mov_b32 m0, s94
	s_nop 0
	global_load_lds_dwordx4 v[222:223], off
	v_lshl_add_u64 v[222:223], s[66:67], 0, v[130:131]
	s_mov_b32 m0, s43
	s_nop 0
	global_load_lds_dwordx4 v[222:223], off
	s_mov_b32 m0, s45
	s_nop 0
	global_load_lds_dwordx4 v[224:225], off
	s_waitcnt vmcnt(8)
	s_waitcnt lgkmcnt(0)
	s_barrier
	s_setprio 1
	s_waitcnt lgkmcnt(0)
	v_mfma_f32_16x16x32_bf16 v[62:65], v[148:151], v[186:189], v[62:65]
	v_mfma_f32_16x16x32_bf16 v[62:65], v[152:155], v[190:193], v[62:65]
	v_mfma_f32_16x16x32_bf16 v[54:57], v[152:155], v[202:205], v[54:57]
	v_mfma_f32_16x16x32_bf16 v[54:57], v[148:151], v[194:197], v[54:57]
	v_mfma_f32_16x16x32_bf16 v[38:41], v[148:151], v[206:209], v[38:41]
	v_mfma_f32_16x16x32_bf16 v[38:41], v[152:155], v[210:213], v[38:41]
	v_mfma_f32_16x16x32_bf16 v[22:25], v[152:155], v[218:221], v[22:25]
	v_mfma_f32_16x16x32_bf16 v[22:25], v[148:151], v[214:217], v[22:25]
	v_mfma_f32_16x16x32_bf16 v[14:17], v[156:159], v[214:217], v[14:17]
	v_mfma_f32_16x16x32_bf16 v[14:17], v[166:169], v[218:221], v[14:17]
	v_mfma_f32_16x16x32_bf16 v[30:33], v[166:169], v[210:213], v[30:33]
	v_mfma_f32_16x16x32_bf16 v[30:33], v[156:159], v[206:209], v[30:33]
	v_mfma_f32_16x16x32_bf16 v[46:49], v[156:159], v[194:197], v[46:49]
	v_mfma_f32_16x16x32_bf16 v[46:49], v[166:169], v[202:205], v[46:49]
	v_mfma_f32_16x16x32_bf16 v[58:61], v[166:169], v[190:193], v[58:61]
	v_mfma_f32_16x16x32_bf16 v[58:61], v[156:159], v[186:189], v[58:61]
	v_mfma_f32_16x16x32_bf16 v[50:53], v[170:173], v[186:189], v[50:53]
	v_mfma_f32_16x16x32_bf16 v[50:53], v[174:177], v[190:193], v[50:53]
	v_mfma_f32_16x16x32_bf16 v[34:37], v[174:177], v[202:205], v[34:37]
	v_mfma_f32_16x16x32_bf16 v[34:37], v[170:173], v[194:197], v[34:37]
	v_mfma_f32_16x16x32_bf16 v[18:21], v[170:173], v[206:209], v[18:21]
	v_mfma_f32_16x16x32_bf16 v[18:21], v[174:177], v[210:213], v[18:21]
	v_mfma_f32_16x16x32_bf16 v[6:9], v[174:177], v[218:221], v[6:9]
	v_mfma_f32_16x16x32_bf16 v[6:9], v[170:173], v[214:217], v[6:9]
	v_mfma_f32_16x16x32_bf16 v[2:5], v[178:181], v[214:217], v[2:5]
	v_mfma_f32_16x16x32_bf16 v[2:5], v[182:185], v[218:221], v[2:5]
	v_mfma_f32_16x16x32_bf16 v[10:13], v[182:185], v[210:213], v[10:13]
	v_mfma_f32_16x16x32_bf16 v[10:13], v[178:181], v[206:209], v[10:13]
	v_mfma_f32_16x16x32_bf16 v[26:29], v[178:181], v[194:197], v[26:29]
	v_mfma_f32_16x16x32_bf16 v[26:29], v[182:185], v[202:205], v[26:29]
	v_mfma_f32_16x16x32_bf16 v[42:45], v[182:185], v[190:193], v[42:45]
	v_mfma_f32_16x16x32_bf16 v[42:45], v[178:181], v[186:189], v[42:45]
	s_setprio 0
	s_barrier
	v_add_u32_e32 v147, s92, v142
	ds_read_b128 v[148:151], v147
	ds_read_b128 v[152:155], v147 offset:1024
	ds_read_b128 v[156:159], v147 offset:2048
	ds_read_b128 v[166:169], v147 offset:3072
	v_add_u32_e32 v147, s89, v142
	ds_read_b128 v[170:173], v147
	ds_read_b128 v[174:177], v147 offset:1024
	ds_read_b128 v[178:181], v147 offset:2048
	ds_read_b128 v[182:185], v147 offset:3072
	s_mov_b32 m0, s49
	v_lshl_add_u64 v[226:227], s[64:65], 0, v[130:131]
	ds_read_b128 v[186:189], v146 offset:32768
	ds_read_b128 v[190:193], v146 offset:33792
	ds_read_b128 v[194:197], v146 offset:34816
	ds_read_b128 v[202:205], v146 offset:35840
	ds_read_b128 v[206:209], v146 offset:36864
	ds_read_b128 v[210:213], v146 offset:37888
	ds_read_b128 v[214:217], v146 offset:38912
	ds_read_b128 v[218:221], v146 offset:39936
	global_load_lds_dwordx4 v[226:227], off
	v_lshl_add_u64 v[226:227], s[64:65], 0, v[134:135]
	s_mov_b32 m0, s74
	s_nop 0
	global_load_lds_dwordx4 v[226:227], off
	s_waitcnt vmcnt(8)
	s_waitcnt lgkmcnt(0)
	s_barrier
	s_setprio 1
	s_waitcnt lgkmcnt(0)
	v_mfma_f32_16x16x32_bf16 v[126:129], v[148:151], v[186:189], v[126:129]
	v_mfma_f32_16x16x32_bf16 v[126:129], v[152:155], v[190:193], v[126:129]
	v_mfma_f32_16x16x32_bf16 v[118:121], v[152:155], v[202:205], v[118:121]
	v_mfma_f32_16x16x32_bf16 v[118:121], v[148:151], v[194:197], v[118:121]
	v_mfma_f32_16x16x32_bf16 v[102:105], v[148:151], v[206:209], v[102:105]
	v_mfma_f32_16x16x32_bf16 v[102:105], v[152:155], v[210:213], v[102:105]
	v_mfma_f32_16x16x32_bf16 v[86:89], v[152:155], v[218:221], v[86:89]
	v_mfma_f32_16x16x32_bf16 v[86:89], v[148:151], v[214:217], v[86:89]
	v_mfma_f32_16x16x32_bf16 v[78:81], v[156:159], v[214:217], v[78:81]
	v_mfma_f32_16x16x32_bf16 v[78:81], v[166:169], v[218:221], v[78:81]
	v_mfma_f32_16x16x32_bf16 v[94:97], v[166:169], v[210:213], v[94:97]
	v_mfma_f32_16x16x32_bf16 v[94:97], v[156:159], v[206:209], v[94:97]
	v_mfma_f32_16x16x32_bf16 v[110:113], v[156:159], v[194:197], v[110:113]
	v_mfma_f32_16x16x32_bf16 v[110:113], v[166:169], v[202:205], v[110:113]
	v_mfma_f32_16x16x32_bf16 v[122:125], v[166:169], v[190:193], v[122:125]
	v_mfma_f32_16x16x32_bf16 v[122:125], v[156:159], v[186:189], v[122:125]
	v_mfma_f32_16x16x32_bf16 v[114:117], v[170:173], v[186:189], v[114:117]
	v_mfma_f32_16x16x32_bf16 v[114:117], v[174:177], v[190:193], v[114:117]
	v_mfma_f32_16x16x32_bf16 v[98:101], v[174:177], v[202:205], v[98:101]
	v_mfma_f32_16x16x32_bf16 v[98:101], v[170:173], v[194:197], v[98:101]
	v_mfma_f32_16x16x32_bf16 v[82:85], v[170:173], v[206:209], v[82:85]
	v_mfma_f32_16x16x32_bf16 v[82:85], v[174:177], v[210:213], v[82:85]
	v_mfma_f32_16x16x32_bf16 v[70:73], v[174:177], v[218:221], v[70:73]
	v_mfma_f32_16x16x32_bf16 v[70:73], v[170:173], v[214:217], v[70:73]
	v_mfma_f32_16x16x32_bf16 v[66:69], v[178:181], v[214:217], v[66:69]
	v_mfma_f32_16x16x32_bf16 v[66:69], v[182:185], v[218:221], v[66:69]
	v_mfma_f32_16x16x32_bf16 v[74:77], v[182:185], v[210:213], v[74:77]
	v_mfma_f32_16x16x32_bf16 v[74:77], v[178:181], v[206:209], v[74:77]
	v_mfma_f32_16x16x32_bf16 v[90:93], v[178:181], v[194:197], v[90:93]
	v_mfma_f32_16x16x32_bf16 v[90:93], v[182:185], v[202:205], v[90:93]
	v_mfma_f32_16x16x32_bf16 v[106:109], v[182:185], v[190:193], v[106:109]
	v_mfma_f32_16x16x32_bf16 v[106:109], v[178:181], v[186:189], v[106:109]
	s_setprio 0
	s_barrier
	s_mov_b32 m0, s87
	v_lshl_add_u64 v[160:161], v[160:161], 0, s[10:11]
	ds_read_b128 v[186:189], v146 offset:49152
	ds_read_b128 v[190:193], v146 offset:50176
	ds_read_b128 v[194:197], v146 offset:51200
	ds_read_b128 v[202:205], v146 offset:52224
	ds_read_b128 v[206:209], v146 offset:53248
	ds_read_b128 v[210:213], v146 offset:54272
	ds_read_b128 v[214:217], v146 offset:55296
	ds_read_b128 v[218:221], v146 offset:56320
	global_load_lds_dwordx4 v[160:161], off
	v_lshl_add_u64 v[160:161], v[198:199], 0, s[10:11]
	s_mov_b32 m0, s85
	s_nop 0
	global_load_lds_dwordx4 v[160:161], off
	v_lshl_add_u64 v[160:161], s[62:63], 0, v[132:133]
	s_mov_b32 m0, s86
	s_nop 0
	global_load_lds_dwordx4 v[160:161], off
	v_lshl_add_u64 v[160:161], s[62:63], 0, v[136:137]
	s_mov_b32 m0, s44
	s_nop 0
	global_load_lds_dwordx4 v[160:161], off
	v_lshl_add_u64 v[160:161], v[222:223], 0, s[10:11]
	s_mov_b32 m0, s76
	s_nop 0
	global_load_lds_dwordx4 v[160:161], off
	v_lshl_add_u64 v[160:161], v[224:225], 0, s[10:11]
	s_mov_b32 m0, s77
	s_nop 0
	global_load_lds_dwordx4 v[160:161], off
	s_waitcnt vmcnt(8)
	s_waitcnt lgkmcnt(0)
	s_barrier
	s_setprio 1
	s_waitcnt lgkmcnt(0)
	v_mfma_f32_16x16x32_bf16 v[62:65], v[148:151], v[186:189], v[62:65]
	v_mfma_f32_16x16x32_bf16 v[62:65], v[152:155], v[190:193], v[62:65]
	v_mfma_f32_16x16x32_bf16 v[54:57], v[152:155], v[202:205], v[54:57]
	v_mfma_f32_16x16x32_bf16 v[54:57], v[148:151], v[194:197], v[54:57]
	v_mfma_f32_16x16x32_bf16 v[38:41], v[148:151], v[206:209], v[38:41]
	v_mfma_f32_16x16x32_bf16 v[38:41], v[152:155], v[210:213], v[38:41]
	v_mfma_f32_16x16x32_bf16 v[22:25], v[152:155], v[218:221], v[22:25]
	v_mfma_f32_16x16x32_bf16 v[22:25], v[148:151], v[214:217], v[22:25]
	v_mfma_f32_16x16x32_bf16 v[14:17], v[156:159], v[214:217], v[14:17]
	v_mfma_f32_16x16x32_bf16 v[14:17], v[166:169], v[218:221], v[14:17]
	v_mfma_f32_16x16x32_bf16 v[30:33], v[166:169], v[210:213], v[30:33]
	v_mfma_f32_16x16x32_bf16 v[30:33], v[156:159], v[206:209], v[30:33]
	v_mfma_f32_16x16x32_bf16 v[46:49], v[156:159], v[194:197], v[46:49]
	v_mfma_f32_16x16x32_bf16 v[46:49], v[166:169], v[202:205], v[46:49]
	v_mfma_f32_16x16x32_bf16 v[58:61], v[166:169], v[190:193], v[58:61]
	v_mfma_f32_16x16x32_bf16 v[58:61], v[156:159], v[186:189], v[58:61]
	v_mfma_f32_16x16x32_bf16 v[50:53], v[170:173], v[186:189], v[50:53]
	v_mfma_f32_16x16x32_bf16 v[50:53], v[174:177], v[190:193], v[50:53]
	v_mfma_f32_16x16x32_bf16 v[34:37], v[174:177], v[202:205], v[34:37]
	v_mfma_f32_16x16x32_bf16 v[34:37], v[170:173], v[194:197], v[34:37]
	v_mfma_f32_16x16x32_bf16 v[18:21], v[170:173], v[206:209], v[18:21]
	v_mfma_f32_16x16x32_bf16 v[18:21], v[174:177], v[210:213], v[18:21]
	v_mfma_f32_16x16x32_bf16 v[6:9], v[174:177], v[218:221], v[6:9]
	v_mfma_f32_16x16x32_bf16 v[6:9], v[170:173], v[214:217], v[6:9]
	v_mfma_f32_16x16x32_bf16 v[2:5], v[178:181], v[214:217], v[2:5]
	v_mfma_f32_16x16x32_bf16 v[2:5], v[182:185], v[218:221], v[2:5]
	v_mfma_f32_16x16x32_bf16 v[10:13], v[182:185], v[210:213], v[10:13]
	v_mfma_f32_16x16x32_bf16 v[10:13], v[178:181], v[206:209], v[10:13]
	v_mfma_f32_16x16x32_bf16 v[26:29], v[178:181], v[194:197], v[26:29]
	v_mfma_f32_16x16x32_bf16 v[26:29], v[182:185], v[202:205], v[26:29]
	v_mfma_f32_16x16x32_bf16 v[42:45], v[182:185], v[190:193], v[42:45]
	v_mfma_f32_16x16x32_bf16 v[42:45], v[178:181], v[186:189], v[42:45]
	s_setprio 0
	s_barrier
	s_movk_i32 s44, 0x100
	s_andn2_b64 vcc, exec, s[60:61]
	s_mov_b64 s[62:63], -1
	s_mov_b64 s[60:61], 0
	s_cbranch_vccz .LBB0_722
	s_and_b64 vcc, exec, s[12:13]
	s_cbranch_vccz .LBB0_725
	s_barrier

.LBB0_1226:
	v_add_u32_e32 v3, s71, v165
	ds_read_b128 v[150:153], v3
	ds_read_b128 v[154:157], v3 offset:1024
	ds_read_b128 v[158:161], v3 offset:2048
	ds_read_b128 v[170:173], v3 offset:3072
	v_add_u32_e32 v3, s72, v165
	ds_read_b128 v[174:177], v3
	ds_read_b128 v[178:181], v3 offset:1024
	ds_read_b128 v[182:185], v3 offset:2048
	ds_read_b128 v[186:189], v3 offset:3072
	s_add_u32 s36, s52, 0xfff80080
	s_addc_u32 s37, s53, -1
	s_cmp_eq_u32 s78, 28
	s_cselect_b32 s59, s21, s37
	s_cselect_b32 s58, s44, s36
	s_cselect_b32 s57, s19, s77
	s_cselect_b32 s56, s55, s76
	v_lshl_add_u64 v[4:5], s[52:53], 0, v[142:143]
	s_add_i32 m0, s63, 0xc000
	ds_read_b128 v[190:193], v169
	ds_read_b128 v[194:197], v169 offset:1024
	ds_read_b128 v[202:205], v169 offset:2048
	ds_read_b128 v[206:209], v169 offset:3072
	ds_read_b128 v[210:213], v169 offset:4096
	ds_read_b128 v[214:217], v169 offset:5120
	ds_read_b128 v[218:221], v169 offset:6144
	ds_read_b128 v[222:225], v169 offset:7168
	global_load_lds_dwordx4 v[4:5], off
	v_lshl_add_u64 v[4:5], s[52:53], 0, v[144:145]
	s_add_i32 m0, s63, 0xe000
	s_nop 0
	global_load_lds_dwordx4 v[4:5], off
	s_waitcnt vmcnt(8)
	s_waitcnt lgkmcnt(0)
	s_barrier
	s_setprio 1
	s_waitcnt lgkmcnt(0)
	v_mfma_f32_16x16x32_bf16 v[130:133], v[150:153], v[190:193], v[130:133]
	v_mfma_f32_16x16x32_bf16 v[130:133], v[154:157], v[194:197], v[130:133]
	v_mfma_f32_16x16x32_bf16 v[122:125], v[154:157], v[206:209], v[122:125]
	v_mfma_f32_16x16x32_bf16 v[122:125], v[150:153], v[202:205], v[122:125]
	v_mfma_f32_16x16x32_bf16 v[114:117], v[150:153], v[210:213], v[114:117]
	v_mfma_f32_16x16x32_bf16 v[114:117], v[154:157], v[214:217], v[114:117]
	v_mfma_f32_16x16x32_bf16 v[106:109], v[154:157], v[222:225], v[106:109]
	v_mfma_f32_16x16x32_bf16 v[106:109], v[150:153], v[218:221], v[106:109]
	v_mfma_f32_16x16x32_bf16 v[102:105], v[158:161], v[218:221], v[102:105]
	v_mfma_f32_16x16x32_bf16 v[102:105], v[170:173], v[222:225], v[102:105]
	v_mfma_f32_16x16x32_bf16 v[110:113], v[170:173], v[214:217], v[110:113]
	v_mfma_f32_16x16x32_bf16 v[110:113], v[158:161], v[210:213], v[110:113]
	v_mfma_f32_16x16x32_bf16 v[118:121], v[158:161], v[202:205], v[118:121]
	v_mfma_f32_16x16x32_bf16 v[118:121], v[170:173], v[206:209], v[118:121]
	v_mfma_f32_16x16x32_bf16 v[126:129], v[170:173], v[194:197], v[126:129]
	v_mfma_f32_16x16x32_bf16 v[126:129], v[158:161], v[190:193], v[126:129]
	v_mfma_f32_16x16x32_bf16 v[98:101], v[174:177], v[190:193], v[98:101]
	v_mfma_f32_16x16x32_bf16 v[98:101], v[178:181], v[194:197], v[98:101]
	v_mfma_f32_16x16x32_bf16 v[90:93], v[178:181], v[206:209], v[90:93]
	v_mfma_f32_16x16x32_bf16 v[90:93], v[174:177], v[202:205], v[90:93]
	v_mfma_f32_16x16x32_bf16 v[82:85], v[174:177], v[210:213], v[82:85]
	v_mfma_f32_16x16x32_bf16 v[82:85], v[178:181], v[214:217], v[82:85]
	v_mfma_f32_16x16x32_bf16 v[74:77], v[178:181], v[222:225], v[74:77]
	v_mfma_f32_16x16x32_bf16 v[74:77], v[174:177], v[218:221], v[74:77]
	v_mfma_f32_16x16x32_bf16 v[70:73], v[182:185], v[218:221], v[70:73]
	v_mfma_f32_16x16x32_bf16 v[70:73], v[186:189], v[222:225], v[70:73]
	v_mfma_f32_16x16x32_bf16 v[78:81], v[186:189], v[214:217], v[78:81]
	v_mfma_f32_16x16x32_bf16 v[78:81], v[182:185], v[210:213], v[78:81]
	v_mfma_f32_16x16x32_bf16 v[86:89], v[182:185], v[202:205], v[86:89]
	v_mfma_f32_16x16x32_bf16 v[86:89], v[186:189], v[206:209], v[86:89]
	v_mfma_f32_16x16x32_bf16 v[94:97], v[186:189], v[194:197], v[94:97]
	v_mfma_f32_16x16x32_bf16 v[94:97], v[182:185], v[190:193], v[94:97]
	s_setprio 0
	s_barrier
	s_add_i32 s36, s71, s43
	v_lshl_add_u64 v[166:167], s[56:57], 0, v[138:139]
	s_mov_b32 m0, s36
	ds_read_b128 v[190:193], v169 offset:16384
	ds_read_b128 v[194:197], v169 offset:17408
	ds_read_b128 v[202:205], v169 offset:18432
	ds_read_b128 v[206:209], v169 offset:19456
	ds_read_b128 v[210:213], v169 offset:20480
	ds_read_b128 v[214:217], v169 offset:21504
	ds_read_b128 v[218:221], v169 offset:22528
	ds_read_b128 v[222:225], v169 offset:23552
	global_load_lds_dwordx4 v[166:167], off
	s_add_i32 m0, s36, 0x2000
	s_add_u32 s80, s56, 0x80000
	v_lshl_add_u64 v[198:199], s[56:57], 0, v[134:135]
	s_addc_u32 s81, s57, 0
	s_add_i32 s36, s72, s43
	global_load_lds_dwordx4 v[198:199], off
	v_lshl_add_u64 v[4:5], s[80:81], 0, v[138:139]
	s_mov_b32 m0, s36
	v_lshl_add_u64 v[226:227], s[58:59], 0, v[140:141]
	global_load_lds_dwordx4 v[4:5], off
	v_lshl_add_u64 v[4:5], s[80:81], 0, v[134:135]
	s_add_i32 m0, s36, 0x2000
	v_lshl_add_u64 v[228:229], s[58:59], 0, v[136:137]
	global_load_lds_dwordx4 v[4:5], off
	s_mov_b32 m0, s63
	s_nop 0
	global_load_lds_dwordx4 v[226:227], off
	s_mov_b32 m0, s64
	s_nop 0
	global_load_lds_dwordx4 v[228:229], off
	s_waitcnt vmcnt(8)
	s_waitcnt lgkmcnt(0)
	s_barrier
	s_setprio 1
	s_waitcnt lgkmcnt(0)
	v_mfma_f32_16x16x32_bf16 v[66:69], v[150:153], v[190:193], v[66:69]
	v_mfma_f32_16x16x32_bf16 v[62:65], v[158:161], v[190:193], v[62:65]
	v_mfma_f32_16x16x32_bf16 v[58:61], v[150:153], v[202:205], v[58:61]
	v_mfma_f32_16x16x32_bf16 v[54:57], v[158:161], v[202:205], v[54:57]
	v_mfma_f32_16x16x32_bf16 v[50:53], v[150:153], v[210:213], v[50:53]
	v_mfma_f32_16x16x32_bf16 v[46:49], v[158:161], v[210:213], v[46:49]
	v_mfma_f32_16x16x32_bf16 v[42:45], v[150:153], v[218:221], v[42:45]
	v_mfma_f32_16x16x32_bf16 v[38:41], v[158:161], v[218:221], v[38:41]
	v_mfma_f32_16x16x32_bf16 v[66:69], v[154:157], v[194:197], v[66:69]
	v_mfma_f32_16x16x32_bf16 v[62:65], v[170:173], v[194:197], v[62:65]
	v_mfma_f32_16x16x32_bf16 v[58:61], v[154:157], v[206:209], v[58:61]
	v_mfma_f32_16x16x32_bf16 v[54:57], v[170:173], v[206:209], v[54:57]
	v_mfma_f32_16x16x32_bf16 v[50:53], v[154:157], v[214:217], v[50:53]
	v_mfma_f32_16x16x32_bf16 v[46:49], v[170:173], v[214:217], v[46:49]
	v_mfma_f32_16x16x32_bf16 v[42:45], v[154:157], v[222:225], v[42:45]
	v_mfma_f32_16x16x32_bf16 v[38:41], v[170:173], v[222:225], v[38:41]
	s_setprio 0
	s_setprio 1
	v_mfma_f32_16x16x32_bf16 v[34:37], v[174:177], v[190:193], v[34:37]
	v_mfma_f32_16x16x32_bf16 v[30:33], v[182:185], v[190:193], v[30:33]
	v_mfma_f32_16x16x32_bf16 v[26:29], v[174:177], v[202:205], v[26:29]
	v_mfma_f32_16x16x32_bf16 v[22:25], v[182:185], v[202:205], v[22:25]
	v_mfma_f32_16x16x32_bf16 v[18:21], v[174:177], v[210:213], v[18:21]
	v_mfma_f32_16x16x32_bf16 v[14:17], v[182:185], v[210:213], v[14:17]
	v_mfma_f32_16x16x32_bf16 v[10:13], v[174:177], v[218:221], v[10:13]
	v_mfma_f32_16x16x32_bf16 v[4:7], v[182:185], v[218:221], v[6:9]
	v_mfma_f32_16x16x32_bf16 v[34:37], v[178:181], v[194:197], v[34:37]
	v_mfma_f32_16x16x32_bf16 v[30:33], v[186:189], v[194:197], v[30:33]
	v_mfma_f32_16x16x32_bf16 v[26:29], v[178:181], v[206:209], v[26:29]
	v_mfma_f32_16x16x32_bf16 v[22:25], v[186:189], v[206:209], v[22:25]
	v_mfma_f32_16x16x32_bf16 v[18:21], v[178:181], v[214:217], v[18:21]
	v_mfma_f32_16x16x32_bf16 v[14:17], v[186:189], v[214:217], v[14:17]
	v_mfma_f32_16x16x32_bf16 v[10:13], v[178:181], v[222:225], v[10:13]
	v_mfma_f32_16x16x32_bf16 v[4:7], v[186:189], v[222:225], v[4:7]
	s_setprio 0
	s_barrier
	s_add_i32 s36, 0, 0x18000
	v_add_u32_e32 v3, s36, v165
	s_add_i32 s37, 0, 0x1c000
	ds_read_b128 v[150:153], v3
	ds_read_b128 v[154:157], v3 offset:1024
	ds_read_b128 v[158:161], v3 offset:2048
	ds_read_b128 v[170:173], v3 offset:3072
	v_add_u32_e32 v3, s37, v165
	ds_read_b128 v[174:177], v3
	ds_read_b128 v[178:181], v3 offset:1024
	ds_read_b128 v[182:185], v3 offset:2048
	ds_read_b128 v[186:189], v3 offset:3072
	s_add_u32 s58, s58, 0x80000
	s_addc_u32 s59, s59, 0
	s_mov_b32 m0, s65
	v_lshl_add_u64 v[8:9], s[58:59], 0, v[140:141]
	ds_read_b128 v[190:193], v169 offset:32768
	ds_read_b128 v[194:197], v169 offset:33792
	ds_read_b128 v[202:205], v169 offset:34816
	ds_read_b128 v[206:209], v169 offset:35840
	ds_read_b128 v[210:213], v169 offset:36864
	ds_read_b128 v[214:217], v169 offset:37888
	ds_read_b128 v[218:221], v169 offset:38912
	ds_read_b128 v[222:225], v169 offset:39936
	global_load_lds_dwordx4 v[8:9], off
	v_lshl_add_u64 v[8:9], s[58:59], 0, v[136:137]
	s_mov_b32 m0, s66
	s_nop 0
	global_load_lds_dwordx4 v[8:9], off
	s_waitcnt vmcnt(8)
	s_waitcnt lgkmcnt(0)
	s_barrier
	s_setprio 1
	s_waitcnt lgkmcnt(0)
	v_mfma_f32_16x16x32_bf16 v[130:133], v[150:153], v[190:193], v[130:133]
	v_mfma_f32_16x16x32_bf16 v[130:133], v[154:157], v[194:197], v[130:133]
	v_mfma_f32_16x16x32_bf16 v[122:125], v[154:157], v[206:209], v[122:125]
	v_mfma_f32_16x16x32_bf16 v[122:125], v[150:153], v[202:205], v[122:125]
	v_mfma_f32_16x16x32_bf16 v[114:117], v[150:153], v[210:213], v[114:117]
	v_mfma_f32_16x16x32_bf16 v[114:117], v[154:157], v[214:217], v[114:117]
	v_mfma_f32_16x16x32_bf16 v[106:109], v[154:157], v[222:225], v[106:109]
	v_mfma_f32_16x16x32_bf16 v[106:109], v[150:153], v[218:221], v[106:109]
	v_mfma_f32_16x16x32_bf16 v[102:105], v[158:161], v[218:221], v[102:105]
	v_mfma_f32_16x16x32_bf16 v[102:105], v[170:173], v[222:225], v[102:105]
	v_mfma_f32_16x16x32_bf16 v[110:113], v[170:173], v[214:217], v[110:113]
	v_mfma_f32_16x16x32_bf16 v[110:113], v[158:161], v[210:213], v[110:113]
	v_mfma_f32_16x16x32_bf16 v[118:121], v[158:161], v[202:205], v[118:121]
	v_mfma_f32_16x16x32_bf16 v[118:121], v[170:173], v[206:209], v[118:121]
	v_mfma_f32_16x16x32_bf16 v[126:129], v[170:173], v[194:197], v[126:129]
	v_mfma_f32_16x16x32_bf16 v[126:129], v[158:161], v[190:193], v[126:129]
	v_mfma_f32_16x16x32_bf16 v[98:101], v[174:177], v[190:193], v[98:101]
	v_mfma_f32_16x16x32_bf16 v[98:101], v[178:181], v[194:197], v[98:101]
	v_mfma_f32_16x16x32_bf16 v[90:93], v[178:181], v[206:209], v[90:93]
	v_mfma_f32_16x16x32_bf16 v[90:93], v[174:177], v[202:205], v[90:93]
	v_mfma_f32_16x16x32_bf16 v[82:85], v[174:177], v[210:213], v[82:85]
	v_mfma_f32_16x16x32_bf16 v[82:85], v[178:181], v[214:217], v[82:85]
	v_mfma_f32_16x16x32_bf16 v[74:77], v[178:181], v[222:225], v[74:77]
	v_mfma_f32_16x16x32_bf16 v[74:77], v[174:177], v[218:221], v[74:77]
	v_mfma_f32_16x16x32_bf16 v[70:73], v[182:185], v[218:221], v[70:73]
	v_mfma_f32_16x16x32_bf16 v[70:73], v[186:189], v[222:225], v[70:73]
	v_mfma_f32_16x16x32_bf16 v[78:81], v[186:189], v[214:217], v[78:81]
	v_mfma_f32_16x16x32_bf16 v[78:81], v[182:185], v[210:213], v[78:81]
	v_mfma_f32_16x16x32_bf16 v[86:89], v[182:185], v[202:205], v[86:89]
	v_mfma_f32_16x16x32_bf16 v[86:89], v[186:189], v[206:209], v[86:89]
	v_mfma_f32_16x16x32_bf16 v[94:97], v[186:189], v[194:197], v[94:97]
	v_mfma_f32_16x16x32_bf16 v[94:97], v[182:185], v[190:193], v[94:97]
	s_setprio 0
	s_barrier
	s_add_i32 s36, s36, s43
	v_lshl_add_u64 v[8:9], v[166:167], 0, s[10:11]
	s_mov_b32 m0, s36
	ds_read_b128 v[190:193], v169 offset:49152
	ds_read_b128 v[194:197], v169 offset:50176
	ds_read_b128 v[202:205], v169 offset:51200
	ds_read_b128 v[206:209], v169 offset:52224
	ds_read_b128 v[210:213], v169 offset:53248
	ds_read_b128 v[214:217], v169 offset:54272
	ds_read_b128 v[218:221], v169 offset:55296
	ds_read_b128 v[222:225], v169 offset:56320
	global_load_lds_dwordx4 v[8:9], off
	s_add_i32 m0, s36, 0x2000
	s_add_u32 s56, s56, 0x80080
	v_lshl_add_u64 v[8:9], v[198:199], 0, s[10:11]
	s_addc_u32 s57, s57, 0
	s_add_i32 s36, s37, s43
	global_load_lds_dwordx4 v[8:9], off
	v_lshl_add_u64 v[8:9], s[56:57], 0, v[138:139]
	s_mov_b32 m0, s36
	s_nop 0
	global_load_lds_dwordx4 v[8:9], off
	v_lshl_add_u64 v[8:9], s[56:57], 0, v[134:135]
	s_add_i32 m0, s36, 0x2000
	s_nop 0
	global_load_lds_dwordx4 v[8:9], off
	v_lshl_add_u64 v[8:9], v[226:227], 0, s[10:11]
	s_mov_b32 m0, s69
	s_nop 0
	global_load_lds_dwordx4 v[8:9], off
	v_lshl_add_u64 v[8:9], v[228:229], 0, s[10:11]
	s_mov_b32 m0, s70
	s_nop 0
	global_load_lds_dwordx4 v[8:9], off
	s_waitcnt vmcnt(8)
	s_waitcnt lgkmcnt(0)
	s_barrier
	s_setprio 1
	s_waitcnt lgkmcnt(0)
	v_mfma_f32_16x16x32_bf16 v[66:69], v[150:153], v[190:193], v[66:69]
	v_mfma_f32_16x16x32_bf16 v[62:65], v[158:161], v[190:193], v[62:65]
	v_mfma_f32_16x16x32_bf16 v[58:61], v[150:153], v[202:205], v[58:61]
	v_mfma_f32_16x16x32_bf16 v[54:57], v[158:161], v[202:205], v[54:57]
	v_mfma_f32_16x16x32_bf16 v[50:53], v[150:153], v[210:213], v[50:53]
	v_mfma_f32_16x16x32_bf16 v[46:49], v[158:161], v[210:213], v[46:49]
	v_mfma_f32_16x16x32_bf16 v[42:45], v[150:153], v[218:221], v[42:45]
	v_mfma_f32_16x16x32_bf16 v[38:41], v[158:161], v[218:221], v[38:41]
	v_mfma_f32_16x16x32_bf16 v[66:69], v[154:157], v[194:197], v[66:69]
	v_mfma_f32_16x16x32_bf16 v[62:65], v[170:173], v[194:197], v[62:65]
	v_mfma_f32_16x16x32_bf16 v[58:61], v[154:157], v[206:209], v[58:61]
	v_mfma_f32_16x16x32_bf16 v[54:57], v[170:173], v[206:209], v[54:57]
	v_mfma_f32_16x16x32_bf16 v[50:53], v[154:157], v[214:217], v[50:53]
	v_mfma_f32_16x16x32_bf16 v[46:49], v[170:173], v[214:217], v[46:49]
	v_mfma_f32_16x16x32_bf16 v[42:45], v[154:157], v[222:225], v[42:45]
	v_mfma_f32_16x16x32_bf16 v[38:41], v[170:173], v[222:225], v[38:41]
	s_setprio 0
	s_setprio 1
	v_mfma_f32_16x16x32_bf16 v[34:37], v[174:177], v[190:193], v[34:37]
	v_mfma_f32_16x16x32_bf16 v[30:33], v[182:185], v[190:193], v[30:33]
	v_mfma_f32_16x16x32_bf16 v[26:29], v[174:177], v[202:205], v[26:29]
	v_mfma_f32_16x16x32_bf16 v[22:25], v[182:185], v[202:205], v[22:25]
	v_mfma_f32_16x16x32_bf16 v[18:21], v[174:177], v[210:213], v[18:21]
	v_mfma_f32_16x16x32_bf16 v[14:17], v[182:185], v[210:213], v[14:17]
	v_mfma_f32_16x16x32_bf16 v[8:11], v[174:177], v[218:221], v[10:13]
	v_mfma_f32_16x16x32_bf16 v[4:7], v[182:185], v[218:221], v[4:7]
	v_mfma_f32_16x16x32_bf16 v[34:37], v[178:181], v[194:197], v[34:37]
	v_mfma_f32_16x16x32_bf16 v[30:33], v[186:189], v[194:197], v[30:33]
	v_mfma_f32_16x16x32_bf16 v[26:29], v[178:181], v[206:209], v[26:29]
	v_mfma_f32_16x16x32_bf16 v[22:25], v[186:189], v[206:209], v[22:25]
	v_mfma_f32_16x16x32_bf16 v[18:21], v[178:181], v[214:217], v[18:21]
	v_mfma_f32_16x16x32_bf16 v[14:17], v[186:189], v[214:217], v[14:17]
	v_mfma_f32_16x16x32_bf16 v[10:13], v[178:181], v[222:225], v[8:11]
	v_mfma_f32_16x16x32_bf16 v[6:9], v[186:189], v[222:225], v[4:7]
	s_setprio 0
	s_barrier
	s_add_i32 s78, s78, 2
	s_add_u32 s52, s52, 0x100
	s_addc_u32 s53, s53, 0
	s_add_u32 s76, s76, 0x100
	s_addc_u32 s77, s77, 0
	s_cmp_gt_u32 s78, 29
	s_cbranch_scc0 .LBB0_1226
	s_and_b64 vcc, exec, s[12:13]
	s_cbranch_vccz .LBB0_1229
	s_barrier

.LBB0_1397:
	ds_read_b128 v[146:149], v154
	ds_read_b128 v[158:161], v154 offset:1024
	ds_read_b128 v[166:169], v154 offset:2048
	ds_read_b128 v[170:173], v154 offset:3072
	ds_read_b128 v[174:177], v155
	ds_read_b128 v[178:181], v155 offset:1024
	ds_read_b128 v[182:185], v155 offset:2048
	ds_read_b128 v[186:189], v155 offset:3072
	s_add_i32 s93, s44, 2
	s_add_u32 s36, s62, 0xfff00080
	s_addc_u32 s37, s63, -1
	s_cmp_eq_u32 s59, s44
	s_cselect_b32 s67, s38, s37
	s_cselect_b32 s66, s39, s36
	s_cselect_b32 s65, s51, s92
	s_cselect_b32 s64, s53, s61
	v_lshl_add_u64 v[150:151], s[62:63], 0, v[140:141]
	s_add_i32 m0, s72, 0xc000
	ds_read_b128 v[190:193], v156
	ds_read_b128 v[194:197], v156 offset:1024
	ds_read_b128 v[202:205], v156 offset:2048
	ds_read_b128 v[206:209], v156 offset:3072
	ds_read_b128 v[210:213], v156 offset:4096
	ds_read_b128 v[214:217], v156 offset:5120
	ds_read_b128 v[218:221], v156 offset:6144
	ds_read_b128 v[222:225], v156 offset:7168
	global_load_lds_dwordx4 v[150:151], off
	v_lshl_add_u64 v[150:151], s[62:63], 0, v[142:143]
	s_add_i32 m0, s72, 0xe000
	s_nop 0
	global_load_lds_dwordx4 v[150:151], off
	s_waitcnt vmcnt(8)
	s_waitcnt lgkmcnt(0)
	s_barrier
	s_setprio 1
	s_waitcnt lgkmcnt(0)
	v_mfma_f32_16x16x32_bf16 v[126:129], v[146:149], v[190:193], v[126:129]
	v_mfma_f32_16x16x32_bf16 v[126:129], v[158:161], v[194:197], v[126:129]
	v_mfma_f32_16x16x32_bf16 v[110:113], v[158:161], v[206:209], v[110:113]
	v_mfma_f32_16x16x32_bf16 v[110:113], v[146:149], v[202:205], v[110:113]
	v_mfma_f32_16x16x32_bf16 v[94:97], v[146:149], v[210:213], v[94:97]
	v_mfma_f32_16x16x32_bf16 v[94:97], v[158:161], v[214:217], v[94:97]
	v_mfma_f32_16x16x32_bf16 v[78:81], v[158:161], v[222:225], v[78:81]
	v_mfma_f32_16x16x32_bf16 v[78:81], v[146:149], v[218:221], v[78:81]
	v_mfma_f32_16x16x32_bf16 v[74:77], v[166:169], v[218:221], v[74:77]
	v_mfma_f32_16x16x32_bf16 v[74:77], v[170:173], v[222:225], v[74:77]
	v_mfma_f32_16x16x32_bf16 v[90:93], v[170:173], v[214:217], v[90:93]
	v_mfma_f32_16x16x32_bf16 v[90:93], v[166:169], v[210:213], v[90:93]
	v_mfma_f32_16x16x32_bf16 v[106:109], v[166:169], v[202:205], v[106:109]
	v_mfma_f32_16x16x32_bf16 v[106:109], v[170:173], v[206:209], v[106:109]
	v_mfma_f32_16x16x32_bf16 v[122:125], v[170:173], v[194:197], v[122:125]
	v_mfma_f32_16x16x32_bf16 v[122:125], v[166:169], v[190:193], v[122:125]
	v_mfma_f32_16x16x32_bf16 v[118:121], v[174:177], v[190:193], v[118:121]
	v_mfma_f32_16x16x32_bf16 v[118:121], v[178:181], v[194:197], v[118:121]
	v_mfma_f32_16x16x32_bf16 v[102:105], v[178:181], v[206:209], v[102:105]
	v_mfma_f32_16x16x32_bf16 v[102:105], v[174:177], v[202:205], v[102:105]
	v_mfma_f32_16x16x32_bf16 v[86:89], v[174:177], v[210:213], v[86:89]
	v_mfma_f32_16x16x32_bf16 v[86:89], v[178:181], v[214:217], v[86:89]
	v_mfma_f32_16x16x32_bf16 v[70:73], v[178:181], v[222:225], v[70:73]
	v_mfma_f32_16x16x32_bf16 v[70:73], v[174:177], v[218:221], v[70:73]
	v_mfma_f32_16x16x32_bf16 v[66:69], v[182:185], v[218:221], v[66:69]
	v_mfma_f32_16x16x32_bf16 v[66:69], v[186:189], v[222:225], v[66:69]
	v_mfma_f32_16x16x32_bf16 v[82:85], v[186:189], v[214:217], v[82:85]
	v_mfma_f32_16x16x32_bf16 v[82:85], v[182:185], v[210:213], v[82:85]
	v_mfma_f32_16x16x32_bf16 v[98:101], v[182:185], v[202:205], v[98:101]
	v_mfma_f32_16x16x32_bf16 v[98:101], v[186:189], v[206:209], v[98:101]
	v_mfma_f32_16x16x32_bf16 v[114:117], v[186:189], v[194:197], v[114:117]
	v_mfma_f32_16x16x32_bf16 v[114:117], v[182:185], v[190:193], v[114:117]
	s_setprio 0
	s_barrier
	s_add_i32 s36, s82, s69
	v_lshl_add_u64 v[150:151], s[64:65], 0, v[132:133]
	s_mov_b32 m0, s36
	ds_read_b128 v[190:193], v156 offset:16384
	ds_read_b128 v[194:197], v156 offset:17408
	ds_read_b128 v[202:205], v156 offset:18432
	ds_read_b128 v[206:209], v156 offset:19456
	ds_read_b128 v[210:213], v156 offset:20480
	ds_read_b128 v[214:217], v156 offset:21504
	ds_read_b128 v[218:221], v156 offset:22528
	ds_read_b128 v[222:225], v156 offset:23552
	global_load_lds_dwordx4 v[150:151], off
	s_add_i32 m0, s36, 0x2000
	s_add_u32 s94, s64, 0x100000
	v_lshl_add_u64 v[198:199], s[64:65], 0, v[136:137]
	s_addc_u32 s95, s65, 0
	s_add_i32 s36, s83, s69
	global_load_lds_dwordx4 v[198:199], off
	v_lshl_add_u64 v[226:227], s[94:95], 0, v[132:133]
	s_mov_b32 m0, s36
	v_lshl_add_u64 v[228:229], s[66:67], 0, v[134:135]
	global_load_lds_dwordx4 v[226:227], off
	v_lshl_add_u64 v[226:227], s[94:95], 0, v[136:137]
	s_add_i32 m0, s36, 0x2000
	s_nop 0
	global_load_lds_dwordx4 v[226:227], off
	v_lshl_add_u64 v[226:227], s[66:67], 0, v[130:131]
	s_mov_b32 m0, s72
	s_nop 0
	global_load_lds_dwordx4 v[226:227], off
	s_mov_b32 m0, s73
	s_nop 0
	global_load_lds_dwordx4 v[228:229], off
	s_waitcnt vmcnt(8)
	s_waitcnt lgkmcnt(0)
	s_barrier
	s_setprio 1
	s_waitcnt lgkmcnt(0)
	v_mfma_f32_16x16x32_bf16 v[62:65], v[146:149], v[190:193], v[62:65]
	v_mfma_f32_16x16x32_bf16 v[62:65], v[158:161], v[194:197], v[62:65]
	v_mfma_f32_16x16x32_bf16 v[46:49], v[158:161], v[206:209], v[46:49]
	v_mfma_f32_16x16x32_bf16 v[46:49], v[146:149], v[202:205], v[46:49]
	v_mfma_f32_16x16x32_bf16 v[30:33], v[146:149], v[210:213], v[30:33]
	v_mfma_f32_16x16x32_bf16 v[30:33], v[158:161], v[214:217], v[30:33]
	v_mfma_f32_16x16x32_bf16 v[14:17], v[158:161], v[222:225], v[14:17]
	v_mfma_f32_16x16x32_bf16 v[14:17], v[146:149], v[218:221], v[14:17]
	v_mfma_f32_16x16x32_bf16 v[10:13], v[166:169], v[218:221], v[10:13]
	v_mfma_f32_16x16x32_bf16 v[10:13], v[170:173], v[222:225], v[10:13]
	v_mfma_f32_16x16x32_bf16 v[26:29], v[170:173], v[214:217], v[26:29]
	v_mfma_f32_16x16x32_bf16 v[26:29], v[166:169], v[210:213], v[26:29]
	v_mfma_f32_16x16x32_bf16 v[42:45], v[166:169], v[202:205], v[42:45]
	v_mfma_f32_16x16x32_bf16 v[42:45], v[170:173], v[206:209], v[42:45]
	v_mfma_f32_16x16x32_bf16 v[58:61], v[170:173], v[194:197], v[58:61]
	v_mfma_f32_16x16x32_bf16 v[58:61], v[166:169], v[190:193], v[58:61]
	v_mfma_f32_16x16x32_bf16 v[54:57], v[174:177], v[190:193], v[54:57]
	v_mfma_f32_16x16x32_bf16 v[54:57], v[178:181], v[194:197], v[54:57]
	v_mfma_f32_16x16x32_bf16 v[38:41], v[178:181], v[206:209], v[38:41]
	v_mfma_f32_16x16x32_bf16 v[38:41], v[174:177], v[202:205], v[38:41]
	v_mfma_f32_16x16x32_bf16 v[22:25], v[174:177], v[210:213], v[22:25]
	v_mfma_f32_16x16x32_bf16 v[22:25], v[178:181], v[214:217], v[22:25]
	v_mfma_f32_16x16x32_bf16 v[6:9], v[178:181], v[222:225], v[6:9]
	v_mfma_f32_16x16x32_bf16 v[6:9], v[174:177], v[218:221], v[6:9]
	v_mfma_f32_16x16x32_bf16 v[2:5], v[182:185], v[218:221], v[2:5]
	v_mfma_f32_16x16x32_bf16 v[2:5], v[186:189], v[222:225], v[2:5]
	v_mfma_f32_16x16x32_bf16 v[18:21], v[186:189], v[214:217], v[18:21]
	v_mfma_f32_16x16x32_bf16 v[18:21], v[182:185], v[210:213], v[18:21]
	v_mfma_f32_16x16x32_bf16 v[34:37], v[182:185], v[202:205], v[34:37]
	v_mfma_f32_16x16x32_bf16 v[34:37], v[186:189], v[206:209], v[34:37]
	v_mfma_f32_16x16x32_bf16 v[50:53], v[186:189], v[194:197], v[50:53]
	v_mfma_f32_16x16x32_bf16 v[50:53], v[182:185], v[190:193], v[50:53]
	s_setprio 0
	s_barrier
	s_add_i32 s36, 0, 0x18000
	v_add_u32_e32 v138, s36, v152
	s_add_i32 s37, 0, 0x1c000
	ds_read_b128 v[146:149], v138
	ds_read_b128 v[158:161], v138 offset:1024
	ds_read_b128 v[166:169], v138 offset:2048
	ds_read_b128 v[170:173], v138 offset:3072
	v_add_u32_e32 v138, s37, v152
	ds_read_b128 v[174:177], v138
	ds_read_b128 v[178:181], v138 offset:1024
	ds_read_b128 v[182:185], v138 offset:2048
	ds_read_b128 v[186:189], v138 offset:3072
	s_add_u32 s66, s66, 0x100000
	s_addc_u32 s67, s67, 0
	s_mov_b32 m0, s74
	v_lshl_add_u64 v[230:231], s[66:67], 0, v[130:131]
	ds_read_b128 v[190:193], v156 offset:32768
	ds_read_b128 v[194:197], v156 offset:33792
	ds_read_b128 v[202:205], v156 offset:34816
	ds_read_b128 v[206:209], v156 offset:35840
	ds_read_b128 v[210:213], v156 offset:36864
	ds_read_b128 v[214:217], v156 offset:37888
	ds_read_b128 v[218:221], v156 offset:38912
	ds_read_b128 v[222:225], v156 offset:39936
	global_load_lds_dwordx4 v[230:231], off
	v_lshl_add_u64 v[230:231], s[66:67], 0, v[134:135]
	s_mov_b32 m0, s75
	s_nop 0
	global_load_lds_dwordx4 v[230:231], off
	s_waitcnt vmcnt(8)
	s_waitcnt lgkmcnt(0)
	s_barrier
	s_setprio 1
	s_waitcnt lgkmcnt(0)
	v_mfma_f32_16x16x32_bf16 v[126:129], v[146:149], v[190:193], v[126:129]
	v_mfma_f32_16x16x32_bf16 v[126:129], v[158:161], v[194:197], v[126:129]
	v_mfma_f32_16x16x32_bf16 v[110:113], v[158:161], v[206:209], v[110:113]
	v_mfma_f32_16x16x32_bf16 v[110:113], v[146:149], v[202:205], v[110:113]
	v_mfma_f32_16x16x32_bf16 v[94:97], v[146:149], v[210:213], v[94:97]
	v_mfma_f32_16x16x32_bf16 v[94:97], v[158:161], v[214:217], v[94:97]
	v_mfma_f32_16x16x32_bf16 v[78:81], v[158:161], v[222:225], v[78:81]
	v_mfma_f32_16x16x32_bf16 v[78:81], v[146:149], v[218:221], v[78:81]
	v_mfma_f32_16x16x32_bf16 v[74:77], v[166:169], v[218:221], v[74:77]
	v_mfma_f32_16x16x32_bf16 v[74:77], v[170:173], v[222:225], v[74:77]
	v_mfma_f32_16x16x32_bf16 v[90:93], v[170:173], v[214:217], v[90:93]
	v_mfma_f32_16x16x32_bf16 v[90:93], v[166:169], v[210:213], v[90:93]
	v_mfma_f32_16x16x32_bf16 v[106:109], v[166:169], v[202:205], v[106:109]
	v_mfma_f32_16x16x32_bf16 v[106:109], v[170:173], v[206:209], v[106:109]
	v_mfma_f32_16x16x32_bf16 v[122:125], v[170:173], v[194:197], v[122:125]
	v_mfma_f32_16x16x32_bf16 v[122:125], v[166:169], v[190:193], v[122:125]
	v_mfma_f32_16x16x32_bf16 v[118:121], v[174:177], v[190:193], v[118:121]
	v_mfma_f32_16x16x32_bf16 v[118:121], v[178:181], v[194:197], v[118:121]
	v_mfma_f32_16x16x32_bf16 v[102:105], v[178:181], v[206:209], v[102:105]
	v_mfma_f32_16x16x32_bf16 v[102:105], v[174:177], v[202:205], v[102:105]
	v_mfma_f32_16x16x32_bf16 v[86:89], v[174:177], v[210:213], v[86:89]
	v_mfma_f32_16x16x32_bf16 v[86:89], v[178:181], v[214:217], v[86:89]
	v_mfma_f32_16x16x32_bf16 v[70:73], v[178:181], v[222:225], v[70:73]
	v_mfma_f32_16x16x32_bf16 v[70:73], v[174:177], v[218:221], v[70:73]
	v_mfma_f32_16x16x32_bf16 v[66:69], v[182:185], v[218:221], v[66:69]
	v_mfma_f32_16x16x32_bf16 v[66:69], v[186:189], v[222:225], v[66:69]
	v_mfma_f32_16x16x32_bf16 v[82:85], v[186:189], v[214:217], v[82:85]
	v_mfma_f32_16x16x32_bf16 v[82:85], v[182:185], v[210:213], v[82:85]
	v_mfma_f32_16x16x32_bf16 v[98:101], v[182:185], v[202:205], v[98:101]
	v_mfma_f32_16x16x32_bf16 v[98:101], v[186:189], v[206:209], v[98:101]
	v_mfma_f32_16x16x32_bf16 v[114:117], v[186:189], v[194:197], v[114:117]
	v_mfma_f32_16x16x32_bf16 v[114:117], v[182:185], v[190:193], v[114:117]
	s_setprio 0
	s_barrier
	s_add_i32 s36, s36, s69
	v_lshl_add_u64 v[150:151], v[150:151], 0, s[16:17]
	s_mov_b32 m0, s36
	ds_read_b128 v[190:193], v156 offset:49152
	ds_read_b128 v[194:197], v156 offset:50176
	ds_read_b128 v[202:205], v156 offset:51200
	ds_read_b128 v[206:209], v156 offset:52224
	ds_read_b128 v[210:213], v156 offset:53248
	ds_read_b128 v[214:217], v156 offset:54272
	ds_read_b128 v[218:221], v156 offset:55296
	ds_read_b128 v[222:225], v156 offset:56320
	global_load_lds_dwordx4 v[150:151], off
	s_add_i32 m0, s36, 0x2000
	s_add_u32 s64, s64, 0x100080
	v_lshl_add_u64 v[150:151], v[198:199], 0, s[16:17]
	s_addc_u32 s65, s65, 0
	s_add_i32 s36, s37, s69
	global_load_lds_dwordx4 v[150:151], off
	v_lshl_add_u64 v[150:151], s[64:65], 0, v[132:133]
	s_mov_b32 m0, s36
	s_nop 0
	global_load_lds_dwordx4 v[150:151], off
	v_lshl_add_u64 v[150:151], s[64:65], 0, v[136:137]
	s_add_i32 m0, s36, 0x2000
	s_nop 0
	global_load_lds_dwordx4 v[150:151], off
	v_lshl_add_u64 v[150:151], v[226:227], 0, s[16:17]
	s_mov_b32 m0, s78
	s_nop 0
	global_load_lds_dwordx4 v[150:151], off
	v_lshl_add_u64 v[150:151], v[228:229], 0, s[16:17]
	s_mov_b32 m0, s79
	s_nop 0
	global_load_lds_dwordx4 v[150:151], off
	s_waitcnt vmcnt(8)
	s_waitcnt lgkmcnt(0)
	s_barrier
	s_setprio 1
	s_waitcnt lgkmcnt(0)
	v_mfma_f32_16x16x32_bf16 v[62:65], v[146:149], v[190:193], v[62:65]
	v_mfma_f32_16x16x32_bf16 v[62:65], v[158:161], v[194:197], v[62:65]
	v_mfma_f32_16x16x32_bf16 v[46:49], v[158:161], v[206:209], v[46:49]
	v_mfma_f32_16x16x32_bf16 v[46:49], v[146:149], v[202:205], v[46:49]
	v_mfma_f32_16x16x32_bf16 v[30:33], v[146:149], v[210:213], v[30:33]
	v_mfma_f32_16x16x32_bf16 v[30:33], v[158:161], v[214:217], v[30:33]
	v_mfma_f32_16x16x32_bf16 v[14:17], v[158:161], v[222:225], v[14:17]
	v_mfma_f32_16x16x32_bf16 v[14:17], v[146:149], v[218:221], v[14:17]
	v_mfma_f32_16x16x32_bf16 v[10:13], v[166:169], v[218:221], v[10:13]
	v_mfma_f32_16x16x32_bf16 v[10:13], v[170:173], v[222:225], v[10:13]
	v_mfma_f32_16x16x32_bf16 v[26:29], v[170:173], v[214:217], v[26:29]
	v_mfma_f32_16x16x32_bf16 v[26:29], v[166:169], v[210:213], v[26:29]
	v_mfma_f32_16x16x32_bf16 v[42:45], v[166:169], v[202:205], v[42:45]
	v_mfma_f32_16x16x32_bf16 v[42:45], v[170:173], v[206:209], v[42:45]
	v_mfma_f32_16x16x32_bf16 v[58:61], v[170:173], v[194:197], v[58:61]
	v_mfma_f32_16x16x32_bf16 v[58:61], v[166:169], v[190:193], v[58:61]
	v_mfma_f32_16x16x32_bf16 v[54:57], v[174:177], v[190:193], v[54:57]
	v_mfma_f32_16x16x32_bf16 v[54:57], v[178:181], v[194:197], v[54:57]
	v_mfma_f32_16x16x32_bf16 v[38:41], v[178:181], v[206:209], v[38:41]
	v_mfma_f32_16x16x32_bf16 v[38:41], v[174:177], v[202:205], v[38:41]
	v_mfma_f32_16x16x32_bf16 v[22:25], v[174:177], v[210:213], v[22:25]
	v_mfma_f32_16x16x32_bf16 v[22:25], v[178:181], v[214:217], v[22:25]
	v_mfma_f32_16x16x32_bf16 v[6:9], v[178:181], v[222:225], v[6:9]
	v_mfma_f32_16x16x32_bf16 v[6:9], v[174:177], v[218:221], v[6:9]
	v_mfma_f32_16x16x32_bf16 v[2:5], v[182:185], v[218:221], v[2:5]
	v_mfma_f32_16x16x32_bf16 v[2:5], v[186:189], v[222:225], v[2:5]
	v_mfma_f32_16x16x32_bf16 v[18:21], v[186:189], v[214:217], v[18:21]
	v_mfma_f32_16x16x32_bf16 v[18:21], v[182:185], v[210:213], v[18:21]
	v_mfma_f32_16x16x32_bf16 v[34:37], v[182:185], v[202:205], v[34:37]
	v_mfma_f32_16x16x32_bf16 v[34:37], v[186:189], v[206:209], v[34:37]
	v_mfma_f32_16x16x32_bf16 v[50:53], v[186:189], v[194:197], v[50:53]
	v_mfma_f32_16x16x32_bf16 v[50:53], v[182:185], v[190:193], v[50:53]
	s_setprio 0
	s_barrier
	s_add_u32 s62, s62, 0x100
	s_addc_u32 s63, s63, 0
	s_add_u32 s61, s61, 0x100
	s_addc_u32 s92, s92, 0
	s_cmp_ge_i32 s93, s11
	s_mov_b32 s44, s93
	s_cbranch_scc0 .LBB0_1397
	s_and_b64 vcc, exec, s[18:19]
	s_cbranch_vccz .LBB0_1400

.LBB0_1631:
	ds_read_b128 v[166:169], v158
	ds_read_b128 v[170:173], v158 offset:1024
	ds_read_b128 v[174:177], v158 offset:2048
	ds_read_b128 v[178:181], v158 offset:3072
	ds_read_b128 v[182:185], v159
	ds_read_b128 v[186:189], v159 offset:1024
	ds_read_b128 v[190:193], v159 offset:2048
	ds_read_b128 v[194:197], v159 offset:3072
	s_add_u32 s36, s54, 0xfff00080
	s_addc_u32 s37, s55, -1
	s_cmp_eq_u32 s78, 60
	s_cselect_b32 s59, s21, s37
	s_cselect_b32 s58, s74, s36
	s_cselect_b32 s57, s19, s77
	s_cselect_b32 s56, s75, s76
	v_lshl_add_u64 v[198:199], s[54:55], 0, v[140:141]
	s_add_i32 m0, s53, 0xc000
	ds_read_b128 v[202:205], v160
	ds_read_b128 v[206:209], v160 offset:1024
	ds_read_b128 v[210:213], v160 offset:2048
	ds_read_b128 v[214:217], v160 offset:3072
	ds_read_b128 v[218:221], v160 offset:4096
	ds_read_b128 v[222:225], v160 offset:5120
	ds_read_b128 v[226:229], v160 offset:6144
	ds_read_b128 v[230:233], v160 offset:7168
	global_load_lds_dwordx4 v[198:199], off
	v_lshl_add_u64 v[198:199], s[54:55], 0, v[142:143]
	s_add_i32 m0, s53, 0xe000
	s_nop 0
	global_load_lds_dwordx4 v[198:199], off
	s_waitcnt vmcnt(8)
	s_waitcnt lgkmcnt(0)
	s_barrier
	s_setprio 1
	s_waitcnt lgkmcnt(0)
	v_mfma_f32_16x16x32_bf16 v[126:129], v[166:169], v[202:205], v[126:129]
	v_mfma_f32_16x16x32_bf16 v[126:129], v[170:173], v[206:209], v[126:129]
	v_mfma_f32_16x16x32_bf16 v[118:121], v[170:173], v[214:217], v[118:121]
	v_mfma_f32_16x16x32_bf16 v[118:121], v[166:169], v[210:213], v[118:121]
	v_mfma_f32_16x16x32_bf16 v[102:105], v[166:169], v[218:221], v[102:105]
	v_mfma_f32_16x16x32_bf16 v[102:105], v[170:173], v[222:225], v[102:105]
	v_mfma_f32_16x16x32_bf16 v[86:89], v[170:173], v[230:233], v[86:89]
	v_mfma_f32_16x16x32_bf16 v[86:89], v[166:169], v[226:229], v[86:89]
	v_mfma_f32_16x16x32_bf16 v[78:81], v[174:177], v[226:229], v[78:81]
	v_mfma_f32_16x16x32_bf16 v[78:81], v[178:181], v[230:233], v[78:81]
	v_mfma_f32_16x16x32_bf16 v[94:97], v[178:181], v[222:225], v[94:97]
	v_mfma_f32_16x16x32_bf16 v[94:97], v[174:177], v[218:221], v[94:97]
	v_mfma_f32_16x16x32_bf16 v[110:113], v[174:177], v[210:213], v[110:113]
	v_mfma_f32_16x16x32_bf16 v[110:113], v[178:181], v[214:217], v[110:113]
	v_mfma_f32_16x16x32_bf16 v[122:125], v[178:181], v[206:209], v[122:125]
	v_mfma_f32_16x16x32_bf16 v[122:125], v[174:177], v[202:205], v[122:125]
	v_mfma_f32_16x16x32_bf16 v[114:117], v[182:185], v[202:205], v[114:117]
	v_mfma_f32_16x16x32_bf16 v[114:117], v[186:189], v[206:209], v[114:117]
	v_mfma_f32_16x16x32_bf16 v[98:101], v[186:189], v[214:217], v[98:101]
	v_mfma_f32_16x16x32_bf16 v[98:101], v[182:185], v[210:213], v[98:101]
	v_mfma_f32_16x16x32_bf16 v[82:85], v[182:185], v[218:221], v[82:85]
	v_mfma_f32_16x16x32_bf16 v[82:85], v[186:189], v[222:225], v[82:85]
	v_mfma_f32_16x16x32_bf16 v[70:73], v[186:189], v[230:233], v[70:73]
	v_mfma_f32_16x16x32_bf16 v[70:73], v[182:185], v[226:229], v[70:73]
	v_mfma_f32_16x16x32_bf16 v[66:69], v[190:193], v[226:229], v[66:69]
	v_mfma_f32_16x16x32_bf16 v[66:69], v[194:197], v[230:233], v[66:69]
	v_mfma_f32_16x16x32_bf16 v[74:77], v[194:197], v[222:225], v[74:77]
	v_mfma_f32_16x16x32_bf16 v[74:77], v[190:193], v[218:221], v[74:77]
	v_mfma_f32_16x16x32_bf16 v[90:93], v[190:193], v[210:213], v[90:93]
	v_mfma_f32_16x16x32_bf16 v[90:93], v[194:197], v[214:217], v[90:93]
	v_mfma_f32_16x16x32_bf16 v[106:109], v[194:197], v[206:209], v[106:109]
	v_mfma_f32_16x16x32_bf16 v[106:109], v[190:193], v[202:205], v[106:109]
	s_setprio 0
	s_barrier
	s_add_i32 s36, s68, s38
	v_lshl_add_u64 v[198:199], s[56:57], 0, v[136:137]
	s_mov_b32 m0, s36
	ds_read_b128 v[202:205], v160 offset:16384
	ds_read_b128 v[206:209], v160 offset:17408
	ds_read_b128 v[210:213], v160 offset:18432
	ds_read_b128 v[214:217], v160 offset:19456
	ds_read_b128 v[218:221], v160 offset:20480
	ds_read_b128 v[222:225], v160 offset:21504
	ds_read_b128 v[226:229], v160 offset:22528
	ds_read_b128 v[230:233], v160 offset:23552
	global_load_lds_dwordx4 v[198:199], off
	s_add_i32 m0, s36, 0x2000
	s_add_u32 s80, s56, 0x100000
	v_lshl_add_u64 v[234:235], s[56:57], 0, v[132:133]
	s_addc_u32 s81, s57, 0
	s_add_i32 s36, s69, s38
	global_load_lds_dwordx4 v[234:235], off
	v_lshl_add_u64 v[236:237], s[80:81], 0, v[136:137]
	s_mov_b32 m0, s36
	v_lshl_add_u64 v[238:239], s[58:59], 0, v[134:135]
	global_load_lds_dwordx4 v[236:237], off
	v_lshl_add_u64 v[236:237], s[80:81], 0, v[132:133]
	s_add_i32 m0, s36, 0x2000
	s_nop 0
	global_load_lds_dwordx4 v[236:237], off
	v_lshl_add_u64 v[236:237], s[58:59], 0, v[138:139]
	s_mov_b32 m0, s53
	s_nop 0
	global_load_lds_dwordx4 v[236:237], off
	s_mov_b32 m0, s61
	s_nop 0
	global_load_lds_dwordx4 v[238:239], off
	s_waitcnt vmcnt(8)
	s_waitcnt lgkmcnt(0)
	s_barrier
	s_setprio 1
	s_waitcnt lgkmcnt(0)
	v_mfma_f32_16x16x32_bf16 v[62:65], v[166:169], v[202:205], v[62:65]
	v_mfma_f32_16x16x32_bf16 v[62:65], v[170:173], v[206:209], v[62:65]
	v_mfma_f32_16x16x32_bf16 v[54:57], v[170:173], v[214:217], v[54:57]
	v_mfma_f32_16x16x32_bf16 v[54:57], v[166:169], v[210:213], v[54:57]
	v_mfma_f32_16x16x32_bf16 v[38:41], v[166:169], v[218:221], v[38:41]
	v_mfma_f32_16x16x32_bf16 v[38:41], v[170:173], v[222:225], v[38:41]
	v_mfma_f32_16x16x32_bf16 v[22:25], v[170:173], v[230:233], v[22:25]
	v_mfma_f32_16x16x32_bf16 v[22:25], v[166:169], v[226:229], v[22:25]
	v_mfma_f32_16x16x32_bf16 v[14:17], v[174:177], v[226:229], v[14:17]
	v_mfma_f32_16x16x32_bf16 v[14:17], v[178:181], v[230:233], v[14:17]
	v_mfma_f32_16x16x32_bf16 v[30:33], v[178:181], v[222:225], v[30:33]
	v_mfma_f32_16x16x32_bf16 v[30:33], v[174:177], v[218:221], v[30:33]
	v_mfma_f32_16x16x32_bf16 v[46:49], v[174:177], v[210:213], v[46:49]
	v_mfma_f32_16x16x32_bf16 v[46:49], v[178:181], v[214:217], v[46:49]
	v_mfma_f32_16x16x32_bf16 v[58:61], v[178:181], v[206:209], v[58:61]
	v_mfma_f32_16x16x32_bf16 v[58:61], v[174:177], v[202:205], v[58:61]
	v_mfma_f32_16x16x32_bf16 v[50:53], v[182:185], v[202:205], v[50:53]
	v_mfma_f32_16x16x32_bf16 v[50:53], v[186:189], v[206:209], v[50:53]
	v_mfma_f32_16x16x32_bf16 v[34:37], v[186:189], v[214:217], v[34:37]
	v_mfma_f32_16x16x32_bf16 v[34:37], v[182:185], v[210:213], v[34:37]
	v_mfma_f32_16x16x32_bf16 v[18:21], v[182:185], v[218:221], v[18:21]
	v_mfma_f32_16x16x32_bf16 v[18:21], v[186:189], v[222:225], v[18:21]
	v_mfma_f32_16x16x32_bf16 v[6:9], v[186:189], v[230:233], v[6:9]
	v_mfma_f32_16x16x32_bf16 v[6:9], v[182:185], v[226:229], v[6:9]
	v_mfma_f32_16x16x32_bf16 v[2:5], v[190:193], v[226:229], v[2:5]
	v_mfma_f32_16x16x32_bf16 v[2:5], v[194:197], v[230:233], v[2:5]
	v_mfma_f32_16x16x32_bf16 v[10:13], v[194:197], v[222:225], v[10:13]
	v_mfma_f32_16x16x32_bf16 v[10:13], v[190:193], v[218:221], v[10:13]
	v_mfma_f32_16x16x32_bf16 v[26:29], v[190:193], v[210:213], v[26:29]
	v_mfma_f32_16x16x32_bf16 v[26:29], v[194:197], v[214:217], v[26:29]
	v_mfma_f32_16x16x32_bf16 v[42:45], v[194:197], v[206:209], v[42:45]
	v_mfma_f32_16x16x32_bf16 v[42:45], v[190:193], v[202:205], v[42:45]
	s_setprio 0
	s_barrier
	s_add_i32 s36, 0, 0x18000
	v_add_u32_e32 v161, s36, v156
	s_add_i32 s37, 0, 0x1c000
	ds_read_b128 v[166:169], v161
	ds_read_b128 v[170:173], v161 offset:1024
	ds_read_b128 v[174:177], v161 offset:2048
	ds_read_b128 v[178:181], v161 offset:3072
	v_add_u32_e32 v161, s37, v156
	ds_read_b128 v[182:185], v161
	ds_read_b128 v[186:189], v161 offset:1024
	ds_read_b128 v[190:193], v161 offset:2048
	ds_read_b128 v[194:197], v161 offset:3072
	s_add_u32 s58, s58, 0x100000
	s_addc_u32 s59, s59, 0
	s_mov_b32 m0, s62
	v_lshl_add_u64 v[240:241], s[58:59], 0, v[138:139]
	ds_read_b128 v[202:205], v160 offset:32768
	ds_read_b128 v[206:209], v160 offset:33792
	ds_read_b128 v[210:213], v160 offset:34816
	ds_read_b128 v[214:217], v160 offset:35840
	ds_read_b128 v[218:221], v160 offset:36864
	ds_read_b128 v[222:225], v160 offset:37888
	ds_read_b128 v[226:229], v160 offset:38912
	ds_read_b128 v[230:233], v160 offset:39936
	global_load_lds_dwordx4 v[240:241], off
	v_lshl_add_u64 v[240:241], s[58:59], 0, v[134:135]
	s_mov_b32 m0, s63
	s_nop 0
	global_load_lds_dwordx4 v[240:241], off
	s_waitcnt vmcnt(8)
	s_waitcnt lgkmcnt(0)
	s_barrier
	s_setprio 1
	s_waitcnt lgkmcnt(0)
	v_mfma_f32_16x16x32_bf16 v[126:129], v[166:169], v[202:205], v[126:129]
	v_mfma_f32_16x16x32_bf16 v[126:129], v[170:173], v[206:209], v[126:129]
	v_mfma_f32_16x16x32_bf16 v[118:121], v[170:173], v[214:217], v[118:121]
	v_mfma_f32_16x16x32_bf16 v[118:121], v[166:169], v[210:213], v[118:121]
	v_mfma_f32_16x16x32_bf16 v[102:105], v[166:169], v[218:221], v[102:105]
	v_mfma_f32_16x16x32_bf16 v[102:105], v[170:173], v[222:225], v[102:105]
	v_mfma_f32_16x16x32_bf16 v[86:89], v[170:173], v[230:233], v[86:89]
	v_mfma_f32_16x16x32_bf16 v[86:89], v[166:169], v[226:229], v[86:89]
	v_mfma_f32_16x16x32_bf16 v[78:81], v[174:177], v[226:229], v[78:81]
	v_mfma_f32_16x16x32_bf16 v[78:81], v[178:181], v[230:233], v[78:81]
	v_mfma_f32_16x16x32_bf16 v[94:97], v[178:181], v[222:225], v[94:97]
	v_mfma_f32_16x16x32_bf16 v[94:97], v[174:177], v[218:221], v[94:97]
	v_mfma_f32_16x16x32_bf16 v[110:113], v[174:177], v[210:213], v[110:113]
	v_mfma_f32_16x16x32_bf16 v[110:113], v[178:181], v[214:217], v[110:113]
	v_mfma_f32_16x16x32_bf16 v[122:125], v[178:181], v[206:209], v[122:125]
	v_mfma_f32_16x16x32_bf16 v[122:125], v[174:177], v[202:205], v[122:125]
	v_mfma_f32_16x16x32_bf16 v[114:117], v[182:185], v[202:205], v[114:117]
	v_mfma_f32_16x16x32_bf16 v[114:117], v[186:189], v[206:209], v[114:117]
	v_mfma_f32_16x16x32_bf16 v[98:101], v[186:189], v[214:217], v[98:101]
	v_mfma_f32_16x16x32_bf16 v[98:101], v[182:185], v[210:213], v[98:101]
	v_mfma_f32_16x16x32_bf16 v[82:85], v[182:185], v[218:221], v[82:85]
	v_mfma_f32_16x16x32_bf16 v[82:85], v[186:189], v[222:225], v[82:85]
	v_mfma_f32_16x16x32_bf16 v[70:73], v[186:189], v[230:233], v[70:73]
	v_mfma_f32_16x16x32_bf16 v[70:73], v[182:185], v[226:229], v[70:73]
	v_mfma_f32_16x16x32_bf16 v[66:69], v[190:193], v[226:229], v[66:69]
	v_mfma_f32_16x16x32_bf16 v[66:69], v[194:197], v[230:233], v[66:69]
	v_mfma_f32_16x16x32_bf16 v[74:77], v[194:197], v[222:225], v[74:77]
	v_mfma_f32_16x16x32_bf16 v[74:77], v[190:193], v[218:221], v[74:77]
	v_mfma_f32_16x16x32_bf16 v[90:93], v[190:193], v[210:213], v[90:93]
	v_mfma_f32_16x16x32_bf16 v[90:93], v[194:197], v[214:217], v[90:93]
	v_mfma_f32_16x16x32_bf16 v[106:109], v[194:197], v[206:209], v[106:109]
	v_mfma_f32_16x16x32_bf16 v[106:109], v[190:193], v[202:205], v[106:109]
	s_setprio 0
	s_barrier
	s_add_i32 s36, s36, s38
	v_lshl_add_u64 v[198:199], v[198:199], 0, s[14:15]
	s_mov_b32 m0, s36
	ds_read_b128 v[202:205], v160 offset:49152
	ds_read_b128 v[206:209], v160 offset:50176
	ds_read_b128 v[210:213], v160 offset:51200
	ds_read_b128 v[214:217], v160 offset:52224
	ds_read_b128 v[218:221], v160 offset:53248
	ds_read_b128 v[222:225], v160 offset:54272
	ds_read_b128 v[226:229], v160 offset:55296
	ds_read_b128 v[230:233], v160 offset:56320
	global_load_lds_dwordx4 v[198:199], off
	s_add_i32 m0, s36, 0x2000
	s_add_u32 s56, s56, 0x100080
	v_lshl_add_u64 v[198:199], v[234:235], 0, s[14:15]
	s_addc_u32 s57, s57, 0
	s_add_i32 s36, s37, s38
	global_load_lds_dwordx4 v[198:199], off
	v_lshl_add_u64 v[198:199], s[56:57], 0, v[136:137]
	s_mov_b32 m0, s36
	s_nop 0
	global_load_lds_dwordx4 v[198:199], off
	v_lshl_add_u64 v[198:199], s[56:57], 0, v[132:133]
	s_add_i32 m0, s36, 0x2000
	s_nop 0
	global_load_lds_dwordx4 v[198:199], off
	v_lshl_add_u64 v[198:199], v[236:237], 0, s[14:15]
	s_mov_b32 m0, s65
	s_nop 0
	global_load_lds_dwordx4 v[198:199], off
	v_lshl_add_u64 v[198:199], v[238:239], 0, s[14:15]
	s_mov_b32 m0, s66
	s_nop 0
	global_load_lds_dwordx4 v[198:199], off
	s_waitcnt vmcnt(8)
	s_waitcnt lgkmcnt(0)
	s_barrier
	s_setprio 1
	s_waitcnt lgkmcnt(0)
	v_mfma_f32_16x16x32_bf16 v[62:65], v[166:169], v[202:205], v[62:65]
	v_mfma_f32_16x16x32_bf16 v[62:65], v[170:173], v[206:209], v[62:65]
	v_mfma_f32_16x16x32_bf16 v[54:57], v[170:173], v[214:217], v[54:57]
	v_mfma_f32_16x16x32_bf16 v[54:57], v[166:169], v[210:213], v[54:57]
	v_mfma_f32_16x16x32_bf16 v[38:41], v[166:169], v[218:221], v[38:41]
	v_mfma_f32_16x16x32_bf16 v[38:41], v[170:173], v[222:225], v[38:41]
	v_mfma_f32_16x16x32_bf16 v[22:25], v[170:173], v[230:233], v[22:25]
	v_mfma_f32_16x16x32_bf16 v[22:25], v[166:169], v[226:229], v[22:25]
	v_mfma_f32_16x16x32_bf16 v[14:17], v[174:177], v[226:229], v[14:17]
	v_mfma_f32_16x16x32_bf16 v[14:17], v[178:181], v[230:233], v[14:17]
	v_mfma_f32_16x16x32_bf16 v[30:33], v[178:181], v[222:225], v[30:33]
	v_mfma_f32_16x16x32_bf16 v[30:33], v[174:177], v[218:221], v[30:33]
	v_mfma_f32_16x16x32_bf16 v[46:49], v[174:177], v[210:213], v[46:49]
	v_mfma_f32_16x16x32_bf16 v[46:49], v[178:181], v[214:217], v[46:49]
	v_mfma_f32_16x16x32_bf16 v[58:61], v[178:181], v[206:209], v[58:61]
	v_mfma_f32_16x16x32_bf16 v[58:61], v[174:177], v[202:205], v[58:61]
	v_mfma_f32_16x16x32_bf16 v[50:53], v[182:185], v[202:205], v[50:53]
	v_mfma_f32_16x16x32_bf16 v[50:53], v[186:189], v[206:209], v[50:53]
	v_mfma_f32_16x16x32_bf16 v[34:37], v[186:189], v[214:217], v[34:37]
	v_mfma_f32_16x16x32_bf16 v[34:37], v[182:185], v[210:213], v[34:37]
	v_mfma_f32_16x16x32_bf16 v[18:21], v[182:185], v[218:221], v[18:21]
	v_mfma_f32_16x16x32_bf16 v[18:21], v[186:189], v[222:225], v[18:21]
	v_mfma_f32_16x16x32_bf16 v[6:9], v[186:189], v[230:233], v[6:9]
	v_mfma_f32_16x16x32_bf16 v[6:9], v[182:185], v[226:229], v[6:9]
	v_mfma_f32_16x16x32_bf16 v[2:5], v[190:193], v[226:229], v[2:5]
	v_mfma_f32_16x16x32_bf16 v[2:5], v[194:197], v[230:233], v[2:5]
	v_mfma_f32_16x16x32_bf16 v[10:13], v[194:197], v[222:225], v[10:13]
	v_mfma_f32_16x16x32_bf16 v[10:13], v[190:193], v[218:221], v[10:13]
	v_mfma_f32_16x16x32_bf16 v[26:29], v[190:193], v[210:213], v[26:29]
	v_mfma_f32_16x16x32_bf16 v[26:29], v[194:197], v[214:217], v[26:29]
	v_mfma_f32_16x16x32_bf16 v[42:45], v[194:197], v[206:209], v[42:45]
	v_mfma_f32_16x16x32_bf16 v[42:45], v[190:193], v[202:205], v[42:45]
	s_setprio 0
	s_barrier
	s_add_i32 s78, s78, 2
	s_add_u32 s54, s54, 0x100
	s_addc_u32 s55, s55, 0
	s_add_u32 s76, s76, 0x100
	s_addc_u32 s77, s77, 0
	s_cmp_gt_u32 s78, 61
	s_cbranch_scc0 .LBB0_1631
	s_and_b64 vcc, exec, s[16:17]
	s_cbranch_vccz .LBB0_1634
	s_barrier

.LBB0_1649:
	s_add_u32 s36, s56, s44
	s_addc_u32 s37, s57, 0
	s_add_u32 s64, s36, 0x100
	s_addc_u32 s65, s37, 0
	s_and_b64 s[62:63], s[60:61], exec
	s_cselect_b32 s65, s21, s65
	s_cselect_b32 s64, s87, s64
	s_add_u32 s44, s54, s44
	s_addc_u32 s62, s55, 0
	s_add_u32 s44, s44, 0x100
	s_addc_u32 s62, s62, 0
	s_and_b64 s[60:61], s[60:61], exec
	s_cselect_b32 s67, s19, s62
	s_cselect_b32 s66, s89, s44
	s_add_u32 s70, s36, 0x10080
	s_addc_u32 s71, s37, 0
	s_add_i32 vcc_lo, s84, s39
	ds_read_b128 v[158:161], v147
	ds_read_b128 v[166:169], v147 offset:1024
	ds_read_b128 v[170:173], v147 offset:2048
	ds_read_b128 v[174:177], v147 offset:3072
	ds_read_b128 v[178:181], v155
	ds_read_b128 v[182:185], v155 offset:1024
	ds_read_b128 v[186:189], v155 offset:2048
	ds_read_b128 v[190:193], v155 offset:3072
	s_add_i32 m0, s53, 0xc000
	s_add_i32 vcc_hi, s53, 0xe000
	s_add_i32 s95, vcc_lo, 0x2000
	s_add_u32 s68, s66, 0x10000
	s_addc_u32 s69, s67, 0
	s_add_i32 s97, s85, s39
	s_add_i32 s96, s97, 0x2000
	s_add_i32 s94, 0, 0x18000
	s_add_i32 s93, 0, 0x1c000
	s_add_u32 s62, s64, 0x10000
	s_addc_u32 s63, s65, 0
	s_add_i32 s92, s94, s39
	s_add_i32 s90, s92, 0x2000
	s_add_u32 s60, s66, 0x10080
	s_addc_u32 s61, s67, 0
	s_add_i32 s91, s93, s39
	s_add_i32 s44, s91, 0x2000
	v_lshl_add_u64 v[198:199], s[70:71], 0, v[138:139]
	ds_read_b128 v[194:197], v156
	ds_read_b128 v[202:205], v156 offset:1024
	ds_read_b128 v[206:209], v156 offset:2048
	ds_read_b128 v[210:213], v156 offset:3072
	ds_read_b128 v[214:217], v156 offset:4096
	ds_read_b128 v[218:221], v156 offset:5120
	ds_read_b128 v[222:225], v156 offset:6144
	ds_read_b128 v[226:229], v156 offset:7168
	global_load_lds_dwordx4 v[198:199], off
	v_lshl_add_u64 v[198:199], s[70:71], 0, v[134:135]
	s_mov_b32 m0, vcc_hi
	s_nop 0
	global_load_lds_dwordx4 v[198:199], off
	s_waitcnt vmcnt(8)
	s_waitcnt lgkmcnt(0)
	s_barrier
	s_setprio 1
	s_waitcnt lgkmcnt(0)
	v_mfma_f32_16x16x32_bf16 v[126:129], v[158:161], v[194:197], v[126:129]
	v_mfma_f32_16x16x32_bf16 v[126:129], v[166:169], v[202:205], v[126:129]
	v_mfma_f32_16x16x32_bf16 v[118:121], v[166:169], v[210:213], v[118:121]
	v_mfma_f32_16x16x32_bf16 v[118:121], v[158:161], v[206:209], v[118:121]
	v_mfma_f32_16x16x32_bf16 v[102:105], v[158:161], v[214:217], v[102:105]
	v_mfma_f32_16x16x32_bf16 v[102:105], v[166:169], v[218:221], v[102:105]
	v_mfma_f32_16x16x32_bf16 v[86:89], v[166:169], v[226:229], v[86:89]
	v_mfma_f32_16x16x32_bf16 v[86:89], v[158:161], v[222:225], v[86:89]
	v_mfma_f32_16x16x32_bf16 v[78:81], v[170:173], v[222:225], v[78:81]
	v_mfma_f32_16x16x32_bf16 v[78:81], v[174:177], v[226:229], v[78:81]
	v_mfma_f32_16x16x32_bf16 v[94:97], v[174:177], v[218:221], v[94:97]
	v_mfma_f32_16x16x32_bf16 v[94:97], v[170:173], v[214:217], v[94:97]
	v_mfma_f32_16x16x32_bf16 v[110:113], v[170:173], v[206:209], v[110:113]
	v_mfma_f32_16x16x32_bf16 v[110:113], v[174:177], v[210:213], v[110:113]
	v_mfma_f32_16x16x32_bf16 v[122:125], v[174:177], v[202:205], v[122:125]
	v_mfma_f32_16x16x32_bf16 v[122:125], v[170:173], v[194:197], v[122:125]
	v_mfma_f32_16x16x32_bf16 v[114:117], v[178:181], v[194:197], v[114:117]
	v_mfma_f32_16x16x32_bf16 v[114:117], v[182:185], v[202:205], v[114:117]
	v_mfma_f32_16x16x32_bf16 v[98:101], v[182:185], v[210:213], v[98:101]
	v_mfma_f32_16x16x32_bf16 v[98:101], v[178:181], v[206:209], v[98:101]
	v_mfma_f32_16x16x32_bf16 v[82:85], v[178:181], v[214:217], v[82:85]
	v_mfma_f32_16x16x32_bf16 v[82:85], v[182:185], v[218:221], v[82:85]
	v_mfma_f32_16x16x32_bf16 v[70:73], v[182:185], v[226:229], v[70:73]
	v_mfma_f32_16x16x32_bf16 v[70:73], v[178:181], v[222:225], v[70:73]
	v_mfma_f32_16x16x32_bf16 v[66:69], v[186:189], v[222:225], v[66:69]
	v_mfma_f32_16x16x32_bf16 v[66:69], v[190:193], v[226:229], v[66:69]
	v_mfma_f32_16x16x32_bf16 v[74:77], v[190:193], v[218:221], v[74:77]
	v_mfma_f32_16x16x32_bf16 v[74:77], v[186:189], v[214:217], v[74:77]
	v_mfma_f32_16x16x32_bf16 v[90:93], v[186:189], v[206:209], v[90:93]
	v_mfma_f32_16x16x32_bf16 v[90:93], v[190:193], v[210:213], v[90:93]
	v_mfma_f32_16x16x32_bf16 v[106:109], v[190:193], v[202:205], v[106:109]
	v_mfma_f32_16x16x32_bf16 v[106:109], v[186:189], v[194:197], v[106:109]
	s_setprio 0
	s_barrier
	s_mov_b32 m0, vcc_lo
	v_lshl_add_u64 v[198:199], s[66:67], 0, v[136:137]
	ds_read_b128 v[194:197], v156 offset:16384
	ds_read_b128 v[202:205], v156 offset:17408
	ds_read_b128 v[206:209], v156 offset:18432
	ds_read_b128 v[210:213], v156 offset:19456
	ds_read_b128 v[214:217], v156 offset:20480
	ds_read_b128 v[218:221], v156 offset:21504
	ds_read_b128 v[222:225], v156 offset:22528
	ds_read_b128 v[226:229], v156 offset:23552
	global_load_lds_dwordx4 v[198:199], off
	v_lshl_add_u64 v[230:231], s[66:67], 0, v[132:133]
	s_mov_b32 m0, s95
	v_lshl_add_u64 v[232:233], s[68:69], 0, v[136:137]
	global_load_lds_dwordx4 v[230:231], off
	s_mov_b32 m0, s97
	v_lshl_add_u64 v[234:235], s[64:65], 0, v[134:135]
	global_load_lds_dwordx4 v[232:233], off
	v_lshl_add_u64 v[232:233], s[68:69], 0, v[132:133]
	s_mov_b32 m0, s96
	s_nop 0
	global_load_lds_dwordx4 v[232:233], off
	v_lshl_add_u64 v[232:233], s[64:65], 0, v[138:139]
	s_mov_b32 m0, s53
	s_nop 0
	global_load_lds_dwordx4 v[232:233], off
	s_mov_b32 m0, s75
	s_nop 0
	global_load_lds_dwordx4 v[234:235], off
	s_waitcnt vmcnt(8)
	s_waitcnt lgkmcnt(0)
	s_barrier
	s_setprio 1
	s_waitcnt lgkmcnt(0)
	v_mfma_f32_16x16x32_bf16 v[62:65], v[158:161], v[194:197], v[62:65]
	v_mfma_f32_16x16x32_bf16 v[62:65], v[166:169], v[202:205], v[62:65]
	v_mfma_f32_16x16x32_bf16 v[54:57], v[166:169], v[210:213], v[54:57]
	v_mfma_f32_16x16x32_bf16 v[54:57], v[158:161], v[206:209], v[54:57]
	v_mfma_f32_16x16x32_bf16 v[38:41], v[158:161], v[214:217], v[38:41]
	v_mfma_f32_16x16x32_bf16 v[38:41], v[166:169], v[218:221], v[38:41]
	v_mfma_f32_16x16x32_bf16 v[22:25], v[166:169], v[226:229], v[22:25]
	v_mfma_f32_16x16x32_bf16 v[22:25], v[158:161], v[222:225], v[22:25]
	v_mfma_f32_16x16x32_bf16 v[14:17], v[170:173], v[222:225], v[14:17]
	v_mfma_f32_16x16x32_bf16 v[14:17], v[174:177], v[226:229], v[14:17]
	v_mfma_f32_16x16x32_bf16 v[30:33], v[174:177], v[218:221], v[30:33]
	v_mfma_f32_16x16x32_bf16 v[30:33], v[170:173], v[214:217], v[30:33]
	v_mfma_f32_16x16x32_bf16 v[46:49], v[170:173], v[206:209], v[46:49]
	v_mfma_f32_16x16x32_bf16 v[46:49], v[174:177], v[210:213], v[46:49]
	v_mfma_f32_16x16x32_bf16 v[58:61], v[174:177], v[202:205], v[58:61]
	v_mfma_f32_16x16x32_bf16 v[58:61], v[170:173], v[194:197], v[58:61]
	v_mfma_f32_16x16x32_bf16 v[50:53], v[178:181], v[194:197], v[50:53]
	v_mfma_f32_16x16x32_bf16 v[50:53], v[182:185], v[202:205], v[50:53]
	v_mfma_f32_16x16x32_bf16 v[34:37], v[182:185], v[210:213], v[34:37]
	v_mfma_f32_16x16x32_bf16 v[34:37], v[178:181], v[206:209], v[34:37]
	v_mfma_f32_16x16x32_bf16 v[18:21], v[178:181], v[214:217], v[18:21]
	v_mfma_f32_16x16x32_bf16 v[18:21], v[182:185], v[218:221], v[18:21]
	v_mfma_f32_16x16x32_bf16 v[6:9], v[182:185], v[226:229], v[6:9]
	v_mfma_f32_16x16x32_bf16 v[6:9], v[178:181], v[222:225], v[6:9]
	v_mfma_f32_16x16x32_bf16 v[2:5], v[186:189], v[222:225], v[2:5]
	v_mfma_f32_16x16x32_bf16 v[2:5], v[190:193], v[226:229], v[2:5]
	v_mfma_f32_16x16x32_bf16 v[10:13], v[190:193], v[218:221], v[10:13]
	v_mfma_f32_16x16x32_bf16 v[10:13], v[186:189], v[214:217], v[10:13]
	v_mfma_f32_16x16x32_bf16 v[26:29], v[186:189], v[206:209], v[26:29]
	v_mfma_f32_16x16x32_bf16 v[26:29], v[190:193], v[210:213], v[26:29]
	v_mfma_f32_16x16x32_bf16 v[42:45], v[190:193], v[202:205], v[42:45]
	v_mfma_f32_16x16x32_bf16 v[42:45], v[186:189], v[194:197], v[42:45]
	s_setprio 0
	s_barrier
	v_add_u32_e32 v157, s94, v145
	ds_read_b128 v[158:161], v157
	ds_read_b128 v[166:169], v157 offset:1024
	ds_read_b128 v[170:173], v157 offset:2048
	ds_read_b128 v[174:177], v157 offset:3072
	v_add_u32_e32 v157, s93, v145
	ds_read_b128 v[178:181], v157
	ds_read_b128 v[182:185], v157 offset:1024
	ds_read_b128 v[186:189], v157 offset:2048
	ds_read_b128 v[190:193], v157 offset:3072
	s_mov_b32 m0, s76
	v_lshl_add_u64 v[236:237], s[62:63], 0, v[138:139]
	ds_read_b128 v[194:197], v156 offset:32768
	ds_read_b128 v[202:205], v156 offset:33792
	ds_read_b128 v[206:209], v156 offset:34816
	ds_read_b128 v[210:213], v156 offset:35840
	ds_read_b128 v[214:217], v156 offset:36864
	ds_read_b128 v[218:221], v156 offset:37888
	ds_read_b128 v[222:225], v156 offset:38912
	ds_read_b128 v[226:229], v156 offset:39936
	global_load_lds_dwordx4 v[236:237], off
	v_lshl_add_u64 v[236:237], s[62:63], 0, v[134:135]
	s_mov_b32 m0, s77
	s_nop 0
	global_load_lds_dwordx4 v[236:237], off
	s_waitcnt vmcnt(8)
	s_waitcnt lgkmcnt(0)
	s_barrier
	s_setprio 1
	s_waitcnt lgkmcnt(0)
	v_mfma_f32_16x16x32_bf16 v[126:129], v[158:161], v[194:197], v[126:129]
	v_mfma_f32_16x16x32_bf16 v[126:129], v[166:169], v[202:205], v[126:129]
	v_mfma_f32_16x16x32_bf16 v[118:121], v[166:169], v[210:213], v[118:121]
	v_mfma_f32_16x16x32_bf16 v[118:121], v[158:161], v[206:209], v[118:121]
	v_mfma_f32_16x16x32_bf16 v[102:105], v[158:161], v[214:217], v[102:105]
	v_mfma_f32_16x16x32_bf16 v[102:105], v[166:169], v[218:221], v[102:105]
	v_mfma_f32_16x16x32_bf16 v[86:89], v[166:169], v[226:229], v[86:89]
	v_mfma_f32_16x16x32_bf16 v[86:89], v[158:161], v[222:225], v[86:89]
	v_mfma_f32_16x16x32_bf16 v[78:81], v[170:173], v[222:225], v[78:81]
	v_mfma_f32_16x16x32_bf16 v[78:81], v[174:177], v[226:229], v[78:81]
	v_mfma_f32_16x16x32_bf16 v[94:97], v[174:177], v[218:221], v[94:97]
	v_mfma_f32_16x16x32_bf16 v[94:97], v[170:173], v[214:217], v[94:97]
	v_mfma_f32_16x16x32_bf16 v[110:113], v[170:173], v[206:209], v[110:113]
	v_mfma_f32_16x16x32_bf16 v[110:113], v[174:177], v[210:213], v[110:113]
	v_mfma_f32_16x16x32_bf16 v[122:125], v[174:177], v[202:205], v[122:125]
	v_mfma_f32_16x16x32_bf16 v[122:125], v[170:173], v[194:197], v[122:125]
	v_mfma_f32_16x16x32_bf16 v[114:117], v[178:181], v[194:197], v[114:117]
	v_mfma_f32_16x16x32_bf16 v[114:117], v[182:185], v[202:205], v[114:117]
	v_mfma_f32_16x16x32_bf16 v[98:101], v[182:185], v[210:213], v[98:101]
	v_mfma_f32_16x16x32_bf16 v[98:101], v[178:181], v[206:209], v[98:101]
	v_mfma_f32_16x16x32_bf16 v[82:85], v[178:181], v[214:217], v[82:85]
	v_mfma_f32_16x16x32_bf16 v[82:85], v[182:185], v[218:221], v[82:85]
	v_mfma_f32_16x16x32_bf16 v[70:73], v[182:185], v[226:229], v[70:73]
	v_mfma_f32_16x16x32_bf16 v[70:73], v[178:181], v[222:225], v[70:73]
	v_mfma_f32_16x16x32_bf16 v[66:69], v[186:189], v[222:225], v[66:69]
	v_mfma_f32_16x16x32_bf16 v[66:69], v[190:193], v[226:229], v[66:69]
	v_mfma_f32_16x16x32_bf16 v[74:77], v[190:193], v[218:221], v[74:77]
	v_mfma_f32_16x16x32_bf16 v[74:77], v[186:189], v[214:217], v[74:77]
	v_mfma_f32_16x16x32_bf16 v[90:93], v[186:189], v[206:209], v[90:93]
	v_mfma_f32_16x16x32_bf16 v[90:93], v[190:193], v[210:213], v[90:93]
	v_mfma_f32_16x16x32_bf16 v[106:109], v[190:193], v[202:205], v[106:109]
	v_mfma_f32_16x16x32_bf16 v[106:109], v[186:189], v[194:197], v[106:109]
	s_setprio 0
	s_barrier
	s_mov_b32 m0, s92
	v_lshl_add_u64 v[198:199], v[198:199], 0, s[14:15]
	ds_read_b128 v[194:197], v156 offset:49152
	ds_read_b128 v[202:205], v156 offset:50176
	ds_read_b128 v[206:209], v156 offset:51200
	ds_read_b128 v[210:213], v156 offset:52224
	ds_read_b128 v[214:217], v156 offset:53248
	ds_read_b128 v[218:221], v156 offset:54272
	ds_read_b128 v[222:225], v156 offset:55296
	ds_read_b128 v[226:229], v156 offset:56320
	global_load_lds_dwordx4 v[198:199], off
	v_lshl_add_u64 v[198:199], v[230:231], 0, s[14:15]
	s_mov_b32 m0, s90
	s_nop 0
	global_load_lds_dwordx4 v[198:199], off
	v_lshl_add_u64 v[198:199], s[60:61], 0, v[136:137]
	s_mov_b32 m0, s91
	s_nop 0
	global_load_lds_dwordx4 v[198:199], off
	v_lshl_add_u64 v[198:199], s[60:61], 0, v[132:133]
	s_mov_b32 m0, s44
	s_nop 0
	global_load_lds_dwordx4 v[198:199], off
	v_lshl_add_u64 v[198:199], v[232:233], 0, s[14:15]
	s_mov_b32 m0, s80
	s_nop 0
	global_load_lds_dwordx4 v[198:199], off
	v_lshl_add_u64 v[198:199], v[234:235], 0, s[14:15]
	s_mov_b32 m0, s81
	s_nop 0
	global_load_lds_dwordx4 v[198:199], off
	s_waitcnt vmcnt(8)
	s_waitcnt lgkmcnt(0)
	s_barrier
	s_setprio 1
	s_waitcnt lgkmcnt(0)
	v_mfma_f32_16x16x32_bf16 v[62:65], v[158:161], v[194:197], v[62:65]
	v_mfma_f32_16x16x32_bf16 v[62:65], v[166:169], v[202:205], v[62:65]
	v_mfma_f32_16x16x32_bf16 v[54:57], v[166:169], v[210:213], v[54:57]
	v_mfma_f32_16x16x32_bf16 v[54:57], v[158:161], v[206:209], v[54:57]
	v_mfma_f32_16x16x32_bf16 v[38:41], v[158:161], v[214:217], v[38:41]
	v_mfma_f32_16x16x32_bf16 v[38:41], v[166:169], v[218:221], v[38:41]
	v_mfma_f32_16x16x32_bf16 v[22:25], v[166:169], v[226:229], v[22:25]
	v_mfma_f32_16x16x32_bf16 v[22:25], v[158:161], v[222:225], v[22:25]
	v_mfma_f32_16x16x32_bf16 v[14:17], v[170:173], v[222:225], v[14:17]
	v_mfma_f32_16x16x32_bf16 v[14:17], v[174:177], v[226:229], v[14:17]
	v_mfma_f32_16x16x32_bf16 v[30:33], v[174:177], v[218:221], v[30:33]
	v_mfma_f32_16x16x32_bf16 v[30:33], v[170:173], v[214:217], v[30:33]
	v_mfma_f32_16x16x32_bf16 v[46:49], v[170:173], v[206:209], v[46:49]
	v_mfma_f32_16x16x32_bf16 v[46:49], v[174:177], v[210:213], v[46:49]
	v_mfma_f32_16x16x32_bf16 v[58:61], v[174:177], v[202:205], v[58:61]
	v_mfma_f32_16x16x32_bf16 v[58:61], v[170:173], v[194:197], v[58:61]
	v_mfma_f32_16x16x32_bf16 v[50:53], v[178:181], v[194:197], v[50:53]
	v_mfma_f32_16x16x32_bf16 v[50:53], v[182:185], v[202:205], v[50:53]
	v_mfma_f32_16x16x32_bf16 v[34:37], v[182:185], v[210:213], v[34:37]
	v_mfma_f32_16x16x32_bf16 v[34:37], v[178:181], v[206:209], v[34:37]
	v_mfma_f32_16x16x32_bf16 v[18:21], v[178:181], v[214:217], v[18:21]
	v_mfma_f32_16x16x32_bf16 v[18:21], v[182:185], v[218:221], v[18:21]
	v_mfma_f32_16x16x32_bf16 v[6:9], v[182:185], v[226:229], v[6:9]
	v_mfma_f32_16x16x32_bf16 v[6:9], v[178:181], v[222:225], v[6:9]
	v_mfma_f32_16x16x32_bf16 v[2:5], v[186:189], v[222:225], v[2:5]
	v_mfma_f32_16x16x32_bf16 v[2:5], v[190:193], v[226:229], v[2:5]
	v_mfma_f32_16x16x32_bf16 v[10:13], v[190:193], v[218:221], v[10:13]
	v_mfma_f32_16x16x32_bf16 v[10:13], v[186:189], v[214:217], v[10:13]
	v_mfma_f32_16x16x32_bf16 v[26:29], v[186:189], v[206:209], v[26:29]
	v_mfma_f32_16x16x32_bf16 v[26:29], v[190:193], v[210:213], v[26:29]
	v_mfma_f32_16x16x32_bf16 v[42:45], v[190:193], v[202:205], v[42:45]
	v_mfma_f32_16x16x32_bf16 v[42:45], v[186:189], v[194:197], v[42:45]
	s_setprio 0
	s_barrier
	s_movk_i32 s44, 0x100
	s_andn2_b64 vcc, exec, s[58:59]
	s_mov_b64 s[60:61], -1
	s_mov_b64 s[58:59], 0
	s_cbranch_vccz .LBB0_1649
	s_and_b64 vcc, exec, s[16:17]
	s_cbranch_vccz .LBB0_1652
	s_barrier

.LBB0_1667:
	s_add_u32 s36, s56, s44
	s_addc_u32 s37, s57, 0
	s_add_u32 s64, s36, 0x100
	s_addc_u32 s65, s37, 0
	s_and_b64 s[62:63], s[60:61], exec
	s_cselect_b32 s65, s21, s65
	s_cselect_b32 s64, s86, s64
	s_add_u32 s44, s54, s44
	s_addc_u32 s62, s55, 0
	s_add_u32 s44, s44, 0x100
	s_addc_u32 s62, s62, 0
	s_and_b64 s[60:61], s[60:61], exec
	s_cselect_b32 s67, s19, s62
	s_cselect_b32 s66, s87, s44
	s_add_u32 s70, s36, 0x10080
	s_addc_u32 s71, s37, 0
	s_add_i32 s97, s82, s38
	ds_read_b128 v[150:153], v146
	ds_read_b128 v[154:157], v146 offset:1024
	ds_read_b128 v[158:161], v146 offset:2048
	ds_read_b128 v[166:169], v146 offset:3072
	ds_read_b128 v[170:173], v147
	ds_read_b128 v[174:177], v147 offset:1024
	ds_read_b128 v[178:181], v147 offset:2048
	ds_read_b128 v[182:185], v147 offset:3072
	s_add_i32 m0, s53, 0xc000
	s_add_i32 vcc_lo, s53, 0xe000
	s_add_i32 s94, s97, 0x2000
	s_add_u32 s68, s66, 0x10000
	s_addc_u32 s69, s67, 0
	s_add_i32 s96, s83, s38
	s_add_i32 s95, s96, 0x2000
	s_add_i32 s93, 0, 0x18000
	s_add_i32 s92, 0, 0x1c000
	s_add_u32 s62, s64, 0x10000
	s_addc_u32 s63, s65, 0
	s_add_i32 s91, s93, s38
	s_add_i32 s89, s91, 0x2000
	s_add_u32 s60, s66, 0x10080
	s_addc_u32 s61, s67, 0
	s_add_i32 s90, s92, s38
	s_add_i32 s44, s90, 0x2000
	v_lshl_add_u64 v[198:199], s[70:71], 0, v[138:139]
	ds_read_b128 v[186:189], v148
	ds_read_b128 v[190:193], v148 offset:1024
	ds_read_b128 v[194:197], v148 offset:2048
	ds_read_b128 v[202:205], v148 offset:3072
	ds_read_b128 v[206:209], v148 offset:4096
	ds_read_b128 v[210:213], v148 offset:5120
	ds_read_b128 v[214:217], v148 offset:6144
	ds_read_b128 v[218:221], v148 offset:7168
	global_load_lds_dwordx4 v[198:199], off
	v_lshl_add_u64 v[198:199], s[70:71], 0, v[134:135]
	s_mov_b32 m0, vcc_lo
	s_nop 0
	global_load_lds_dwordx4 v[198:199], off
	s_waitcnt vmcnt(8)
	s_waitcnt lgkmcnt(0)
	s_barrier
	s_setprio 1
	s_waitcnt lgkmcnt(0)
	v_mfma_f32_16x16x32_bf16 v[126:129], v[150:153], v[186:189], v[126:129]
	v_mfma_f32_16x16x32_bf16 v[126:129], v[154:157], v[190:193], v[126:129]
	v_mfma_f32_16x16x32_bf16 v[118:121], v[154:157], v[202:205], v[118:121]
	v_mfma_f32_16x16x32_bf16 v[118:121], v[150:153], v[194:197], v[118:121]
	v_mfma_f32_16x16x32_bf16 v[102:105], v[150:153], v[206:209], v[102:105]
	v_mfma_f32_16x16x32_bf16 v[102:105], v[154:157], v[210:213], v[102:105]
	v_mfma_f32_16x16x32_bf16 v[86:89], v[154:157], v[218:221], v[86:89]
	v_mfma_f32_16x16x32_bf16 v[86:89], v[150:153], v[214:217], v[86:89]
	v_mfma_f32_16x16x32_bf16 v[78:81], v[158:161], v[214:217], v[78:81]
	v_mfma_f32_16x16x32_bf16 v[78:81], v[166:169], v[218:221], v[78:81]
	v_mfma_f32_16x16x32_bf16 v[94:97], v[166:169], v[210:213], v[94:97]
	v_mfma_f32_16x16x32_bf16 v[94:97], v[158:161], v[206:209], v[94:97]
	v_mfma_f32_16x16x32_bf16 v[110:113], v[158:161], v[194:197], v[110:113]
	v_mfma_f32_16x16x32_bf16 v[110:113], v[166:169], v[202:205], v[110:113]
	v_mfma_f32_16x16x32_bf16 v[122:125], v[166:169], v[190:193], v[122:125]
	v_mfma_f32_16x16x32_bf16 v[122:125], v[158:161], v[186:189], v[122:125]
	v_mfma_f32_16x16x32_bf16 v[114:117], v[170:173], v[186:189], v[114:117]
	v_mfma_f32_16x16x32_bf16 v[114:117], v[174:177], v[190:193], v[114:117]
	v_mfma_f32_16x16x32_bf16 v[98:101], v[174:177], v[202:205], v[98:101]
	v_mfma_f32_16x16x32_bf16 v[98:101], v[170:173], v[194:197], v[98:101]
	v_mfma_f32_16x16x32_bf16 v[82:85], v[170:173], v[206:209], v[82:85]
	v_mfma_f32_16x16x32_bf16 v[82:85], v[174:177], v[210:213], v[82:85]
	v_mfma_f32_16x16x32_bf16 v[70:73], v[174:177], v[218:221], v[70:73]
	v_mfma_f32_16x16x32_bf16 v[70:73], v[170:173], v[214:217], v[70:73]
	v_mfma_f32_16x16x32_bf16 v[66:69], v[178:181], v[214:217], v[66:69]
	v_mfma_f32_16x16x32_bf16 v[66:69], v[182:185], v[218:221], v[66:69]
	v_mfma_f32_16x16x32_bf16 v[74:77], v[182:185], v[210:213], v[74:77]
	v_mfma_f32_16x16x32_bf16 v[74:77], v[178:181], v[206:209], v[74:77]
	v_mfma_f32_16x16x32_bf16 v[90:93], v[178:181], v[194:197], v[90:93]
	v_mfma_f32_16x16x32_bf16 v[90:93], v[182:185], v[202:205], v[90:93]
	v_mfma_f32_16x16x32_bf16 v[106:109], v[182:185], v[190:193], v[106:109]
	v_mfma_f32_16x16x32_bf16 v[106:109], v[178:181], v[186:189], v[106:109]
	s_setprio 0
	s_barrier
	s_mov_b32 m0, s97
	v_lshl_add_u64 v[198:199], s[66:67], 0, v[136:137]
	ds_read_b128 v[186:189], v148 offset:16384
	ds_read_b128 v[190:193], v148 offset:17408
	ds_read_b128 v[194:197], v148 offset:18432
	ds_read_b128 v[202:205], v148 offset:19456
	ds_read_b128 v[206:209], v148 offset:20480
	ds_read_b128 v[210:213], v148 offset:21504
	ds_read_b128 v[214:217], v148 offset:22528
	ds_read_b128 v[218:221], v148 offset:23552
	global_load_lds_dwordx4 v[198:199], off
	v_lshl_add_u64 v[222:223], s[66:67], 0, v[132:133]
	s_mov_b32 m0, s94
	v_lshl_add_u64 v[224:225], s[68:69], 0, v[136:137]
	global_load_lds_dwordx4 v[222:223], off
	s_mov_b32 m0, s96
	v_lshl_add_u64 v[226:227], s[64:65], 0, v[134:135]
	global_load_lds_dwordx4 v[224:225], off
	v_lshl_add_u64 v[224:225], s[68:69], 0, v[132:133]
	s_mov_b32 m0, s95
	s_nop 0
	global_load_lds_dwordx4 v[224:225], off
	v_lshl_add_u64 v[224:225], s[64:65], 0, v[138:139]
	s_mov_b32 m0, s53
	s_nop 0
	global_load_lds_dwordx4 v[224:225], off
	s_mov_b32 m0, s75
	s_nop 0
	global_load_lds_dwordx4 v[226:227], off
	s_waitcnt vmcnt(8)
	s_waitcnt lgkmcnt(0)
	s_barrier
	s_setprio 1
	s_waitcnt lgkmcnt(0)
	v_mfma_f32_16x16x32_bf16 v[62:65], v[150:153], v[186:189], v[62:65]
	v_mfma_f32_16x16x32_bf16 v[62:65], v[154:157], v[190:193], v[62:65]
	v_mfma_f32_16x16x32_bf16 v[54:57], v[154:157], v[202:205], v[54:57]
	v_mfma_f32_16x16x32_bf16 v[54:57], v[150:153], v[194:197], v[54:57]
	v_mfma_f32_16x16x32_bf16 v[38:41], v[150:153], v[206:209], v[38:41]
	v_mfma_f32_16x16x32_bf16 v[38:41], v[154:157], v[210:213], v[38:41]
	v_mfma_f32_16x16x32_bf16 v[22:25], v[154:157], v[218:221], v[22:25]
	v_mfma_f32_16x16x32_bf16 v[22:25], v[150:153], v[214:217], v[22:25]
	v_mfma_f32_16x16x32_bf16 v[14:17], v[158:161], v[214:217], v[14:17]
	v_mfma_f32_16x16x32_bf16 v[14:17], v[166:169], v[218:221], v[14:17]
	v_mfma_f32_16x16x32_bf16 v[30:33], v[166:169], v[210:213], v[30:33]
	v_mfma_f32_16x16x32_bf16 v[30:33], v[158:161], v[206:209], v[30:33]
	v_mfma_f32_16x16x32_bf16 v[46:49], v[158:161], v[194:197], v[46:49]
	v_mfma_f32_16x16x32_bf16 v[46:49], v[166:169], v[202:205], v[46:49]
	v_mfma_f32_16x16x32_bf16 v[58:61], v[166:169], v[190:193], v[58:61]
	v_mfma_f32_16x16x32_bf16 v[58:61], v[158:161], v[186:189], v[58:61]
	v_mfma_f32_16x16x32_bf16 v[50:53], v[170:173], v[186:189], v[50:53]
	v_mfma_f32_16x16x32_bf16 v[50:53], v[174:177], v[190:193], v[50:53]
	v_mfma_f32_16x16x32_bf16 v[34:37], v[174:177], v[202:205], v[34:37]
	v_mfma_f32_16x16x32_bf16 v[34:37], v[170:173], v[194:197], v[34:37]
	v_mfma_f32_16x16x32_bf16 v[18:21], v[170:173], v[206:209], v[18:21]
	v_mfma_f32_16x16x32_bf16 v[18:21], v[174:177], v[210:213], v[18:21]
	v_mfma_f32_16x16x32_bf16 v[6:9], v[174:177], v[218:221], v[6:9]
	v_mfma_f32_16x16x32_bf16 v[6:9], v[170:173], v[214:217], v[6:9]
	v_mfma_f32_16x16x32_bf16 v[2:5], v[178:181], v[214:217], v[2:5]
	v_mfma_f32_16x16x32_bf16 v[2:5], v[182:185], v[218:221], v[2:5]
	v_mfma_f32_16x16x32_bf16 v[10:13], v[182:185], v[210:213], v[10:13]
	v_mfma_f32_16x16x32_bf16 v[10:13], v[178:181], v[206:209], v[10:13]
	v_mfma_f32_16x16x32_bf16 v[26:29], v[178:181], v[194:197], v[26:29]
	v_mfma_f32_16x16x32_bf16 v[26:29], v[182:185], v[202:205], v[26:29]
	v_mfma_f32_16x16x32_bf16 v[42:45], v[182:185], v[190:193], v[42:45]
	v_mfma_f32_16x16x32_bf16 v[42:45], v[178:181], v[186:189], v[42:45]
	s_setprio 0
	s_barrier
	v_add_u32_e32 v149, s93, v145
	ds_read_b128 v[150:153], v149
	ds_read_b128 v[154:157], v149 offset:1024
	ds_read_b128 v[158:161], v149 offset:2048
	ds_read_b128 v[166:169], v149 offset:3072
	v_add_u32_e32 v149, s92, v145
	ds_read_b128 v[170:173], v149
	ds_read_b128 v[174:177], v149 offset:1024
	ds_read_b128 v[178:181], v149 offset:2048
	ds_read_b128 v[182:185], v149 offset:3072
	s_mov_b32 m0, s76
	v_lshl_add_u64 v[228:229], s[62:63], 0, v[138:139]
	ds_read_b128 v[186:189], v148 offset:32768
	ds_read_b128 v[190:193], v148 offset:33792
	ds_read_b128 v[194:197], v148 offset:34816
	ds_read_b128 v[202:205], v148 offset:35840
	ds_read_b128 v[206:209], v148 offset:36864
	ds_read_b128 v[210:213], v148 offset:37888
	ds_read_b128 v[214:217], v148 offset:38912
	ds_read_b128 v[218:221], v148 offset:39936
	global_load_lds_dwordx4 v[228:229], off
	v_lshl_add_u64 v[228:229], s[62:63], 0, v[134:135]
	s_mov_b32 m0, s77
	s_nop 0
	global_load_lds_dwordx4 v[228:229], off
	s_waitcnt vmcnt(8)
	s_waitcnt lgkmcnt(0)
	s_barrier
	s_setprio 1
	s_waitcnt lgkmcnt(0)
	v_mfma_f32_16x16x32_bf16 v[126:129], v[150:153], v[186:189], v[126:129]
	v_mfma_f32_16x16x32_bf16 v[126:129], v[154:157], v[190:193], v[126:129]
	v_mfma_f32_16x16x32_bf16 v[118:121], v[154:157], v[202:205], v[118:121]
	v_mfma_f32_16x16x32_bf16 v[118:121], v[150:153], v[194:197], v[118:121]
	v_mfma_f32_16x16x32_bf16 v[102:105], v[150:153], v[206:209], v[102:105]
	v_mfma_f32_16x16x32_bf16 v[102:105], v[154:157], v[210:213], v[102:105]
	v_mfma_f32_16x16x32_bf16 v[86:89], v[154:157], v[218:221], v[86:89]
	v_mfma_f32_16x16x32_bf16 v[86:89], v[150:153], v[214:217], v[86:89]
	v_mfma_f32_16x16x32_bf16 v[78:81], v[158:161], v[214:217], v[78:81]
	v_mfma_f32_16x16x32_bf16 v[78:81], v[166:169], v[218:221], v[78:81]
	v_mfma_f32_16x16x32_bf16 v[94:97], v[166:169], v[210:213], v[94:97]
	v_mfma_f32_16x16x32_bf16 v[94:97], v[158:161], v[206:209], v[94:97]
	v_mfma_f32_16x16x32_bf16 v[110:113], v[158:161], v[194:197], v[110:113]
	v_mfma_f32_16x16x32_bf16 v[110:113], v[166:169], v[202:205], v[110:113]
	v_mfma_f32_16x16x32_bf16 v[122:125], v[166:169], v[190:193], v[122:125]
	v_mfma_f32_16x16x32_bf16 v[122:125], v[158:161], v[186:189], v[122:125]
	v_mfma_f32_16x16x32_bf16 v[114:117], v[170:173], v[186:189], v[114:117]
	v_mfma_f32_16x16x32_bf16 v[114:117], v[174:177], v[190:193], v[114:117]
	v_mfma_f32_16x16x32_bf16 v[98:101], v[174:177], v[202:205], v[98:101]
	v_mfma_f32_16x16x32_bf16 v[98:101], v[170:173], v[194:197], v[98:101]
	v_mfma_f32_16x16x32_bf16 v[82:85], v[170:173], v[206:209], v[82:85]
	v_mfma_f32_16x16x32_bf16 v[82:85], v[174:177], v[210:213], v[82:85]
	v_mfma_f32_16x16x32_bf16 v[70:73], v[174:177], v[218:221], v[70:73]
	v_mfma_f32_16x16x32_bf16 v[70:73], v[170:173], v[214:217], v[70:73]
	v_mfma_f32_16x16x32_bf16 v[66:69], v[178:181], v[214:217], v[66:69]
	v_mfma_f32_16x16x32_bf16 v[66:69], v[182:185], v[218:221], v[66:69]
	v_mfma_f32_16x16x32_bf16 v[74:77], v[182:185], v[210:213], v[74:77]
	v_mfma_f32_16x16x32_bf16 v[74:77], v[178:181], v[206:209], v[74:77]
	v_mfma_f32_16x16x32_bf16 v[90:93], v[178:181], v[194:197], v[90:93]
	v_mfma_f32_16x16x32_bf16 v[90:93], v[182:185], v[202:205], v[90:93]
	v_mfma_f32_16x16x32_bf16 v[106:109], v[182:185], v[190:193], v[106:109]
	v_mfma_f32_16x16x32_bf16 v[106:109], v[178:181], v[186:189], v[106:109]
	s_setprio 0
	s_barrier
	s_mov_b32 m0, s91
	v_lshl_add_u64 v[198:199], v[198:199], 0, s[14:15]
	ds_read_b128 v[186:189], v148 offset:49152
	ds_read_b128 v[190:193], v148 offset:50176
	ds_read_b128 v[194:197], v148 offset:51200
	ds_read_b128 v[202:205], v148 offset:52224
	ds_read_b128 v[206:209], v148 offset:53248
	ds_read_b128 v[210:213], v148 offset:54272
	ds_read_b128 v[214:217], v148 offset:55296
	ds_read_b128 v[218:221], v148 offset:56320
	global_load_lds_dwordx4 v[198:199], off
	v_lshl_add_u64 v[198:199], v[222:223], 0, s[14:15]
	s_mov_b32 m0, s89
	s_nop 0
	global_load_lds_dwordx4 v[198:199], off
	v_lshl_add_u64 v[198:199], s[60:61], 0, v[136:137]
	s_mov_b32 m0, s90
	s_nop 0
	global_load_lds_dwordx4 v[198:199], off
	v_lshl_add_u64 v[198:199], s[60:61], 0, v[132:133]
	s_mov_b32 m0, s44
	s_nop 0
	global_load_lds_dwordx4 v[198:199], off
	v_lshl_add_u64 v[198:199], v[224:225], 0, s[14:15]
	s_mov_b32 m0, s79
	s_nop 0
	global_load_lds_dwordx4 v[198:199], off
	v_lshl_add_u64 v[198:199], v[226:227], 0, s[14:15]
	s_mov_b32 m0, s80
	s_nop 0
	global_load_lds_dwordx4 v[198:199], off
	s_waitcnt vmcnt(8)
	s_waitcnt lgkmcnt(0)
	s_barrier
	s_setprio 1
	s_waitcnt lgkmcnt(0)
	v_mfma_f32_16x16x32_bf16 v[62:65], v[150:153], v[186:189], v[62:65]
	v_mfma_f32_16x16x32_bf16 v[62:65], v[154:157], v[190:193], v[62:65]
	v_mfma_f32_16x16x32_bf16 v[54:57], v[154:157], v[202:205], v[54:57]
	v_mfma_f32_16x16x32_bf16 v[54:57], v[150:153], v[194:197], v[54:57]
	v_mfma_f32_16x16x32_bf16 v[38:41], v[150:153], v[206:209], v[38:41]
	v_mfma_f32_16x16x32_bf16 v[38:41], v[154:157], v[210:213], v[38:41]
	v_mfma_f32_16x16x32_bf16 v[22:25], v[154:157], v[218:221], v[22:25]
	v_mfma_f32_16x16x32_bf16 v[22:25], v[150:153], v[214:217], v[22:25]
	v_mfma_f32_16x16x32_bf16 v[14:17], v[158:161], v[214:217], v[14:17]
	v_mfma_f32_16x16x32_bf16 v[14:17], v[166:169], v[218:221], v[14:17]
	v_mfma_f32_16x16x32_bf16 v[30:33], v[166:169], v[210:213], v[30:33]
	v_mfma_f32_16x16x32_bf16 v[30:33], v[158:161], v[206:209], v[30:33]
	v_mfma_f32_16x16x32_bf16 v[46:49], v[158:161], v[194:197], v[46:49]
	v_mfma_f32_16x16x32_bf16 v[46:49], v[166:169], v[202:205], v[46:49]
	v_mfma_f32_16x16x32_bf16 v[58:61], v[166:169], v[190:193], v[58:61]
	v_mfma_f32_16x16x32_bf16 v[58:61], v[158:161], v[186:189], v[58:61]
	v_mfma_f32_16x16x32_bf16 v[50:53], v[170:173], v[186:189], v[50:53]
	v_mfma_f32_16x16x32_bf16 v[50:53], v[174:177], v[190:193], v[50:53]
	v_mfma_f32_16x16x32_bf16 v[34:37], v[174:177], v[202:205], v[34:37]
	v_mfma_f32_16x16x32_bf16 v[34:37], v[170:173], v[194:197], v[34:37]
	v_mfma_f32_16x16x32_bf16 v[18:21], v[170:173], v[206:209], v[18:21]
	v_mfma_f32_16x16x32_bf16 v[18:21], v[174:177], v[210:213], v[18:21]
	v_mfma_f32_16x16x32_bf16 v[6:9], v[174:177], v[218:221], v[6:9]
	v_mfma_f32_16x16x32_bf16 v[6:9], v[170:173], v[214:217], v[6:9]
	v_mfma_f32_16x16x32_bf16 v[2:5], v[178:181], v[214:217], v[2:5]
	v_mfma_f32_16x16x32_bf16 v[2:5], v[182:185], v[218:221], v[2:5]
	v_mfma_f32_16x16x32_bf16 v[10:13], v[182:185], v[210:213], v[10:13]
	v_mfma_f32_16x16x32_bf16 v[10:13], v[178:181], v[206:209], v[10:13]
	v_mfma_f32_16x16x32_bf16 v[26:29], v[178:181], v[194:197], v[26:29]
	v_mfma_f32_16x16x32_bf16 v[26:29], v[182:185], v[202:205], v[26:29]
	v_mfma_f32_16x16x32_bf16 v[42:45], v[182:185], v[190:193], v[42:45]
	v_mfma_f32_16x16x32_bf16 v[42:45], v[178:181], v[186:189], v[42:45]
	s_setprio 0
	s_barrier
	s_movk_i32 s44, 0x100
	s_andn2_b64 vcc, exec, s[58:59]
	s_mov_b64 s[60:61], -1
	s_mov_b64 s[58:59], 0
	s_cbranch_vccz .LBB0_1667
	s_and_b64 vcc, exec, s[16:17]
	s_cbranch_vccz .LBB0_1670
	s_barrier

.LBB0_1685:
	ds_read_b128 v[156:159], v153
	ds_read_b128 v[166:169], v153 offset:1024
	ds_read_b128 v[170:173], v153 offset:2048
	ds_read_b128 v[174:177], v153 offset:3072
	ds_read_b128 v[178:181], v154
	ds_read_b128 v[182:185], v154 offset:1024
	ds_read_b128 v[186:189], v154 offset:2048
	ds_read_b128 v[190:193], v154 offset:3072
	s_add_u32 s36, s56, 0xfff00080
	s_addc_u32 s37, s57, -1
	s_cmp_eq_u32 s78, 60
	s_cselect_b32 s61, s25, s37
	s_cselect_b32 s60, s74, s36
	s_cselect_b32 s59, s21, s77
	s_cselect_b32 s58, s75, s76
	v_lshl_add_u64 v[160:161], s[56:57], 0, v[140:141]
	s_add_i32 m0, s55, 0xc000
	ds_read_b128 v[194:197], v155
	ds_read_b128 v[202:205], v155 offset:1024
	ds_read_b128 v[206:209], v155 offset:2048
	ds_read_b128 v[210:213], v155 offset:3072
	ds_read_b128 v[214:217], v155 offset:4096
	ds_read_b128 v[218:221], v155 offset:5120
	ds_read_b128 v[222:225], v155 offset:6144
	ds_read_b128 v[226:229], v155 offset:7168
	global_load_lds_dwordx4 v[160:161], off
	v_lshl_add_u64 v[160:161], s[56:57], 0, v[142:143]
	s_add_i32 m0, s55, 0xe000
	s_nop 0
	global_load_lds_dwordx4 v[160:161], off
	s_waitcnt vmcnt(8)
	s_waitcnt lgkmcnt(0)
	s_barrier
	s_setprio 1
	s_waitcnt lgkmcnt(0)
	v_mfma_f32_16x16x32_bf16 v[126:129], v[156:159], v[194:197], v[126:129]
	v_mfma_f32_16x16x32_bf16 v[126:129], v[166:169], v[202:205], v[126:129]
	v_mfma_f32_16x16x32_bf16 v[118:121], v[166:169], v[210:213], v[118:121]
	v_mfma_f32_16x16x32_bf16 v[118:121], v[156:159], v[206:209], v[118:121]
	v_mfma_f32_16x16x32_bf16 v[102:105], v[156:159], v[214:217], v[102:105]
	v_mfma_f32_16x16x32_bf16 v[102:105], v[166:169], v[218:221], v[102:105]
	v_mfma_f32_16x16x32_bf16 v[86:89], v[166:169], v[226:229], v[86:89]
	v_mfma_f32_16x16x32_bf16 v[86:89], v[156:159], v[222:225], v[86:89]
	v_mfma_f32_16x16x32_bf16 v[78:81], v[170:173], v[222:225], v[78:81]
	v_mfma_f32_16x16x32_bf16 v[78:81], v[174:177], v[226:229], v[78:81]
	v_mfma_f32_16x16x32_bf16 v[94:97], v[174:177], v[218:221], v[94:97]
	v_mfma_f32_16x16x32_bf16 v[94:97], v[170:173], v[214:217], v[94:97]
	v_mfma_f32_16x16x32_bf16 v[110:113], v[170:173], v[206:209], v[110:113]
	v_mfma_f32_16x16x32_bf16 v[110:113], v[174:177], v[210:213], v[110:113]
	v_mfma_f32_16x16x32_bf16 v[122:125], v[174:177], v[202:205], v[122:125]
	v_mfma_f32_16x16x32_bf16 v[122:125], v[170:173], v[194:197], v[122:125]
	v_mfma_f32_16x16x32_bf16 v[114:117], v[178:181], v[194:197], v[114:117]
	v_mfma_f32_16x16x32_bf16 v[114:117], v[182:185], v[202:205], v[114:117]
	v_mfma_f32_16x16x32_bf16 v[98:101], v[182:185], v[210:213], v[98:101]
	v_mfma_f32_16x16x32_bf16 v[98:101], v[178:181], v[206:209], v[98:101]
	v_mfma_f32_16x16x32_bf16 v[82:85], v[178:181], v[214:217], v[82:85]
	v_mfma_f32_16x16x32_bf16 v[82:85], v[182:185], v[218:221], v[82:85]
	v_mfma_f32_16x16x32_bf16 v[70:73], v[182:185], v[226:229], v[70:73]
	v_mfma_f32_16x16x32_bf16 v[70:73], v[178:181], v[222:225], v[70:73]
	v_mfma_f32_16x16x32_bf16 v[66:69], v[186:189], v[222:225], v[66:69]
	v_mfma_f32_16x16x32_bf16 v[66:69], v[190:193], v[226:229], v[66:69]
	v_mfma_f32_16x16x32_bf16 v[74:77], v[190:193], v[218:221], v[74:77]
	v_mfma_f32_16x16x32_bf16 v[74:77], v[186:189], v[214:217], v[74:77]
	v_mfma_f32_16x16x32_bf16 v[90:93], v[186:189], v[206:209], v[90:93]
	v_mfma_f32_16x16x32_bf16 v[90:93], v[190:193], v[210:213], v[90:93]
	v_mfma_f32_16x16x32_bf16 v[106:109], v[190:193], v[202:205], v[106:109]
	v_mfma_f32_16x16x32_bf16 v[106:109], v[186:189], v[194:197], v[106:109]
	s_setprio 0
	s_barrier
	s_add_i32 s36, s68, s38
	v_lshl_add_u64 v[160:161], s[58:59], 0, v[136:137]
	s_mov_b32 m0, s36
	ds_read_b128 v[194:197], v155 offset:16384
	ds_read_b128 v[202:205], v155 offset:17408
	ds_read_b128 v[206:209], v155 offset:18432
	ds_read_b128 v[210:213], v155 offset:19456
	ds_read_b128 v[214:217], v155 offset:20480
	ds_read_b128 v[218:221], v155 offset:21504
	ds_read_b128 v[222:225], v155 offset:22528
	ds_read_b128 v[226:229], v155 offset:23552
	global_load_lds_dwordx4 v[160:161], off
	s_add_i32 m0, s36, 0x2000
	s_add_u32 s80, s58, 0x100000
	v_lshl_add_u64 v[198:199], s[58:59], 0, v[132:133]
	s_addc_u32 s81, s59, 0
	s_add_i32 s36, s69, s38
	global_load_lds_dwordx4 v[198:199], off
	v_lshl_add_u64 v[230:231], s[80:81], 0, v[136:137]
	s_mov_b32 m0, s36
	v_lshl_add_u64 v[232:233], s[60:61], 0, v[134:135]
	global_load_lds_dwordx4 v[230:231], off
	v_lshl_add_u64 v[230:231], s[80:81], 0, v[132:133]
	s_add_i32 m0, s36, 0x2000
	s_nop 0
	global_load_lds_dwordx4 v[230:231], off
	v_lshl_add_u64 v[230:231], s[60:61], 0, v[138:139]
	s_mov_b32 m0, s55
	s_nop 0
	global_load_lds_dwordx4 v[230:231], off
	s_mov_b32 m0, s63
	s_nop 0
	global_load_lds_dwordx4 v[232:233], off
	s_waitcnt vmcnt(8)
	s_waitcnt lgkmcnt(0)
	s_barrier
	s_setprio 1
	s_waitcnt lgkmcnt(0)
	v_mfma_f32_16x16x32_bf16 v[62:65], v[156:159], v[194:197], v[62:65]
	v_mfma_f32_16x16x32_bf16 v[62:65], v[166:169], v[202:205], v[62:65]
	v_mfma_f32_16x16x32_bf16 v[54:57], v[166:169], v[210:213], v[54:57]
	v_mfma_f32_16x16x32_bf16 v[54:57], v[156:159], v[206:209], v[54:57]
	v_mfma_f32_16x16x32_bf16 v[38:41], v[156:159], v[214:217], v[38:41]
	v_mfma_f32_16x16x32_bf16 v[38:41], v[166:169], v[218:221], v[38:41]
	v_mfma_f32_16x16x32_bf16 v[22:25], v[166:169], v[226:229], v[22:25]
	v_mfma_f32_16x16x32_bf16 v[22:25], v[156:159], v[222:225], v[22:25]
	v_mfma_f32_16x16x32_bf16 v[14:17], v[170:173], v[222:225], v[14:17]
	v_mfma_f32_16x16x32_bf16 v[14:17], v[174:177], v[226:229], v[14:17]
	v_mfma_f32_16x16x32_bf16 v[30:33], v[174:177], v[218:221], v[30:33]
	v_mfma_f32_16x16x32_bf16 v[30:33], v[170:173], v[214:217], v[30:33]
	v_mfma_f32_16x16x32_bf16 v[46:49], v[170:173], v[206:209], v[46:49]
	v_mfma_f32_16x16x32_bf16 v[46:49], v[174:177], v[210:213], v[46:49]
	v_mfma_f32_16x16x32_bf16 v[58:61], v[174:177], v[202:205], v[58:61]
	v_mfma_f32_16x16x32_bf16 v[58:61], v[170:173], v[194:197], v[58:61]
	v_mfma_f32_16x16x32_bf16 v[50:53], v[178:181], v[194:197], v[50:53]
	v_mfma_f32_16x16x32_bf16 v[50:53], v[182:185], v[202:205], v[50:53]
	v_mfma_f32_16x16x32_bf16 v[34:37], v[182:185], v[210:213], v[34:37]
	v_mfma_f32_16x16x32_bf16 v[34:37], v[178:181], v[206:209], v[34:37]
	v_mfma_f32_16x16x32_bf16 v[18:21], v[178:181], v[214:217], v[18:21]
	v_mfma_f32_16x16x32_bf16 v[18:21], v[182:185], v[218:221], v[18:21]
	v_mfma_f32_16x16x32_bf16 v[6:9], v[182:185], v[226:229], v[6:9]
	v_mfma_f32_16x16x32_bf16 v[6:9], v[178:181], v[222:225], v[6:9]
	v_mfma_f32_16x16x32_bf16 v[2:5], v[186:189], v[222:225], v[2:5]
	v_mfma_f32_16x16x32_bf16 v[2:5], v[190:193], v[226:229], v[2:5]
	v_mfma_f32_16x16x32_bf16 v[10:13], v[190:193], v[218:221], v[10:13]
	v_mfma_f32_16x16x32_bf16 v[10:13], v[186:189], v[214:217], v[10:13]
	v_mfma_f32_16x16x32_bf16 v[26:29], v[186:189], v[206:209], v[26:29]
	v_mfma_f32_16x16x32_bf16 v[26:29], v[190:193], v[210:213], v[26:29]
	v_mfma_f32_16x16x32_bf16 v[42:45], v[190:193], v[202:205], v[42:45]
	v_mfma_f32_16x16x32_bf16 v[42:45], v[186:189], v[194:197], v[42:45]
	s_setprio 0
	s_barrier
	s_add_i32 s36, 0, 0x18000
	v_add_u32_e32 v165, s36, v151
	s_add_i32 s37, 0, 0x1c000
	ds_read_b128 v[156:159], v165
	ds_read_b128 v[166:169], v165 offset:1024
	ds_read_b128 v[170:173], v165 offset:2048
	ds_read_b128 v[174:177], v165 offset:3072
	v_add_u32_e32 v165, s37, v151
	ds_read_b128 v[178:181], v165
	ds_read_b128 v[182:185], v165 offset:1024
	ds_read_b128 v[186:189], v165 offset:2048
	ds_read_b128 v[190:193], v165 offset:3072
	s_add_u32 s60, s60, 0x100000
	s_addc_u32 s61, s61, 0
	s_mov_b32 m0, s64
	v_lshl_add_u64 v[234:235], s[60:61], 0, v[138:139]
	ds_read_b128 v[194:197], v155 offset:32768
	ds_read_b128 v[202:205], v155 offset:33792
	ds_read_b128 v[206:209], v155 offset:34816
	ds_read_b128 v[210:213], v155 offset:35840
	ds_read_b128 v[214:217], v155 offset:36864
	ds_read_b128 v[218:221], v155 offset:37888
	ds_read_b128 v[222:225], v155 offset:38912
	ds_read_b128 v[226:229], v155 offset:39936
	global_load_lds_dwordx4 v[234:235], off
	v_lshl_add_u64 v[234:235], s[60:61], 0, v[134:135]
	s_mov_b32 m0, s65
	s_nop 0
	global_load_lds_dwordx4 v[234:235], off
	s_waitcnt vmcnt(8)
	s_waitcnt lgkmcnt(0)
	s_barrier
	s_setprio 1
	s_waitcnt lgkmcnt(0)
	v_mfma_f32_16x16x32_bf16 v[126:129], v[156:159], v[194:197], v[126:129]
	v_mfma_f32_16x16x32_bf16 v[126:129], v[166:169], v[202:205], v[126:129]
	v_mfma_f32_16x16x32_bf16 v[118:121], v[166:169], v[210:213], v[118:121]
	v_mfma_f32_16x16x32_bf16 v[118:121], v[156:159], v[206:209], v[118:121]
	v_mfma_f32_16x16x32_bf16 v[102:105], v[156:159], v[214:217], v[102:105]
	v_mfma_f32_16x16x32_bf16 v[102:105], v[166:169], v[218:221], v[102:105]
	v_mfma_f32_16x16x32_bf16 v[86:89], v[166:169], v[226:229], v[86:89]
	v_mfma_f32_16x16x32_bf16 v[86:89], v[156:159], v[222:225], v[86:89]
	v_mfma_f32_16x16x32_bf16 v[78:81], v[170:173], v[222:225], v[78:81]
	v_mfma_f32_16x16x32_bf16 v[78:81], v[174:177], v[226:229], v[78:81]
	v_mfma_f32_16x16x32_bf16 v[94:97], v[174:177], v[218:221], v[94:97]
	v_mfma_f32_16x16x32_bf16 v[94:97], v[170:173], v[214:217], v[94:97]
	v_mfma_f32_16x16x32_bf16 v[110:113], v[170:173], v[206:209], v[110:113]
	v_mfma_f32_16x16x32_bf16 v[110:113], v[174:177], v[210:213], v[110:113]
	v_mfma_f32_16x16x32_bf16 v[122:125], v[174:177], v[202:205], v[122:125]
	v_mfma_f32_16x16x32_bf16 v[122:125], v[170:173], v[194:197], v[122:125]
	v_mfma_f32_16x16x32_bf16 v[114:117], v[178:181], v[194:197], v[114:117]
	v_mfma_f32_16x16x32_bf16 v[114:117], v[182:185], v[202:205], v[114:117]
	v_mfma_f32_16x16x32_bf16 v[98:101], v[182:185], v[210:213], v[98:101]
	v_mfma_f32_16x16x32_bf16 v[98:101], v[178:181], v[206:209], v[98:101]
	v_mfma_f32_16x16x32_bf16 v[82:85], v[178:181], v[214:217], v[82:85]
	v_mfma_f32_16x16x32_bf16 v[82:85], v[182:185], v[218:221], v[82:85]
	v_mfma_f32_16x16x32_bf16 v[70:73], v[182:185], v[226:229], v[70:73]
	v_mfma_f32_16x16x32_bf16 v[70:73], v[178:181], v[222:225], v[70:73]
	v_mfma_f32_16x16x32_bf16 v[66:69], v[186:189], v[222:225], v[66:69]
	v_mfma_f32_16x16x32_bf16 v[66:69], v[190:193], v[226:229], v[66:69]
	v_mfma_f32_16x16x32_bf16 v[74:77], v[190:193], v[218:221], v[74:77]
	v_mfma_f32_16x16x32_bf16 v[74:77], v[186:189], v[214:217], v[74:77]
	v_mfma_f32_16x16x32_bf16 v[90:93], v[186:189], v[206:209], v[90:93]
	v_mfma_f32_16x16x32_bf16 v[90:93], v[190:193], v[210:213], v[90:93]
	v_mfma_f32_16x16x32_bf16 v[106:109], v[190:193], v[202:205], v[106:109]
	v_mfma_f32_16x16x32_bf16 v[106:109], v[186:189], v[194:197], v[106:109]
	s_setprio 0
	s_barrier
	s_add_i32 s36, s36, s38
	v_lshl_add_u64 v[160:161], v[160:161], 0, s[16:17]
	s_mov_b32 m0, s36
	ds_read_b128 v[194:197], v155 offset:49152
	ds_read_b128 v[202:205], v155 offset:50176
	ds_read_b128 v[206:209], v155 offset:51200
	ds_read_b128 v[210:213], v155 offset:52224
	ds_read_b128 v[214:217], v155 offset:53248
	ds_read_b128 v[218:221], v155 offset:54272
	ds_read_b128 v[222:225], v155 offset:55296
	ds_read_b128 v[226:229], v155 offset:56320
	global_load_lds_dwordx4 v[160:161], off
	s_add_i32 m0, s36, 0x2000
	s_add_u32 s58, s58, 0x100080
	v_lshl_add_u64 v[160:161], v[198:199], 0, s[16:17]
	s_addc_u32 s59, s59, 0
	s_add_i32 s36, s37, s38
	global_load_lds_dwordx4 v[160:161], off
	v_lshl_add_u64 v[160:161], s[58:59], 0, v[136:137]
	s_mov_b32 m0, s36
	s_nop 0
	global_load_lds_dwordx4 v[160:161], off
	v_lshl_add_u64 v[160:161], s[58:59], 0, v[132:133]
	s_add_i32 m0, s36, 0x2000
	s_nop 0
	global_load_lds_dwordx4 v[160:161], off
	v_lshl_add_u64 v[160:161], v[230:231], 0, s[16:17]
	s_mov_b32 m0, s66
	s_nop 0
	global_load_lds_dwordx4 v[160:161], off
	v_lshl_add_u64 v[160:161], v[232:233], 0, s[16:17]
	s_mov_b32 m0, s67
	s_nop 0
	global_load_lds_dwordx4 v[160:161], off
	s_waitcnt vmcnt(8)
	s_waitcnt lgkmcnt(0)
	s_barrier
	s_setprio 1
	s_waitcnt lgkmcnt(0)
	v_mfma_f32_16x16x32_bf16 v[62:65], v[156:159], v[194:197], v[62:65]
	v_mfma_f32_16x16x32_bf16 v[62:65], v[166:169], v[202:205], v[62:65]
	v_mfma_f32_16x16x32_bf16 v[54:57], v[166:169], v[210:213], v[54:57]
	v_mfma_f32_16x16x32_bf16 v[54:57], v[156:159], v[206:209], v[54:57]
	v_mfma_f32_16x16x32_bf16 v[38:41], v[156:159], v[214:217], v[38:41]
	v_mfma_f32_16x16x32_bf16 v[38:41], v[166:169], v[218:221], v[38:41]
	v_mfma_f32_16x16x32_bf16 v[22:25], v[166:169], v[226:229], v[22:25]
	v_mfma_f32_16x16x32_bf16 v[22:25], v[156:159], v[222:225], v[22:25]
	v_mfma_f32_16x16x32_bf16 v[14:17], v[170:173], v[222:225], v[14:17]
	v_mfma_f32_16x16x32_bf16 v[14:17], v[174:177], v[226:229], v[14:17]
	v_mfma_f32_16x16x32_bf16 v[30:33], v[174:177], v[218:221], v[30:33]
	v_mfma_f32_16x16x32_bf16 v[30:33], v[170:173], v[214:217], v[30:33]
	v_mfma_f32_16x16x32_bf16 v[46:49], v[170:173], v[206:209], v[46:49]
	v_mfma_f32_16x16x32_bf16 v[46:49], v[174:177], v[210:213], v[46:49]
	v_mfma_f32_16x16x32_bf16 v[58:61], v[174:177], v[202:205], v[58:61]
	v_mfma_f32_16x16x32_bf16 v[58:61], v[170:173], v[194:197], v[58:61]
	v_mfma_f32_16x16x32_bf16 v[50:53], v[178:181], v[194:197], v[50:53]
	v_mfma_f32_16x16x32_bf16 v[50:53], v[182:185], v[202:205], v[50:53]
	v_mfma_f32_16x16x32_bf16 v[34:37], v[182:185], v[210:213], v[34:37]
	v_mfma_f32_16x16x32_bf16 v[34:37], v[178:181], v[206:209], v[34:37]
	v_mfma_f32_16x16x32_bf16 v[18:21], v[178:181], v[214:217], v[18:21]
	v_mfma_f32_16x16x32_bf16 v[18:21], v[182:185], v[218:221], v[18:21]
	v_mfma_f32_16x16x32_bf16 v[6:9], v[182:185], v[226:229], v[6:9]
	v_mfma_f32_16x16x32_bf16 v[6:9], v[178:181], v[222:225], v[6:9]
	v_mfma_f32_16x16x32_bf16 v[2:5], v[186:189], v[222:225], v[2:5]
	v_mfma_f32_16x16x32_bf16 v[2:5], v[190:193], v[226:229], v[2:5]
	v_mfma_f32_16x16x32_bf16 v[10:13], v[190:193], v[218:221], v[10:13]
	v_mfma_f32_16x16x32_bf16 v[10:13], v[186:189], v[214:217], v[10:13]
	v_mfma_f32_16x16x32_bf16 v[26:29], v[186:189], v[206:209], v[26:29]
	v_mfma_f32_16x16x32_bf16 v[26:29], v[190:193], v[210:213], v[26:29]
	v_mfma_f32_16x16x32_bf16 v[42:45], v[190:193], v[202:205], v[42:45]
	v_mfma_f32_16x16x32_bf16 v[42:45], v[186:189], v[194:197], v[42:45]
	s_setprio 0
	s_barrier
	s_add_i32 s78, s78, 2
	s_add_u32 s56, s56, 0x100
	s_addc_u32 s57, s57, 0
	s_add_u32 s76, s76, 0x100
	s_addc_u32 s77, s77, 0
	s_cmp_gt_u32 s78, 61
	s_cbranch_scc0 .LBB0_1685
	s_and_b64 vcc, exec, s[18:19]
	s_cbranch_vccz .LBB0_1688
	s_barrier

.LBB0_1701:
	s_add_u32 s36, s56, s44
	s_addc_u32 s37, s57, 0
	s_add_u32 s64, s36, 0x100
	s_addc_u32 s65, s37, 0
	s_and_b64 s[62:63], s[60:61], exec
	s_cselect_b32 s65, s21, s65
	s_cselect_b32 s64, s86, s64
	s_add_u32 s44, s54, s44
	s_addc_u32 s62, s55, 0
	s_add_u32 s44, s44, 0x100
	s_addc_u32 s62, s62, 0
	s_and_b64 s[60:61], s[60:61], exec
	s_cselect_b32 s67, s25, s62
	s_cselect_b32 s66, s87, s44
	s_add_u32 s70, s36, 0x10080
	s_addc_u32 s71, s37, 0
	s_add_i32 s97, s81, s39
	ds_read_b128 v[152:155], v147
	ds_read_b128 v[156:159], v147 offset:1024
	ds_read_b128 v[166:169], v147 offset:2048
	ds_read_b128 v[170:173], v147 offset:3072
	ds_read_b128 v[174:177], v150
	ds_read_b128 v[178:181], v150 offset:1024
	ds_read_b128 v[182:185], v150 offset:2048
	ds_read_b128 v[186:189], v150 offset:3072
	s_add_i32 m0, s74, 0xc000
	s_add_i32 vcc_lo, s74, 0xe000
	s_add_i32 s94, s97, 0x2000
	s_add_u32 s68, s66, 0x10000
	s_addc_u32 s69, s67, 0
	s_add_i32 s96, s82, s39
	s_add_i32 s95, s96, 0x2000
	s_add_i32 s93, 0, 0x18000
	s_add_i32 s92, 0, 0x1c000
	s_add_u32 s62, s64, 0x10000
	s_addc_u32 s63, s65, 0
	s_add_i32 s91, s93, s39
	s_add_i32 s89, s91, 0x2000
	s_add_u32 s60, s66, 0x10080
	s_addc_u32 s61, s67, 0
	s_add_i32 s90, s92, s39
	s_add_i32 s44, s90, 0x2000
	v_lshl_add_u64 v[160:161], s[70:71], 0, v[138:139]
	ds_read_b128 v[190:193], v151
	ds_read_b128 v[194:197], v151 offset:1024
	ds_read_b128 v[202:205], v151 offset:2048
	ds_read_b128 v[206:209], v151 offset:3072
	ds_read_b128 v[210:213], v151 offset:4096
	ds_read_b128 v[214:217], v151 offset:5120
	ds_read_b128 v[218:221], v151 offset:6144
	ds_read_b128 v[222:225], v151 offset:7168
	global_load_lds_dwordx4 v[160:161], off
	v_lshl_add_u64 v[160:161], s[70:71], 0, v[134:135]
	s_mov_b32 m0, vcc_lo
	s_nop 0
	global_load_lds_dwordx4 v[160:161], off
	s_waitcnt vmcnt(8)
	s_waitcnt lgkmcnt(0)
	s_barrier
	s_setprio 1
	s_waitcnt lgkmcnt(0)
	v_mfma_f32_16x16x32_bf16 v[126:129], v[152:155], v[190:193], v[126:129]
	v_mfma_f32_16x16x32_bf16 v[126:129], v[156:159], v[194:197], v[126:129]
	v_mfma_f32_16x16x32_bf16 v[118:121], v[156:159], v[206:209], v[118:121]
	v_mfma_f32_16x16x32_bf16 v[118:121], v[152:155], v[202:205], v[118:121]
	v_mfma_f32_16x16x32_bf16 v[102:105], v[152:155], v[210:213], v[102:105]
	v_mfma_f32_16x16x32_bf16 v[102:105], v[156:159], v[214:217], v[102:105]
	v_mfma_f32_16x16x32_bf16 v[86:89], v[156:159], v[222:225], v[86:89]
	v_mfma_f32_16x16x32_bf16 v[86:89], v[152:155], v[218:221], v[86:89]
	v_mfma_f32_16x16x32_bf16 v[78:81], v[166:169], v[218:221], v[78:81]
	v_mfma_f32_16x16x32_bf16 v[78:81], v[170:173], v[222:225], v[78:81]
	v_mfma_f32_16x16x32_bf16 v[94:97], v[170:173], v[214:217], v[94:97]
	v_mfma_f32_16x16x32_bf16 v[94:97], v[166:169], v[210:213], v[94:97]
	v_mfma_f32_16x16x32_bf16 v[110:113], v[166:169], v[202:205], v[110:113]
	v_mfma_f32_16x16x32_bf16 v[110:113], v[170:173], v[206:209], v[110:113]
	v_mfma_f32_16x16x32_bf16 v[122:125], v[170:173], v[194:197], v[122:125]
	v_mfma_f32_16x16x32_bf16 v[122:125], v[166:169], v[190:193], v[122:125]
	v_mfma_f32_16x16x32_bf16 v[114:117], v[174:177], v[190:193], v[114:117]
	v_mfma_f32_16x16x32_bf16 v[114:117], v[178:181], v[194:197], v[114:117]
	v_mfma_f32_16x16x32_bf16 v[98:101], v[178:181], v[206:209], v[98:101]
	v_mfma_f32_16x16x32_bf16 v[98:101], v[174:177], v[202:205], v[98:101]
	v_mfma_f32_16x16x32_bf16 v[82:85], v[174:177], v[210:213], v[82:85]
	v_mfma_f32_16x16x32_bf16 v[82:85], v[178:181], v[214:217], v[82:85]
	v_mfma_f32_16x16x32_bf16 v[70:73], v[178:181], v[222:225], v[70:73]
	v_mfma_f32_16x16x32_bf16 v[70:73], v[174:177], v[218:221], v[70:73]
	v_mfma_f32_16x16x32_bf16 v[66:69], v[182:185], v[218:221], v[66:69]
	v_mfma_f32_16x16x32_bf16 v[66:69], v[186:189], v[222:225], v[66:69]
	v_mfma_f32_16x16x32_bf16 v[74:77], v[186:189], v[214:217], v[74:77]
	v_mfma_f32_16x16x32_bf16 v[74:77], v[182:185], v[210:213], v[74:77]
	v_mfma_f32_16x16x32_bf16 v[90:93], v[182:185], v[202:205], v[90:93]
	v_mfma_f32_16x16x32_bf16 v[90:93], v[186:189], v[206:209], v[90:93]
	v_mfma_f32_16x16x32_bf16 v[106:109], v[186:189], v[194:197], v[106:109]
	v_mfma_f32_16x16x32_bf16 v[106:109], v[182:185], v[190:193], v[106:109]
	s_setprio 0
	s_barrier
	s_mov_b32 m0, s97
	v_lshl_add_u64 v[160:161], s[66:67], 0, v[136:137]
	ds_read_b128 v[190:193], v151 offset:16384
	ds_read_b128 v[194:197], v151 offset:17408
	ds_read_b128 v[202:205], v151 offset:18432
	ds_read_b128 v[206:209], v151 offset:19456
	ds_read_b128 v[210:213], v151 offset:20480
	ds_read_b128 v[214:217], v151 offset:21504
	ds_read_b128 v[218:221], v151 offset:22528
	ds_read_b128 v[222:225], v151 offset:23552
	global_load_lds_dwordx4 v[160:161], off
	v_lshl_add_u64 v[198:199], s[66:67], 0, v[132:133]
	s_mov_b32 m0, s94
	v_lshl_add_u64 v[226:227], s[68:69], 0, v[136:137]
	global_load_lds_dwordx4 v[198:199], off
	s_mov_b32 m0, s96
	v_lshl_add_u64 v[228:229], s[64:65], 0, v[134:135]
	global_load_lds_dwordx4 v[226:227], off
	v_lshl_add_u64 v[226:227], s[68:69], 0, v[132:133]
	s_mov_b32 m0, s95
	s_nop 0
	global_load_lds_dwordx4 v[226:227], off
	v_lshl_add_u64 v[226:227], s[64:65], 0, v[138:139]
	s_mov_b32 m0, s74
	s_nop 0
	global_load_lds_dwordx4 v[226:227], off
	s_mov_b32 m0, s75
	s_nop 0
	global_load_lds_dwordx4 v[228:229], off
	s_waitcnt vmcnt(8)
	s_waitcnt lgkmcnt(0)
	s_barrier
	s_setprio 1
	s_waitcnt lgkmcnt(0)
	v_mfma_f32_16x16x32_bf16 v[62:65], v[152:155], v[190:193], v[62:65]
	v_mfma_f32_16x16x32_bf16 v[62:65], v[156:159], v[194:197], v[62:65]
	v_mfma_f32_16x16x32_bf16 v[54:57], v[156:159], v[206:209], v[54:57]
	v_mfma_f32_16x16x32_bf16 v[54:57], v[152:155], v[202:205], v[54:57]
	v_mfma_f32_16x16x32_bf16 v[38:41], v[152:155], v[210:213], v[38:41]
	v_mfma_f32_16x16x32_bf16 v[38:41], v[156:159], v[214:217], v[38:41]
	v_mfma_f32_16x16x32_bf16 v[22:25], v[156:159], v[222:225], v[22:25]
	v_mfma_f32_16x16x32_bf16 v[22:25], v[152:155], v[218:221], v[22:25]
	v_mfma_f32_16x16x32_bf16 v[14:17], v[166:169], v[218:221], v[14:17]
	v_mfma_f32_16x16x32_bf16 v[14:17], v[170:173], v[222:225], v[14:17]
	v_mfma_f32_16x16x32_bf16 v[30:33], v[170:173], v[214:217], v[30:33]
	v_mfma_f32_16x16x32_bf16 v[30:33], v[166:169], v[210:213], v[30:33]
	v_mfma_f32_16x16x32_bf16 v[46:49], v[166:169], v[202:205], v[46:49]
	v_mfma_f32_16x16x32_bf16 v[46:49], v[170:173], v[206:209], v[46:49]
	v_mfma_f32_16x16x32_bf16 v[58:61], v[170:173], v[194:197], v[58:61]
	v_mfma_f32_16x16x32_bf16 v[58:61], v[166:169], v[190:193], v[58:61]
	v_mfma_f32_16x16x32_bf16 v[50:53], v[174:177], v[190:193], v[50:53]
	v_mfma_f32_16x16x32_bf16 v[50:53], v[178:181], v[194:197], v[50:53]
	v_mfma_f32_16x16x32_bf16 v[34:37], v[178:181], v[206:209], v[34:37]
	v_mfma_f32_16x16x32_bf16 v[34:37], v[174:177], v[202:205], v[34:37]
	v_mfma_f32_16x16x32_bf16 v[18:21], v[174:177], v[210:213], v[18:21]
	v_mfma_f32_16x16x32_bf16 v[18:21], v[178:181], v[214:217], v[18:21]
	v_mfma_f32_16x16x32_bf16 v[6:9], v[178:181], v[222:225], v[6:9]
	v_mfma_f32_16x16x32_bf16 v[6:9], v[174:177], v[218:221], v[6:9]
	v_mfma_f32_16x16x32_bf16 v[2:5], v[182:185], v[218:221], v[2:5]
	v_mfma_f32_16x16x32_bf16 v[2:5], v[186:189], v[222:225], v[2:5]
	v_mfma_f32_16x16x32_bf16 v[10:13], v[186:189], v[214:217], v[10:13]
	v_mfma_f32_16x16x32_bf16 v[10:13], v[182:185], v[210:213], v[10:13]
	v_mfma_f32_16x16x32_bf16 v[26:29], v[182:185], v[202:205], v[26:29]
	v_mfma_f32_16x16x32_bf16 v[26:29], v[186:189], v[206:209], v[26:29]
	v_mfma_f32_16x16x32_bf16 v[42:45], v[186:189], v[194:197], v[42:45]
	v_mfma_f32_16x16x32_bf16 v[42:45], v[182:185], v[190:193], v[42:45]
	s_setprio 0
	s_barrier
	v_add_u32_e32 v165, s93, v145
	ds_read_b128 v[152:155], v165
	ds_read_b128 v[156:159], v165 offset:1024
	ds_read_b128 v[166:169], v165 offset:2048
	ds_read_b128 v[170:173], v165 offset:3072
	v_add_u32_e32 v165, s92, v145
	ds_read_b128 v[174:177], v165
	ds_read_b128 v[178:181], v165 offset:1024
	ds_read_b128 v[182:185], v165 offset:2048
	ds_read_b128 v[186:189], v165 offset:3072
	s_mov_b32 m0, s76
	v_lshl_add_u64 v[230:231], s[62:63], 0, v[138:139]
	ds_read_b128 v[190:193], v151 offset:32768
	ds_read_b128 v[194:197], v151 offset:33792
	ds_read_b128 v[202:205], v151 offset:34816
	ds_read_b128 v[206:209], v151 offset:35840
	ds_read_b128 v[210:213], v151 offset:36864
	ds_read_b128 v[214:217], v151 offset:37888
	ds_read_b128 v[218:221], v151 offset:38912
	ds_read_b128 v[222:225], v151 offset:39936
	global_load_lds_dwordx4 v[230:231], off
	v_lshl_add_u64 v[230:231], s[62:63], 0, v[134:135]
	s_mov_b32 m0, s77
	s_nop 0
	global_load_lds_dwordx4 v[230:231], off
	s_waitcnt vmcnt(8)
	s_waitcnt lgkmcnt(0)
	s_barrier
	s_setprio 1
	s_waitcnt lgkmcnt(0)
	v_mfma_f32_16x16x32_bf16 v[126:129], v[152:155], v[190:193], v[126:129]
	v_mfma_f32_16x16x32_bf16 v[126:129], v[156:159], v[194:197], v[126:129]
	v_mfma_f32_16x16x32_bf16 v[118:121], v[156:159], v[206:209], v[118:121]
	v_mfma_f32_16x16x32_bf16 v[118:121], v[152:155], v[202:205], v[118:121]
	v_mfma_f32_16x16x32_bf16 v[102:105], v[152:155], v[210:213], v[102:105]
	v_mfma_f32_16x16x32_bf16 v[102:105], v[156:159], v[214:217], v[102:105]
	v_mfma_f32_16x16x32_bf16 v[86:89], v[156:159], v[222:225], v[86:89]
	v_mfma_f32_16x16x32_bf16 v[86:89], v[152:155], v[218:221], v[86:89]
	v_mfma_f32_16x16x32_bf16 v[78:81], v[166:169], v[218:221], v[78:81]
	v_mfma_f32_16x16x32_bf16 v[78:81], v[170:173], v[222:225], v[78:81]
	v_mfma_f32_16x16x32_bf16 v[94:97], v[170:173], v[214:217], v[94:97]
	v_mfma_f32_16x16x32_bf16 v[94:97], v[166:169], v[210:213], v[94:97]
	v_mfma_f32_16x16x32_bf16 v[110:113], v[166:169], v[202:205], v[110:113]
	v_mfma_f32_16x16x32_bf16 v[110:113], v[170:173], v[206:209], v[110:113]
	v_mfma_f32_16x16x32_bf16 v[122:125], v[170:173], v[194:197], v[122:125]
	v_mfma_f32_16x16x32_bf16 v[122:125], v[166:169], v[190:193], v[122:125]
	v_mfma_f32_16x16x32_bf16 v[114:117], v[174:177], v[190:193], v[114:117]
	v_mfma_f32_16x16x32_bf16 v[114:117], v[178:181], v[194:197], v[114:117]
	v_mfma_f32_16x16x32_bf16 v[98:101], v[178:181], v[206:209], v[98:101]
	v_mfma_f32_16x16x32_bf16 v[98:101], v[174:177], v[202:205], v[98:101]
	v_mfma_f32_16x16x32_bf16 v[82:85], v[174:177], v[210:213], v[82:85]
	v_mfma_f32_16x16x32_bf16 v[82:85], v[178:181], v[214:217], v[82:85]
	v_mfma_f32_16x16x32_bf16 v[70:73], v[178:181], v[222:225], v[70:73]
	v_mfma_f32_16x16x32_bf16 v[70:73], v[174:177], v[218:221], v[70:73]
	v_mfma_f32_16x16x32_bf16 v[66:69], v[182:185], v[218:221], v[66:69]
	v_mfma_f32_16x16x32_bf16 v[66:69], v[186:189], v[222:225], v[66:69]
	v_mfma_f32_16x16x32_bf16 v[74:77], v[186:189], v[214:217], v[74:77]
	v_mfma_f32_16x16x32_bf16 v[74:77], v[182:185], v[210:213], v[74:77]
	v_mfma_f32_16x16x32_bf16 v[90:93], v[182:185], v[202:205], v[90:93]
	v_mfma_f32_16x16x32_bf16 v[90:93], v[186:189], v[206:209], v[90:93]
	v_mfma_f32_16x16x32_bf16 v[106:109], v[186:189], v[194:197], v[106:109]
	v_mfma_f32_16x16x32_bf16 v[106:109], v[182:185], v[190:193], v[106:109]
	s_setprio 0
	s_barrier
	s_mov_b32 m0, s91
	v_lshl_add_u64 v[160:161], v[160:161], 0, s[14:15]
	ds_read_b128 v[190:193], v151 offset:49152
	ds_read_b128 v[194:197], v151 offset:50176
	ds_read_b128 v[202:205], v151 offset:51200
	ds_read_b128 v[206:209], v151 offset:52224
	ds_read_b128 v[210:213], v151 offset:53248
	ds_read_b128 v[214:217], v151 offset:54272
	ds_read_b128 v[218:221], v151 offset:55296
	ds_read_b128 v[222:225], v151 offset:56320
	global_load_lds_dwordx4 v[160:161], off
	v_lshl_add_u64 v[160:161], v[198:199], 0, s[14:15]
	s_mov_b32 m0, s89
	s_nop 0
	global_load_lds_dwordx4 v[160:161], off
	v_lshl_add_u64 v[160:161], s[60:61], 0, v[136:137]
	s_mov_b32 m0, s90
	s_nop 0
	global_load_lds_dwordx4 v[160:161], off
	v_lshl_add_u64 v[160:161], s[60:61], 0, v[132:133]
	s_mov_b32 m0, s44
	s_nop 0
	global_load_lds_dwordx4 v[160:161], off
	v_lshl_add_u64 v[160:161], v[226:227], 0, s[14:15]
	s_mov_b32 m0, s79
	s_nop 0
	global_load_lds_dwordx4 v[160:161], off
	v_lshl_add_u64 v[160:161], v[228:229], 0, s[14:15]
	s_mov_b32 m0, s80
	s_nop 0
	global_load_lds_dwordx4 v[160:161], off
	s_waitcnt vmcnt(8)
	s_waitcnt lgkmcnt(0)
	s_barrier
	s_setprio 1
	s_waitcnt lgkmcnt(0)
	v_mfma_f32_16x16x32_bf16 v[62:65], v[152:155], v[190:193], v[62:65]
	v_mfma_f32_16x16x32_bf16 v[62:65], v[156:159], v[194:197], v[62:65]
	v_mfma_f32_16x16x32_bf16 v[54:57], v[156:159], v[206:209], v[54:57]
	v_mfma_f32_16x16x32_bf16 v[54:57], v[152:155], v[202:205], v[54:57]
	v_mfma_f32_16x16x32_bf16 v[38:41], v[152:155], v[210:213], v[38:41]
	v_mfma_f32_16x16x32_bf16 v[38:41], v[156:159], v[214:217], v[38:41]
	v_mfma_f32_16x16x32_bf16 v[22:25], v[156:159], v[222:225], v[22:25]
	v_mfma_f32_16x16x32_bf16 v[22:25], v[152:155], v[218:221], v[22:25]
	v_mfma_f32_16x16x32_bf16 v[14:17], v[166:169], v[218:221], v[14:17]
	v_mfma_f32_16x16x32_bf16 v[14:17], v[170:173], v[222:225], v[14:17]
	v_mfma_f32_16x16x32_bf16 v[30:33], v[170:173], v[214:217], v[30:33]
	v_mfma_f32_16x16x32_bf16 v[30:33], v[166:169], v[210:213], v[30:33]
	v_mfma_f32_16x16x32_bf16 v[46:49], v[166:169], v[202:205], v[46:49]
	v_mfma_f32_16x16x32_bf16 v[46:49], v[170:173], v[206:209], v[46:49]
	v_mfma_f32_16x16x32_bf16 v[58:61], v[170:173], v[194:197], v[58:61]
	v_mfma_f32_16x16x32_bf16 v[58:61], v[166:169], v[190:193], v[58:61]
	v_mfma_f32_16x16x32_bf16 v[50:53], v[174:177], v[190:193], v[50:53]
	v_mfma_f32_16x16x32_bf16 v[50:53], v[178:181], v[194:197], v[50:53]
	v_mfma_f32_16x16x32_bf16 v[34:37], v[178:181], v[206:209], v[34:37]
	v_mfma_f32_16x16x32_bf16 v[34:37], v[174:177], v[202:205], v[34:37]
	v_mfma_f32_16x16x32_bf16 v[18:21], v[174:177], v[210:213], v[18:21]
	v_mfma_f32_16x16x32_bf16 v[18:21], v[178:181], v[214:217], v[18:21]
	v_mfma_f32_16x16x32_bf16 v[6:9], v[178:181], v[222:225], v[6:9]
	v_mfma_f32_16x16x32_bf16 v[6:9], v[174:177], v[218:221], v[6:9]
	v_mfma_f32_16x16x32_bf16 v[2:5], v[182:185], v[218:221], v[2:5]
	v_mfma_f32_16x16x32_bf16 v[2:5], v[186:189], v[222:225], v[2:5]
	v_mfma_f32_16x16x32_bf16 v[10:13], v[186:189], v[214:217], v[10:13]
	v_mfma_f32_16x16x32_bf16 v[10:13], v[182:185], v[210:213], v[10:13]
	v_mfma_f32_16x16x32_bf16 v[26:29], v[182:185], v[202:205], v[26:29]
	v_mfma_f32_16x16x32_bf16 v[26:29], v[186:189], v[206:209], v[26:29]
	v_mfma_f32_16x16x32_bf16 v[42:45], v[186:189], v[194:197], v[42:45]
	v_mfma_f32_16x16x32_bf16 v[42:45], v[182:185], v[190:193], v[42:45]
	s_setprio 0
	s_barrier
	s_movk_i32 s44, 0x100
	s_andn2_b64 vcc, exec, s[58:59]
	s_mov_b64 s[60:61], -1
	s_mov_b64 s[58:59], 0
	s_cbranch_vccz .LBB0_1701
	s_and_b64 vcc, exec, s[16:17]
	s_cbranch_vccz .LBB0_1704
	s_barrier

.LBB0_1902:
	ds_read_b128 v[148:151], v156
	ds_read_b128 v[166:169], v156 offset:1024
	ds_read_b128 v[170:173], v156 offset:2048
	ds_read_b128 v[174:177], v156 offset:3072
	ds_read_b128 v[178:181], v157
	ds_read_b128 v[182:185], v157 offset:1024
	ds_read_b128 v[186:189], v157 offset:2048
	ds_read_b128 v[190:193], v157 offset:3072
	s_add_i32 s92, s58, 2
	s_add_u32 s36, s56, 0xffd50080
	s_addc_u32 s37, s57, -1
	s_cmp_eq_u32 s89, s58
	s_cselect_b32 s58, s54, s90
	s_cselect_b32 s61, s53, s37
	s_cselect_b32 s60, s52, s36
	s_cselect_b32 s59, s55, s91
	v_lshl_add_u64 v[152:153], s[56:57], 0, v[142:143]
	s_add_i32 m0, s67, 0xc000
	ds_read_b128 v[194:197], v158
	ds_read_b128 v[202:205], v158 offset:1024
	ds_read_b128 v[206:209], v158 offset:2048
	ds_read_b128 v[210:213], v158 offset:3072
	ds_read_b128 v[214:217], v158 offset:4096
	ds_read_b128 v[218:221], v158 offset:5120
	ds_read_b128 v[222:225], v158 offset:6144
	ds_read_b128 v[226:229], v158 offset:7168
	global_load_lds_dwordx4 v[152:153], off
	v_lshl_add_u64 v[152:153], s[56:57], 0, v[144:145]
	s_add_i32 m0, s67, 0xe000
	s_nop 0
	global_load_lds_dwordx4 v[152:153], off
	s_waitcnt vmcnt(8)
	s_waitcnt lgkmcnt(0)
	s_barrier
	s_setprio 1
	s_waitcnt lgkmcnt(0)
	v_mfma_f32_16x16x32_bf16 v[126:129], v[148:151], v[194:197], v[126:129]
	v_mfma_f32_16x16x32_bf16 v[126:129], v[166:169], v[202:205], v[126:129]
	v_mfma_f32_16x16x32_bf16 v[110:113], v[166:169], v[210:213], v[110:113]
	v_mfma_f32_16x16x32_bf16 v[110:113], v[148:151], v[206:209], v[110:113]
	v_mfma_f32_16x16x32_bf16 v[94:97], v[148:151], v[214:217], v[94:97]
	v_mfma_f32_16x16x32_bf16 v[94:97], v[166:169], v[218:221], v[94:97]
	v_mfma_f32_16x16x32_bf16 v[78:81], v[166:169], v[226:229], v[78:81]
	v_mfma_f32_16x16x32_bf16 v[78:81], v[148:151], v[222:225], v[78:81]
	v_mfma_f32_16x16x32_bf16 v[74:77], v[170:173], v[222:225], v[74:77]
	v_mfma_f32_16x16x32_bf16 v[74:77], v[174:177], v[226:229], v[74:77]
	v_mfma_f32_16x16x32_bf16 v[90:93], v[174:177], v[218:221], v[90:93]
	v_mfma_f32_16x16x32_bf16 v[90:93], v[170:173], v[214:217], v[90:93]
	v_mfma_f32_16x16x32_bf16 v[106:109], v[170:173], v[206:209], v[106:109]
	v_mfma_f32_16x16x32_bf16 v[106:109], v[174:177], v[210:213], v[106:109]
	v_mfma_f32_16x16x32_bf16 v[122:125], v[174:177], v[202:205], v[122:125]
	v_mfma_f32_16x16x32_bf16 v[122:125], v[170:173], v[194:197], v[122:125]
	v_mfma_f32_16x16x32_bf16 v[118:121], v[178:181], v[194:197], v[118:121]
	v_mfma_f32_16x16x32_bf16 v[118:121], v[182:185], v[202:205], v[118:121]
	v_mfma_f32_16x16x32_bf16 v[102:105], v[182:185], v[210:213], v[102:105]
	v_mfma_f32_16x16x32_bf16 v[102:105], v[178:181], v[206:209], v[102:105]
	v_mfma_f32_16x16x32_bf16 v[86:89], v[178:181], v[214:217], v[86:89]
	v_mfma_f32_16x16x32_bf16 v[86:89], v[182:185], v[218:221], v[86:89]
	v_mfma_f32_16x16x32_bf16 v[70:73], v[182:185], v[226:229], v[70:73]
	v_mfma_f32_16x16x32_bf16 v[70:73], v[178:181], v[222:225], v[70:73]
	v_mfma_f32_16x16x32_bf16 v[66:69], v[186:189], v[222:225], v[66:69]
	v_mfma_f32_16x16x32_bf16 v[66:69], v[190:193], v[226:229], v[66:69]
	v_mfma_f32_16x16x32_bf16 v[82:85], v[190:193], v[218:221], v[82:85]
	v_mfma_f32_16x16x32_bf16 v[82:85], v[186:189], v[214:217], v[82:85]
	v_mfma_f32_16x16x32_bf16 v[98:101], v[186:189], v[206:209], v[98:101]
	v_mfma_f32_16x16x32_bf16 v[98:101], v[190:193], v[210:213], v[98:101]
	v_mfma_f32_16x16x32_bf16 v[114:117], v[190:193], v[202:205], v[114:117]
	v_mfma_f32_16x16x32_bf16 v[114:117], v[186:189], v[194:197], v[114:117]
	s_setprio 0
	s_barrier
	s_add_i32 s36, s77, s64
	v_lshl_add_u64 v[152:153], s[58:59], 0, v[134:135]
	s_mov_b32 m0, s36
	ds_read_b128 v[194:197], v158 offset:16384
	ds_read_b128 v[202:205], v158 offset:17408
	ds_read_b128 v[206:209], v158 offset:18432
	ds_read_b128 v[210:213], v158 offset:19456
	ds_read_b128 v[214:217], v158 offset:20480
	ds_read_b128 v[218:221], v158 offset:21504
	ds_read_b128 v[222:225], v158 offset:22528
	ds_read_b128 v[226:229], v158 offset:23552
	global_load_lds_dwordx4 v[152:153], off
	s_add_i32 m0, s36, 0x2000
	s_add_u32 s94, s58, 0x2b0000
	v_lshl_add_u64 v[160:161], s[58:59], 0, v[138:139]
	s_addc_u32 s95, s59, 0
	s_add_i32 s36, s78, s64
	global_load_lds_dwordx4 v[160:161], off
	v_lshl_add_u64 v[198:199], s[94:95], 0, v[134:135]
	s_mov_b32 m0, s36
	v_lshl_add_u64 v[230:231], s[60:61], 0, v[136:137]
	global_load_lds_dwordx4 v[198:199], off
	v_lshl_add_u64 v[198:199], s[94:95], 0, v[138:139]
	s_add_i32 m0, s36, 0x2000
	s_nop 0
	global_load_lds_dwordx4 v[198:199], off
	v_lshl_add_u64 v[198:199], s[60:61], 0, v[132:133]
	s_mov_b32 m0, s67
	s_nop 0
	global_load_lds_dwordx4 v[198:199], off
	s_mov_b32 m0, s68
	s_nop 0
	global_load_lds_dwordx4 v[230:231], off
	s_waitcnt vmcnt(8)
	s_waitcnt lgkmcnt(0)
	s_barrier
	s_setprio 1
	s_waitcnt lgkmcnt(0)
	v_mfma_f32_16x16x32_bf16 v[62:65], v[148:151], v[194:197], v[62:65]
	v_mfma_f32_16x16x32_bf16 v[62:65], v[166:169], v[202:205], v[62:65]
	v_mfma_f32_16x16x32_bf16 v[46:49], v[166:169], v[210:213], v[46:49]
	v_mfma_f32_16x16x32_bf16 v[46:49], v[148:151], v[206:209], v[46:49]
	v_mfma_f32_16x16x32_bf16 v[30:33], v[148:151], v[214:217], v[30:33]
	v_mfma_f32_16x16x32_bf16 v[30:33], v[166:169], v[218:221], v[30:33]
	v_mfma_f32_16x16x32_bf16 v[14:17], v[166:169], v[226:229], v[14:17]
	v_mfma_f32_16x16x32_bf16 v[14:17], v[148:151], v[222:225], v[14:17]
	v_mfma_f32_16x16x32_bf16 v[10:13], v[170:173], v[222:225], v[10:13]
	v_mfma_f32_16x16x32_bf16 v[10:13], v[174:177], v[226:229], v[10:13]
	v_mfma_f32_16x16x32_bf16 v[26:29], v[174:177], v[218:221], v[26:29]
	v_mfma_f32_16x16x32_bf16 v[26:29], v[170:173], v[214:217], v[26:29]
	v_mfma_f32_16x16x32_bf16 v[42:45], v[170:173], v[206:209], v[42:45]
	v_mfma_f32_16x16x32_bf16 v[42:45], v[174:177], v[210:213], v[42:45]
	v_mfma_f32_16x16x32_bf16 v[58:61], v[174:177], v[202:205], v[58:61]
	v_mfma_f32_16x16x32_bf16 v[58:61], v[170:173], v[194:197], v[58:61]
	v_mfma_f32_16x16x32_bf16 v[54:57], v[178:181], v[194:197], v[54:57]
	v_mfma_f32_16x16x32_bf16 v[54:57], v[182:185], v[202:205], v[54:57]
	v_mfma_f32_16x16x32_bf16 v[38:41], v[182:185], v[210:213], v[38:41]
	v_mfma_f32_16x16x32_bf16 v[38:41], v[178:181], v[206:209], v[38:41]
	v_mfma_f32_16x16x32_bf16 v[22:25], v[178:181], v[214:217], v[22:25]
	v_mfma_f32_16x16x32_bf16 v[22:25], v[182:185], v[218:221], v[22:25]
	v_mfma_f32_16x16x32_bf16 v[6:9], v[182:185], v[226:229], v[6:9]
	v_mfma_f32_16x16x32_bf16 v[6:9], v[178:181], v[222:225], v[6:9]
	v_mfma_f32_16x16x32_bf16 v[2:5], v[186:189], v[222:225], v[2:5]
	v_mfma_f32_16x16x32_bf16 v[2:5], v[190:193], v[226:229], v[2:5]
	v_mfma_f32_16x16x32_bf16 v[18:21], v[190:193], v[218:221], v[18:21]
	v_mfma_f32_16x16x32_bf16 v[18:21], v[186:189], v[214:217], v[18:21]
	v_mfma_f32_16x16x32_bf16 v[34:37], v[186:189], v[206:209], v[34:37]
	v_mfma_f32_16x16x32_bf16 v[34:37], v[190:193], v[210:213], v[34:37]
	v_mfma_f32_16x16x32_bf16 v[50:53], v[190:193], v[202:205], v[50:53]
	v_mfma_f32_16x16x32_bf16 v[50:53], v[186:189], v[194:197], v[50:53]
	s_setprio 0
	s_barrier
	s_add_i32 s36, 0, 0x18000
	v_add_u32_e32 v140, s36, v154
	s_add_i32 s37, 0, 0x1c000
	ds_read_b128 v[148:151], v140
	ds_read_b128 v[166:169], v140 offset:1024
	ds_read_b128 v[170:173], v140 offset:2048
	ds_read_b128 v[174:177], v140 offset:3072
	v_add_u32_e32 v140, s37, v154
	ds_read_b128 v[178:181], v140
	ds_read_b128 v[182:185], v140 offset:1024
	ds_read_b128 v[186:189], v140 offset:2048
	ds_read_b128 v[190:193], v140 offset:3072
	s_add_u32 s60, s60, 0x2b0000
	s_addc_u32 s61, s61, 0
	s_mov_b32 m0, s69
	v_lshl_add_u64 v[232:233], s[60:61], 0, v[132:133]
	ds_read_b128 v[194:197], v158 offset:32768
	ds_read_b128 v[202:205], v158 offset:33792
	ds_read_b128 v[206:209], v158 offset:34816
	ds_read_b128 v[210:213], v158 offset:35840
	ds_read_b128 v[214:217], v158 offset:36864
	ds_read_b128 v[218:221], v158 offset:37888
	ds_read_b128 v[222:225], v158 offset:38912
	ds_read_b128 v[226:229], v158 offset:39936
	global_load_lds_dwordx4 v[232:233], off
	v_lshl_add_u64 v[232:233], s[60:61], 0, v[136:137]
	s_mov_b32 m0, s70
	s_nop 0
	global_load_lds_dwordx4 v[232:233], off
	s_waitcnt vmcnt(8)
	s_waitcnt lgkmcnt(0)
	s_barrier
	s_setprio 1
	s_waitcnt lgkmcnt(0)
	v_mfma_f32_16x16x32_bf16 v[126:129], v[148:151], v[194:197], v[126:129]
	v_mfma_f32_16x16x32_bf16 v[126:129], v[166:169], v[202:205], v[126:129]
	v_mfma_f32_16x16x32_bf16 v[110:113], v[166:169], v[210:213], v[110:113]
	v_mfma_f32_16x16x32_bf16 v[110:113], v[148:151], v[206:209], v[110:113]
	v_mfma_f32_16x16x32_bf16 v[94:97], v[148:151], v[214:217], v[94:97]
	v_mfma_f32_16x16x32_bf16 v[94:97], v[166:169], v[218:221], v[94:97]
	v_mfma_f32_16x16x32_bf16 v[78:81], v[166:169], v[226:229], v[78:81]
	v_mfma_f32_16x16x32_bf16 v[78:81], v[148:151], v[222:225], v[78:81]
	v_mfma_f32_16x16x32_bf16 v[74:77], v[170:173], v[222:225], v[74:77]
	v_mfma_f32_16x16x32_bf16 v[74:77], v[174:177], v[226:229], v[74:77]
	v_mfma_f32_16x16x32_bf16 v[90:93], v[174:177], v[218:221], v[90:93]
	v_mfma_f32_16x16x32_bf16 v[90:93], v[170:173], v[214:217], v[90:93]
	v_mfma_f32_16x16x32_bf16 v[106:109], v[170:173], v[206:209], v[106:109]
	v_mfma_f32_16x16x32_bf16 v[106:109], v[174:177], v[210:213], v[106:109]
	v_mfma_f32_16x16x32_bf16 v[122:125], v[174:177], v[202:205], v[122:125]
	v_mfma_f32_16x16x32_bf16 v[122:125], v[170:173], v[194:197], v[122:125]
	v_mfma_f32_16x16x32_bf16 v[118:121], v[178:181], v[194:197], v[118:121]
	v_mfma_f32_16x16x32_bf16 v[118:121], v[182:185], v[202:205], v[118:121]
	v_mfma_f32_16x16x32_bf16 v[102:105], v[182:185], v[210:213], v[102:105]
	v_mfma_f32_16x16x32_bf16 v[102:105], v[178:181], v[206:209], v[102:105]
	v_mfma_f32_16x16x32_bf16 v[86:89], v[178:181], v[214:217], v[86:89]
	v_mfma_f32_16x16x32_bf16 v[86:89], v[182:185], v[218:221], v[86:89]
	v_mfma_f32_16x16x32_bf16 v[70:73], v[182:185], v[226:229], v[70:73]
	v_mfma_f32_16x16x32_bf16 v[70:73], v[178:181], v[222:225], v[70:73]
	v_mfma_f32_16x16x32_bf16 v[66:69], v[186:189], v[222:225], v[66:69]
	v_mfma_f32_16x16x32_bf16 v[66:69], v[190:193], v[226:229], v[66:69]
	v_mfma_f32_16x16x32_bf16 v[82:85], v[190:193], v[218:221], v[82:85]
	v_mfma_f32_16x16x32_bf16 v[82:85], v[186:189], v[214:217], v[82:85]
	v_mfma_f32_16x16x32_bf16 v[98:101], v[186:189], v[206:209], v[98:101]
	v_mfma_f32_16x16x32_bf16 v[98:101], v[190:193], v[210:213], v[98:101]
	v_mfma_f32_16x16x32_bf16 v[114:117], v[190:193], v[202:205], v[114:117]
	v_mfma_f32_16x16x32_bf16 v[114:117], v[186:189], v[194:197], v[114:117]
	s_setprio 0
	s_barrier
	s_add_i32 s36, s36, s64
	v_lshl_add_u64 v[152:153], v[152:153], 0, s[20:21]
	s_mov_b32 m0, s36
	ds_read_b128 v[194:197], v158 offset:49152
	ds_read_b128 v[202:205], v158 offset:50176
	ds_read_b128 v[206:209], v158 offset:51200
	ds_read_b128 v[210:213], v158 offset:52224
	ds_read_b128 v[214:217], v158 offset:53248
	ds_read_b128 v[218:221], v158 offset:54272
	ds_read_b128 v[222:225], v158 offset:55296
	ds_read_b128 v[226:229], v158 offset:56320
	global_load_lds_dwordx4 v[152:153], off
	s_add_i32 m0, s36, 0x2000
	s_add_u32 s58, s58, 0x2b0080
	v_lshl_add_u64 v[152:153], v[160:161], 0, s[20:21]
	s_addc_u32 s59, s59, 0
	s_add_i32 s36, s37, s64
	global_load_lds_dwordx4 v[152:153], off
	v_lshl_add_u64 v[152:153], s[58:59], 0, v[134:135]
	s_mov_b32 m0, s36
	s_nop 0
	global_load_lds_dwordx4 v[152:153], off
	v_lshl_add_u64 v[152:153], s[58:59], 0, v[138:139]
	s_add_i32 m0, s36, 0x2000
	s_nop 0
	global_load_lds_dwordx4 v[152:153], off
	v_lshl_add_u64 v[152:153], v[198:199], 0, s[20:21]
	s_mov_b32 m0, s73
	s_nop 0
	global_load_lds_dwordx4 v[152:153], off
	v_lshl_add_u64 v[152:153], v[230:231], 0, s[20:21]
	s_mov_b32 m0, s74
	s_nop 0
	global_load_lds_dwordx4 v[152:153], off
	s_waitcnt vmcnt(8)
	s_waitcnt lgkmcnt(0)
	s_barrier
	s_setprio 1
	s_waitcnt lgkmcnt(0)
	v_mfma_f32_16x16x32_bf16 v[62:65], v[148:151], v[194:197], v[62:65]
	v_mfma_f32_16x16x32_bf16 v[62:65], v[166:169], v[202:205], v[62:65]
	v_mfma_f32_16x16x32_bf16 v[46:49], v[166:169], v[210:213], v[46:49]
	v_mfma_f32_16x16x32_bf16 v[46:49], v[148:151], v[206:209], v[46:49]
	v_mfma_f32_16x16x32_bf16 v[30:33], v[148:151], v[214:217], v[30:33]
	v_mfma_f32_16x16x32_bf16 v[30:33], v[166:169], v[218:221], v[30:33]
	v_mfma_f32_16x16x32_bf16 v[14:17], v[166:169], v[226:229], v[14:17]
	v_mfma_f32_16x16x32_bf16 v[14:17], v[148:151], v[222:225], v[14:17]
	v_mfma_f32_16x16x32_bf16 v[10:13], v[170:173], v[222:225], v[10:13]
	v_mfma_f32_16x16x32_bf16 v[10:13], v[174:177], v[226:229], v[10:13]
	v_mfma_f32_16x16x32_bf16 v[26:29], v[174:177], v[218:221], v[26:29]
	v_mfma_f32_16x16x32_bf16 v[26:29], v[170:173], v[214:217], v[26:29]
	v_mfma_f32_16x16x32_bf16 v[42:45], v[170:173], v[206:209], v[42:45]
	v_mfma_f32_16x16x32_bf16 v[42:45], v[174:177], v[210:213], v[42:45]
	v_mfma_f32_16x16x32_bf16 v[58:61], v[174:177], v[202:205], v[58:61]
	v_mfma_f32_16x16x32_bf16 v[58:61], v[170:173], v[194:197], v[58:61]
	v_mfma_f32_16x16x32_bf16 v[54:57], v[178:181], v[194:197], v[54:57]
	v_mfma_f32_16x16x32_bf16 v[54:57], v[182:185], v[202:205], v[54:57]
	v_mfma_f32_16x16x32_bf16 v[38:41], v[182:185], v[210:213], v[38:41]
	v_mfma_f32_16x16x32_bf16 v[38:41], v[178:181], v[206:209], v[38:41]
	v_mfma_f32_16x16x32_bf16 v[22:25], v[178:181], v[214:217], v[22:25]
	v_mfma_f32_16x16x32_bf16 v[22:25], v[182:185], v[218:221], v[22:25]
	v_mfma_f32_16x16x32_bf16 v[6:9], v[182:185], v[226:229], v[6:9]
	v_mfma_f32_16x16x32_bf16 v[6:9], v[178:181], v[222:225], v[6:9]
	v_mfma_f32_16x16x32_bf16 v[2:5], v[186:189], v[222:225], v[2:5]
	v_mfma_f32_16x16x32_bf16 v[2:5], v[190:193], v[226:229], v[2:5]
	v_mfma_f32_16x16x32_bf16 v[18:21], v[190:193], v[218:221], v[18:21]
	v_mfma_f32_16x16x32_bf16 v[18:21], v[186:189], v[214:217], v[18:21]
	v_mfma_f32_16x16x32_bf16 v[34:37], v[186:189], v[206:209], v[34:37]
	v_mfma_f32_16x16x32_bf16 v[34:37], v[190:193], v[210:213], v[34:37]
	v_mfma_f32_16x16x32_bf16 v[50:53], v[190:193], v[202:205], v[50:53]
	v_mfma_f32_16x16x32_bf16 v[50:53], v[186:189], v[194:197], v[50:53]
	s_setprio 0
	s_barrier
	s_add_u32 s56, s56, 0x100
	s_addc_u32 s57, s57, 0
	s_add_u32 s90, s90, 0x100
	s_addc_u32 s91, s91, 0
	s_cmp_ge_i32 s92, s39
	s_mov_b32 s58, s92
	s_cbranch_scc0 .LBB0_1902
	s_and_b64 vcc, exec, s[24:25]
	s_cbranch_vccz .LBB0_1905

.LBB0_2138:
	ds_read_b128 v[146:149], v157
	ds_read_b128 v[164:167], v157 offset:1024
	ds_read_b128 v[168:171], v157 offset:2048
	ds_read_b128 v[172:175], v157 offset:3072
	ds_read_b128 v[176:179], v158
	ds_read_b128 v[180:183], v158 offset:1024
	ds_read_b128 v[184:187], v158 offset:2048
	ds_read_b128 v[188:191], v158 offset:3072
	s_add_u32 s24, s22, 0xfff00080
	s_addc_u32 s25, s23, -1
	s_cmp_eq_u32 s54, 60
	s_cselect_b32 s35, s15, s25
	s_cselect_b32 s34, s50, s24
	s_cselect_b32 s25, s13, s53
	s_cselect_b32 s24, s51, s52
	v_lshl_add_u64 v[150:151], s[22:23], 0, v[138:139]
	s_add_i32 m0, s21, 0xc000
	ds_read_b128 v[192:195], v159
	ds_read_b128 v[196:199], v159 offset:1024
	ds_read_b128 v[200:203], v159 offset:2048
	ds_read_b128 v[204:207], v159 offset:3072
	ds_read_b128 v[208:211], v159 offset:4096
	ds_read_b128 v[212:215], v159 offset:5120
	ds_read_b128 v[216:219], v159 offset:6144
	ds_read_b128 v[220:223], v159 offset:7168
	global_load_lds_dwordx4 v[150:151], off
	v_lshl_add_u64 v[150:151], s[22:23], 0, v[140:141]
	s_add_i32 m0, s21, 0xe000
	s_nop 0
	global_load_lds_dwordx4 v[150:151], off
	s_waitcnt vmcnt(8)
	s_waitcnt lgkmcnt(0)
	s_barrier
	s_setprio 1
	s_waitcnt lgkmcnt(0)
	v_mfma_f32_16x16x32_bf16 v[126:129], v[146:149], v[192:195], v[126:129]
	v_mfma_f32_16x16x32_bf16 v[126:129], v[164:167], v[196:199], v[126:129]
	v_mfma_f32_16x16x32_bf16 v[110:113], v[164:167], v[204:207], v[110:113]
	v_mfma_f32_16x16x32_bf16 v[110:113], v[146:149], v[200:203], v[110:113]
	v_mfma_f32_16x16x32_bf16 v[94:97], v[146:149], v[208:211], v[94:97]
	v_mfma_f32_16x16x32_bf16 v[94:97], v[164:167], v[212:215], v[94:97]
	v_mfma_f32_16x16x32_bf16 v[78:81], v[164:167], v[220:223], v[78:81]
	v_mfma_f32_16x16x32_bf16 v[78:81], v[146:149], v[216:219], v[78:81]
	v_mfma_f32_16x16x32_bf16 v[74:77], v[168:171], v[216:219], v[74:77]
	v_mfma_f32_16x16x32_bf16 v[74:77], v[172:175], v[220:223], v[74:77]
	v_mfma_f32_16x16x32_bf16 v[90:93], v[172:175], v[212:215], v[90:93]
	v_mfma_f32_16x16x32_bf16 v[90:93], v[168:171], v[208:211], v[90:93]
	v_mfma_f32_16x16x32_bf16 v[106:109], v[168:171], v[200:203], v[106:109]
	v_mfma_f32_16x16x32_bf16 v[106:109], v[172:175], v[204:207], v[106:109]
	v_mfma_f32_16x16x32_bf16 v[122:125], v[172:175], v[196:199], v[122:125]
	v_mfma_f32_16x16x32_bf16 v[122:125], v[168:171], v[192:195], v[122:125]
	v_mfma_f32_16x16x32_bf16 v[118:121], v[176:179], v[192:195], v[118:121]
	v_mfma_f32_16x16x32_bf16 v[118:121], v[180:183], v[196:199], v[118:121]
	v_mfma_f32_16x16x32_bf16 v[102:105], v[180:183], v[204:207], v[102:105]
	v_mfma_f32_16x16x32_bf16 v[102:105], v[176:179], v[200:203], v[102:105]
	v_mfma_f32_16x16x32_bf16 v[86:89], v[176:179], v[208:211], v[86:89]
	v_mfma_f32_16x16x32_bf16 v[86:89], v[180:183], v[212:215], v[86:89]
	v_mfma_f32_16x16x32_bf16 v[70:73], v[180:183], v[220:223], v[70:73]
	v_mfma_f32_16x16x32_bf16 v[70:73], v[176:179], v[216:219], v[70:73]
	v_mfma_f32_16x16x32_bf16 v[66:69], v[184:187], v[216:219], v[66:69]
	v_mfma_f32_16x16x32_bf16 v[66:69], v[188:191], v[220:223], v[66:69]
	v_mfma_f32_16x16x32_bf16 v[82:85], v[188:191], v[212:215], v[82:85]
	v_mfma_f32_16x16x32_bf16 v[82:85], v[184:187], v[208:211], v[82:85]
	v_mfma_f32_16x16x32_bf16 v[98:101], v[184:187], v[200:203], v[98:101]
	v_mfma_f32_16x16x32_bf16 v[98:101], v[188:191], v[204:207], v[98:101]
	v_mfma_f32_16x16x32_bf16 v[114:117], v[188:191], v[196:199], v[114:117]
	v_mfma_f32_16x16x32_bf16 v[114:117], v[184:187], v[192:195], v[114:117]
	s_setprio 0
	s_barrier
	s_add_i32 s55, s47, s27
	v_lshl_add_u64 v[150:151], s[24:25], 0, v[134:135]
	s_mov_b32 m0, s55
	ds_read_b128 v[192:195], v159 offset:16384
	ds_read_b128 v[196:199], v159 offset:17408
	ds_read_b128 v[200:203], v159 offset:18432
	ds_read_b128 v[204:207], v159 offset:19456
	ds_read_b128 v[208:211], v159 offset:20480
	ds_read_b128 v[212:215], v159 offset:21504
	ds_read_b128 v[216:219], v159 offset:22528
	ds_read_b128 v[220:223], v159 offset:23552
	global_load_lds_dwordx4 v[150:151], off
	s_add_i32 m0, s55, 0x2000
	s_add_u32 s56, s24, 0x100000
	v_lshl_add_u64 v[160:161], s[24:25], 0, v[130:131]
	s_addc_u32 s57, s25, 0
	s_add_i32 s55, s48, s27
	global_load_lds_dwordx4 v[160:161], off
	v_lshl_add_u64 v[224:225], s[56:57], 0, v[134:135]
	s_mov_b32 m0, s55
	v_lshl_add_u64 v[226:227], s[34:35], 0, v[132:133]
	global_load_lds_dwordx4 v[224:225], off
	v_lshl_add_u64 v[224:225], s[56:57], 0, v[130:131]
	s_add_i32 m0, s55, 0x2000
	s_nop 0
	global_load_lds_dwordx4 v[224:225], off
	v_lshl_add_u64 v[224:225], s[34:35], 0, v[136:137]
	s_mov_b32 m0, s21
	s_nop 0
	global_load_lds_dwordx4 v[224:225], off
	s_mov_b32 m0, s40
	s_nop 0
	global_load_lds_dwordx4 v[226:227], off
	s_waitcnt vmcnt(8)
	s_waitcnt lgkmcnt(0)
	s_barrier
	s_setprio 1
	s_waitcnt lgkmcnt(0)
	v_mfma_f32_16x16x32_bf16 v[62:65], v[146:149], v[192:195], v[62:65]
	v_mfma_f32_16x16x32_bf16 v[62:65], v[164:167], v[196:199], v[62:65]
	v_mfma_f32_16x16x32_bf16 v[46:49], v[164:167], v[204:207], v[46:49]
	v_mfma_f32_16x16x32_bf16 v[46:49], v[146:149], v[200:203], v[46:49]
	v_mfma_f32_16x16x32_bf16 v[30:33], v[146:149], v[208:211], v[30:33]
	v_mfma_f32_16x16x32_bf16 v[30:33], v[164:167], v[212:215], v[30:33]
	v_mfma_f32_16x16x32_bf16 v[14:17], v[164:167], v[220:223], v[14:17]
	v_mfma_f32_16x16x32_bf16 v[14:17], v[146:149], v[216:219], v[14:17]
	v_mfma_f32_16x16x32_bf16 v[10:13], v[168:171], v[216:219], v[10:13]
	v_mfma_f32_16x16x32_bf16 v[10:13], v[172:175], v[220:223], v[10:13]
	v_mfma_f32_16x16x32_bf16 v[26:29], v[172:175], v[212:215], v[26:29]
	v_mfma_f32_16x16x32_bf16 v[26:29], v[168:171], v[208:211], v[26:29]
	v_mfma_f32_16x16x32_bf16 v[42:45], v[168:171], v[200:203], v[42:45]
	v_mfma_f32_16x16x32_bf16 v[42:45], v[172:175], v[204:207], v[42:45]
	v_mfma_f32_16x16x32_bf16 v[58:61], v[172:175], v[196:199], v[58:61]
	v_mfma_f32_16x16x32_bf16 v[58:61], v[168:171], v[192:195], v[58:61]
	v_mfma_f32_16x16x32_bf16 v[54:57], v[176:179], v[192:195], v[54:57]
	v_mfma_f32_16x16x32_bf16 v[54:57], v[180:183], v[196:199], v[54:57]
	v_mfma_f32_16x16x32_bf16 v[38:41], v[180:183], v[204:207], v[38:41]
	v_mfma_f32_16x16x32_bf16 v[38:41], v[176:179], v[200:203], v[38:41]
	v_mfma_f32_16x16x32_bf16 v[22:25], v[176:179], v[208:211], v[22:25]
	v_mfma_f32_16x16x32_bf16 v[22:25], v[180:183], v[212:215], v[22:25]
	v_mfma_f32_16x16x32_bf16 v[6:9], v[180:183], v[220:223], v[6:9]
	v_mfma_f32_16x16x32_bf16 v[6:9], v[176:179], v[216:219], v[6:9]
	v_mfma_f32_16x16x32_bf16 v[2:5], v[184:187], v[216:219], v[2:5]
	v_mfma_f32_16x16x32_bf16 v[2:5], v[188:191], v[220:223], v[2:5]
	v_mfma_f32_16x16x32_bf16 v[18:21], v[188:191], v[212:215], v[18:21]
	v_mfma_f32_16x16x32_bf16 v[18:21], v[184:187], v[208:211], v[18:21]
	v_mfma_f32_16x16x32_bf16 v[34:37], v[184:187], v[200:203], v[34:37]
	v_mfma_f32_16x16x32_bf16 v[34:37], v[188:191], v[204:207], v[34:37]
	v_mfma_f32_16x16x32_bf16 v[50:53], v[188:191], v[196:199], v[50:53]
	v_mfma_f32_16x16x32_bf16 v[50:53], v[184:187], v[192:195], v[50:53]
	s_setprio 0
	s_barrier
	s_add_i32 s55, 0, 0x18000
	v_add_u32_e32 v162, s55, v155
	s_add_i32 s56, 0, 0x1c000
	ds_read_b128 v[146:149], v162
	ds_read_b128 v[164:167], v162 offset:1024
	ds_read_b128 v[168:171], v162 offset:2048
	ds_read_b128 v[172:175], v162 offset:3072
	v_add_u32_e32 v162, s56, v155
	ds_read_b128 v[176:179], v162
	ds_read_b128 v[180:183], v162 offset:1024
	ds_read_b128 v[184:187], v162 offset:2048
	ds_read_b128 v[188:191], v162 offset:3072
	s_add_u32 s34, s34, 0x100000
	s_addc_u32 s35, s35, 0
	s_mov_b32 m0, s41
	v_lshl_add_u64 v[228:229], s[34:35], 0, v[136:137]
	ds_read_b128 v[192:195], v159 offset:32768
	ds_read_b128 v[196:199], v159 offset:33792
	ds_read_b128 v[200:203], v159 offset:34816
	ds_read_b128 v[204:207], v159 offset:35840
	ds_read_b128 v[208:211], v159 offset:36864
	ds_read_b128 v[212:215], v159 offset:37888
	ds_read_b128 v[216:219], v159 offset:38912
	ds_read_b128 v[220:223], v159 offset:39936
	global_load_lds_dwordx4 v[228:229], off
	v_lshl_add_u64 v[228:229], s[34:35], 0, v[132:133]
	s_mov_b32 m0, s42
	s_nop 0
	global_load_lds_dwordx4 v[228:229], off
	s_waitcnt vmcnt(8)
	s_waitcnt lgkmcnt(0)
	s_barrier
	s_setprio 1
	s_waitcnt lgkmcnt(0)
	v_mfma_f32_16x16x32_bf16 v[126:129], v[146:149], v[192:195], v[126:129]
	v_mfma_f32_16x16x32_bf16 v[126:129], v[164:167], v[196:199], v[126:129]
	v_mfma_f32_16x16x32_bf16 v[110:113], v[164:167], v[204:207], v[110:113]
	v_mfma_f32_16x16x32_bf16 v[110:113], v[146:149], v[200:203], v[110:113]
	v_mfma_f32_16x16x32_bf16 v[94:97], v[146:149], v[208:211], v[94:97]
	v_mfma_f32_16x16x32_bf16 v[94:97], v[164:167], v[212:215], v[94:97]
	v_mfma_f32_16x16x32_bf16 v[78:81], v[164:167], v[220:223], v[78:81]
	v_mfma_f32_16x16x32_bf16 v[78:81], v[146:149], v[216:219], v[78:81]
	v_mfma_f32_16x16x32_bf16 v[74:77], v[168:171], v[216:219], v[74:77]
	v_mfma_f32_16x16x32_bf16 v[74:77], v[172:175], v[220:223], v[74:77]
	v_mfma_f32_16x16x32_bf16 v[90:93], v[172:175], v[212:215], v[90:93]
	v_mfma_f32_16x16x32_bf16 v[90:93], v[168:171], v[208:211], v[90:93]
	v_mfma_f32_16x16x32_bf16 v[106:109], v[168:171], v[200:203], v[106:109]
	v_mfma_f32_16x16x32_bf16 v[106:109], v[172:175], v[204:207], v[106:109]
	v_mfma_f32_16x16x32_bf16 v[122:125], v[172:175], v[196:199], v[122:125]
	v_mfma_f32_16x16x32_bf16 v[122:125], v[168:171], v[192:195], v[122:125]
	v_mfma_f32_16x16x32_bf16 v[118:121], v[176:179], v[192:195], v[118:121]
	v_mfma_f32_16x16x32_bf16 v[118:121], v[180:183], v[196:199], v[118:121]
	v_mfma_f32_16x16x32_bf16 v[102:105], v[180:183], v[204:207], v[102:105]
	v_mfma_f32_16x16x32_bf16 v[102:105], v[176:179], v[200:203], v[102:105]
	v_mfma_f32_16x16x32_bf16 v[86:89], v[176:179], v[208:211], v[86:89]
	v_mfma_f32_16x16x32_bf16 v[86:89], v[180:183], v[212:215], v[86:89]
	v_mfma_f32_16x16x32_bf16 v[70:73], v[180:183], v[220:223], v[70:73]
	v_mfma_f32_16x16x32_bf16 v[70:73], v[176:179], v[216:219], v[70:73]
	v_mfma_f32_16x16x32_bf16 v[66:69], v[184:187], v[216:219], v[66:69]
	v_mfma_f32_16x16x32_bf16 v[66:69], v[188:191], v[220:223], v[66:69]
	v_mfma_f32_16x16x32_bf16 v[82:85], v[188:191], v[212:215], v[82:85]
	v_mfma_f32_16x16x32_bf16 v[82:85], v[184:187], v[208:211], v[82:85]
	v_mfma_f32_16x16x32_bf16 v[98:101], v[184:187], v[200:203], v[98:101]
	v_mfma_f32_16x16x32_bf16 v[98:101], v[188:191], v[204:207], v[98:101]
	v_mfma_f32_16x16x32_bf16 v[114:117], v[188:191], v[196:199], v[114:117]
	v_mfma_f32_16x16x32_bf16 v[114:117], v[184:187], v[192:195], v[114:117]
	s_setprio 0
	s_barrier
	s_add_i32 s34, s55, s27
	v_lshl_add_u64 v[150:151], v[150:151], 0, s[8:9]
	s_mov_b32 m0, s34
	ds_read_b128 v[192:195], v159 offset:49152
	ds_read_b128 v[196:199], v159 offset:50176
	ds_read_b128 v[200:203], v159 offset:51200
	ds_read_b128 v[204:207], v159 offset:52224
	ds_read_b128 v[208:211], v159 offset:53248
	ds_read_b128 v[212:215], v159 offset:54272
	ds_read_b128 v[216:219], v159 offset:55296
	ds_read_b128 v[220:223], v159 offset:56320
	global_load_lds_dwordx4 v[150:151], off
	s_add_i32 m0, s34, 0x2000
	s_add_u32 s24, s24, 0x100080
	v_lshl_add_u64 v[150:151], v[160:161], 0, s[8:9]
	s_addc_u32 s25, s25, 0
	s_add_i32 s34, s56, s27
	global_load_lds_dwordx4 v[150:151], off
	v_lshl_add_u64 v[150:151], s[24:25], 0, v[134:135]
	s_mov_b32 m0, s34
	s_nop 0
	global_load_lds_dwordx4 v[150:151], off
	v_lshl_add_u64 v[150:151], s[24:25], 0, v[130:131]
	s_add_i32 m0, s34, 0x2000
	s_nop 0
	global_load_lds_dwordx4 v[150:151], off
	v_lshl_add_u64 v[150:151], v[224:225], 0, s[8:9]
	s_mov_b32 m0, s44
	s_nop 0
	global_load_lds_dwordx4 v[150:151], off
	v_lshl_add_u64 v[150:151], v[226:227], 0, s[8:9]
	s_mov_b32 m0, s45
	s_nop 0
	global_load_lds_dwordx4 v[150:151], off
	s_waitcnt vmcnt(8)
	s_waitcnt lgkmcnt(0)
	s_barrier
	s_setprio 1
	s_waitcnt lgkmcnt(0)
	v_mfma_f32_16x16x32_bf16 v[62:65], v[146:149], v[192:195], v[62:65]
	v_mfma_f32_16x16x32_bf16 v[62:65], v[164:167], v[196:199], v[62:65]
	v_mfma_f32_16x16x32_bf16 v[46:49], v[164:167], v[204:207], v[46:49]
	v_mfma_f32_16x16x32_bf16 v[46:49], v[146:149], v[200:203], v[46:49]
	v_mfma_f32_16x16x32_bf16 v[30:33], v[146:149], v[208:211], v[30:33]
	v_mfma_f32_16x16x32_bf16 v[30:33], v[164:167], v[212:215], v[30:33]
	v_mfma_f32_16x16x32_bf16 v[14:17], v[164:167], v[220:223], v[14:17]
	v_mfma_f32_16x16x32_bf16 v[14:17], v[146:149], v[216:219], v[14:17]
	v_mfma_f32_16x16x32_bf16 v[10:13], v[168:171], v[216:219], v[10:13]
	v_mfma_f32_16x16x32_bf16 v[10:13], v[172:175], v[220:223], v[10:13]
	v_mfma_f32_16x16x32_bf16 v[26:29], v[172:175], v[212:215], v[26:29]
	v_mfma_f32_16x16x32_bf16 v[26:29], v[168:171], v[208:211], v[26:29]
	v_mfma_f32_16x16x32_bf16 v[42:45], v[168:171], v[200:203], v[42:45]
	v_mfma_f32_16x16x32_bf16 v[42:45], v[172:175], v[204:207], v[42:45]
	v_mfma_f32_16x16x32_bf16 v[58:61], v[172:175], v[196:199], v[58:61]
	v_mfma_f32_16x16x32_bf16 v[58:61], v[168:171], v[192:195], v[58:61]
	v_mfma_f32_16x16x32_bf16 v[54:57], v[176:179], v[192:195], v[54:57]
	v_mfma_f32_16x16x32_bf16 v[54:57], v[180:183], v[196:199], v[54:57]
	v_mfma_f32_16x16x32_bf16 v[38:41], v[180:183], v[204:207], v[38:41]
	v_mfma_f32_16x16x32_bf16 v[38:41], v[176:179], v[200:203], v[38:41]
	v_mfma_f32_16x16x32_bf16 v[22:25], v[176:179], v[208:211], v[22:25]
	v_mfma_f32_16x16x32_bf16 v[22:25], v[180:183], v[212:215], v[22:25]
	v_mfma_f32_16x16x32_bf16 v[6:9], v[180:183], v[220:223], v[6:9]
	v_mfma_f32_16x16x32_bf16 v[6:9], v[176:179], v[216:219], v[6:9]
	v_mfma_f32_16x16x32_bf16 v[2:5], v[184:187], v[216:219], v[2:5]
	v_mfma_f32_16x16x32_bf16 v[2:5], v[188:191], v[220:223], v[2:5]
	v_mfma_f32_16x16x32_bf16 v[18:21], v[188:191], v[212:215], v[18:21]
	v_mfma_f32_16x16x32_bf16 v[18:21], v[184:187], v[208:211], v[18:21]
	v_mfma_f32_16x16x32_bf16 v[34:37], v[184:187], v[200:203], v[34:37]
	v_mfma_f32_16x16x32_bf16 v[34:37], v[188:191], v[204:207], v[34:37]
	v_mfma_f32_16x16x32_bf16 v[50:53], v[188:191], v[196:199], v[50:53]
	v_mfma_f32_16x16x32_bf16 v[50:53], v[184:187], v[192:195], v[50:53]
	s_setprio 0
	s_barrier
	s_add_i32 s54, s54, 2
	s_add_u32 s22, s22, 0x100
	s_addc_u32 s23, s23, 0
	s_add_u32 s52, s52, 0x100
	s_addc_u32 s53, s53, 0
	s_cmp_gt_u32 s54, 61
	s_cbranch_scc0 .LBB0_2138
	s_and_b64 vcc, exec, s[10:11]
	s_cbranch_vccz .LBB0_2141
	s_barrier

.LBB0_2158:
	ds_read_b128 v[146:149], v157
	ds_read_b128 v[164:167], v157 offset:1024
	ds_read_b128 v[168:171], v157 offset:2048
	ds_read_b128 v[172:175], v157 offset:3072
	ds_read_b128 v[176:179], v158
	ds_read_b128 v[180:183], v158 offset:1024
	ds_read_b128 v[184:187], v158 offset:2048
	ds_read_b128 v[188:191], v158 offset:3072
	s_add_u32 s26, s24, 0xfff00080
	s_addc_u32 s27, s25, -1
	s_cmp_eq_u32 s52, 60
	s_cselect_b32 s35, s17, s27
	s_cselect_b32 s34, s48, s26
	s_cselect_b32 s27, s15, s51
	s_cselect_b32 s26, s49, s50
	v_lshl_add_u64 v[150:151], s[24:25], 0, v[138:139]
	s_add_i32 m0, s23, 0xc000
	ds_read_b128 v[192:195], v159
	ds_read_b128 v[196:199], v159 offset:1024
	ds_read_b128 v[200:203], v159 offset:2048
	ds_read_b128 v[204:207], v159 offset:3072
	ds_read_b128 v[208:211], v159 offset:4096
	ds_read_b128 v[212:215], v159 offset:5120
	ds_read_b128 v[216:219], v159 offset:6144
	ds_read_b128 v[220:223], v159 offset:7168
	global_load_lds_dwordx4 v[150:151], off
	v_lshl_add_u64 v[150:151], s[24:25], 0, v[140:141]
	s_add_i32 m0, s23, 0xe000
	s_nop 0
	global_load_lds_dwordx4 v[150:151], off
	s_waitcnt vmcnt(8)
	s_waitcnt lgkmcnt(0)
	s_barrier
	s_setprio 1
	s_waitcnt lgkmcnt(0)
	v_mfma_f32_16x16x32_bf16 v[126:129], v[146:149], v[192:195], v[126:129]
	v_mfma_f32_16x16x32_bf16 v[126:129], v[164:167], v[196:199], v[126:129]
	v_mfma_f32_16x16x32_bf16 v[110:113], v[164:167], v[204:207], v[110:113]
	v_mfma_f32_16x16x32_bf16 v[110:113], v[146:149], v[200:203], v[110:113]
	v_mfma_f32_16x16x32_bf16 v[94:97], v[146:149], v[208:211], v[94:97]
	v_mfma_f32_16x16x32_bf16 v[94:97], v[164:167], v[212:215], v[94:97]
	v_mfma_f32_16x16x32_bf16 v[78:81], v[164:167], v[220:223], v[78:81]
	v_mfma_f32_16x16x32_bf16 v[78:81], v[146:149], v[216:219], v[78:81]
	v_mfma_f32_16x16x32_bf16 v[74:77], v[168:171], v[216:219], v[74:77]
	v_mfma_f32_16x16x32_bf16 v[74:77], v[172:175], v[220:223], v[74:77]
	v_mfma_f32_16x16x32_bf16 v[90:93], v[172:175], v[212:215], v[90:93]
	v_mfma_f32_16x16x32_bf16 v[90:93], v[168:171], v[208:211], v[90:93]
	v_mfma_f32_16x16x32_bf16 v[106:109], v[168:171], v[200:203], v[106:109]
	v_mfma_f32_16x16x32_bf16 v[106:109], v[172:175], v[204:207], v[106:109]
	v_mfma_f32_16x16x32_bf16 v[122:125], v[172:175], v[196:199], v[122:125]
	v_mfma_f32_16x16x32_bf16 v[122:125], v[168:171], v[192:195], v[122:125]
	v_mfma_f32_16x16x32_bf16 v[118:121], v[176:179], v[192:195], v[118:121]
	v_mfma_f32_16x16x32_bf16 v[118:121], v[180:183], v[196:199], v[118:121]
	v_mfma_f32_16x16x32_bf16 v[102:105], v[180:183], v[204:207], v[102:105]
	v_mfma_f32_16x16x32_bf16 v[102:105], v[176:179], v[200:203], v[102:105]
	v_mfma_f32_16x16x32_bf16 v[86:89], v[176:179], v[208:211], v[86:89]
	v_mfma_f32_16x16x32_bf16 v[86:89], v[180:183], v[212:215], v[86:89]
	v_mfma_f32_16x16x32_bf16 v[70:73], v[180:183], v[220:223], v[70:73]
	v_mfma_f32_16x16x32_bf16 v[70:73], v[176:179], v[216:219], v[70:73]
	v_mfma_f32_16x16x32_bf16 v[66:69], v[184:187], v[216:219], v[66:69]
	v_mfma_f32_16x16x32_bf16 v[66:69], v[188:191], v[220:223], v[66:69]
	v_mfma_f32_16x16x32_bf16 v[82:85], v[188:191], v[212:215], v[82:85]
	v_mfma_f32_16x16x32_bf16 v[82:85], v[184:187], v[208:211], v[82:85]
	v_mfma_f32_16x16x32_bf16 v[98:101], v[184:187], v[200:203], v[98:101]
	v_mfma_f32_16x16x32_bf16 v[98:101], v[188:191], v[204:207], v[98:101]
	v_mfma_f32_16x16x32_bf16 v[114:117], v[188:191], v[196:199], v[114:117]
	v_mfma_f32_16x16x32_bf16 v[114:117], v[184:187], v[192:195], v[114:117]
	s_setprio 0
	s_barrier
	s_add_i32 s53, s45, s38
	v_lshl_add_u64 v[150:151], s[26:27], 0, v[132:133]
	s_mov_b32 m0, s53
	ds_read_b128 v[192:195], v159 offset:16384
	ds_read_b128 v[196:199], v159 offset:17408
	ds_read_b128 v[200:203], v159 offset:18432
	ds_read_b128 v[204:207], v159 offset:19456
	ds_read_b128 v[208:211], v159 offset:20480
	ds_read_b128 v[212:215], v159 offset:21504
	ds_read_b128 v[216:219], v159 offset:22528
	ds_read_b128 v[220:223], v159 offset:23552
	global_load_lds_dwordx4 v[150:151], off
	s_add_i32 m0, s53, 0x2000
	s_add_u32 s54, s26, 0x100000
	v_lshl_add_u64 v[160:161], s[26:27], 0, v[134:135]
	s_addc_u32 s55, s27, 0
	s_add_i32 s53, s46, s38
	global_load_lds_dwordx4 v[160:161], off
	v_lshl_add_u64 v[224:225], s[54:55], 0, v[132:133]
	s_mov_b32 m0, s53
	v_lshl_add_u64 v[226:227], s[34:35], 0, v[136:137]
	global_load_lds_dwordx4 v[224:225], off
	v_lshl_add_u64 v[224:225], s[54:55], 0, v[134:135]
	s_add_i32 m0, s53, 0x2000
	s_nop 0
	global_load_lds_dwordx4 v[224:225], off
	v_lshl_add_u64 v[224:225], s[34:35], 0, v[130:131]
	s_mov_b32 m0, s23
	s_nop 0
	global_load_lds_dwordx4 v[224:225], off
	s_mov_b32 m0, s40
	s_nop 0
	global_load_lds_dwordx4 v[226:227], off
	s_waitcnt vmcnt(8)
	s_waitcnt lgkmcnt(0)
	s_barrier
	s_setprio 1
	s_waitcnt lgkmcnt(0)
	v_mfma_f32_16x16x32_bf16 v[62:65], v[146:149], v[192:195], v[62:65]
	v_mfma_f32_16x16x32_bf16 v[62:65], v[164:167], v[196:199], v[62:65]
	v_mfma_f32_16x16x32_bf16 v[46:49], v[164:167], v[204:207], v[46:49]
	v_mfma_f32_16x16x32_bf16 v[46:49], v[146:149], v[200:203], v[46:49]
	v_mfma_f32_16x16x32_bf16 v[30:33], v[146:149], v[208:211], v[30:33]
	v_mfma_f32_16x16x32_bf16 v[30:33], v[164:167], v[212:215], v[30:33]
	v_mfma_f32_16x16x32_bf16 v[14:17], v[164:167], v[220:223], v[14:17]
	v_mfma_f32_16x16x32_bf16 v[14:17], v[146:149], v[216:219], v[14:17]
	v_mfma_f32_16x16x32_bf16 v[10:13], v[168:171], v[216:219], v[10:13]
	v_mfma_f32_16x16x32_bf16 v[10:13], v[172:175], v[220:223], v[10:13]
	v_mfma_f32_16x16x32_bf16 v[26:29], v[172:175], v[212:215], v[26:29]
	v_mfma_f32_16x16x32_bf16 v[26:29], v[168:171], v[208:211], v[26:29]
	v_mfma_f32_16x16x32_bf16 v[42:45], v[168:171], v[200:203], v[42:45]
	v_mfma_f32_16x16x32_bf16 v[42:45], v[172:175], v[204:207], v[42:45]
	v_mfma_f32_16x16x32_bf16 v[58:61], v[172:175], v[196:199], v[58:61]
	v_mfma_f32_16x16x32_bf16 v[58:61], v[168:171], v[192:195], v[58:61]
	v_mfma_f32_16x16x32_bf16 v[54:57], v[176:179], v[192:195], v[54:57]
	v_mfma_f32_16x16x32_bf16 v[54:57], v[180:183], v[196:199], v[54:57]
	v_mfma_f32_16x16x32_bf16 v[38:41], v[180:183], v[204:207], v[38:41]
	v_mfma_f32_16x16x32_bf16 v[38:41], v[176:179], v[200:203], v[38:41]
	v_mfma_f32_16x16x32_bf16 v[22:25], v[176:179], v[208:211], v[22:25]
	v_mfma_f32_16x16x32_bf16 v[22:25], v[180:183], v[212:215], v[22:25]
	v_mfma_f32_16x16x32_bf16 v[6:9], v[180:183], v[220:223], v[6:9]
	v_mfma_f32_16x16x32_bf16 v[6:9], v[176:179], v[216:219], v[6:9]
	v_mfma_f32_16x16x32_bf16 v[2:5], v[184:187], v[216:219], v[2:5]
	v_mfma_f32_16x16x32_bf16 v[2:5], v[188:191], v[220:223], v[2:5]
	v_mfma_f32_16x16x32_bf16 v[18:21], v[188:191], v[212:215], v[18:21]
	v_mfma_f32_16x16x32_bf16 v[18:21], v[184:187], v[208:211], v[18:21]
	v_mfma_f32_16x16x32_bf16 v[34:37], v[184:187], v[200:203], v[34:37]
	v_mfma_f32_16x16x32_bf16 v[34:37], v[188:191], v[204:207], v[34:37]
	v_mfma_f32_16x16x32_bf16 v[50:53], v[188:191], v[196:199], v[50:53]
	v_mfma_f32_16x16x32_bf16 v[50:53], v[184:187], v[192:195], v[50:53]
	s_setprio 0
	s_barrier
	s_add_i32 s53, 0, 0x18000
	v_add_u32_e32 v162, s53, v155
	s_add_i32 s54, 0, 0x1c000
	ds_read_b128 v[146:149], v162
	ds_read_b128 v[164:167], v162 offset:1024
	ds_read_b128 v[168:171], v162 offset:2048
	ds_read_b128 v[172:175], v162 offset:3072
	v_add_u32_e32 v162, s54, v155
	ds_read_b128 v[176:179], v162
	ds_read_b128 v[180:183], v162 offset:1024
	ds_read_b128 v[184:187], v162 offset:2048
	ds_read_b128 v[188:191], v162 offset:3072
	s_add_u32 s34, s34, 0x100000
	s_addc_u32 s35, s35, 0
	s_mov_b32 m0, s41
	v_lshl_add_u64 v[228:229], s[34:35], 0, v[130:131]
	ds_read_b128 v[192:195], v159 offset:32768
	ds_read_b128 v[196:199], v159 offset:33792
	ds_read_b128 v[200:203], v159 offset:34816
	ds_read_b128 v[204:207], v159 offset:35840
	ds_read_b128 v[208:211], v159 offset:36864
	ds_read_b128 v[212:215], v159 offset:37888
	ds_read_b128 v[216:219], v159 offset:38912
	ds_read_b128 v[220:223], v159 offset:39936
	global_load_lds_dwordx4 v[228:229], off
	v_lshl_add_u64 v[228:229], s[34:35], 0, v[136:137]
	s_mov_b32 m0, s42
	s_nop 0
	global_load_lds_dwordx4 v[228:229], off
	s_waitcnt vmcnt(8)
	s_waitcnt lgkmcnt(0)
	s_barrier
	s_setprio 1
	s_waitcnt lgkmcnt(0)
	v_mfma_f32_16x16x32_bf16 v[126:129], v[146:149], v[192:195], v[126:129]
	v_mfma_f32_16x16x32_bf16 v[126:129], v[164:167], v[196:199], v[126:129]
	v_mfma_f32_16x16x32_bf16 v[110:113], v[164:167], v[204:207], v[110:113]
	v_mfma_f32_16x16x32_bf16 v[110:113], v[146:149], v[200:203], v[110:113]
	v_mfma_f32_16x16x32_bf16 v[94:97], v[146:149], v[208:211], v[94:97]
	v_mfma_f32_16x16x32_bf16 v[94:97], v[164:167], v[212:215], v[94:97]
	v_mfma_f32_16x16x32_bf16 v[78:81], v[164:167], v[220:223], v[78:81]
	v_mfma_f32_16x16x32_bf16 v[78:81], v[146:149], v[216:219], v[78:81]
	v_mfma_f32_16x16x32_bf16 v[74:77], v[168:171], v[216:219], v[74:77]
	v_mfma_f32_16x16x32_bf16 v[74:77], v[172:175], v[220:223], v[74:77]
	v_mfma_f32_16x16x32_bf16 v[90:93], v[172:175], v[212:215], v[90:93]
	v_mfma_f32_16x16x32_bf16 v[90:93], v[168:171], v[208:211], v[90:93]
	v_mfma_f32_16x16x32_bf16 v[106:109], v[168:171], v[200:203], v[106:109]
	v_mfma_f32_16x16x32_bf16 v[106:109], v[172:175], v[204:207], v[106:109]
	v_mfma_f32_16x16x32_bf16 v[122:125], v[172:175], v[196:199], v[122:125]
	v_mfma_f32_16x16x32_bf16 v[122:125], v[168:171], v[192:195], v[122:125]
	v_mfma_f32_16x16x32_bf16 v[118:121], v[176:179], v[192:195], v[118:121]
	v_mfma_f32_16x16x32_bf16 v[118:121], v[180:183], v[196:199], v[118:121]
	v_mfma_f32_16x16x32_bf16 v[102:105], v[180:183], v[204:207], v[102:105]
	v_mfma_f32_16x16x32_bf16 v[102:105], v[176:179], v[200:203], v[102:105]
	v_mfma_f32_16x16x32_bf16 v[86:89], v[176:179], v[208:211], v[86:89]
	v_mfma_f32_16x16x32_bf16 v[86:89], v[180:183], v[212:215], v[86:89]
	v_mfma_f32_16x16x32_bf16 v[70:73], v[180:183], v[220:223], v[70:73]
	v_mfma_f32_16x16x32_bf16 v[70:73], v[176:179], v[216:219], v[70:73]
	v_mfma_f32_16x16x32_bf16 v[66:69], v[184:187], v[216:219], v[66:69]
	v_mfma_f32_16x16x32_bf16 v[66:69], v[188:191], v[220:223], v[66:69]
	v_mfma_f32_16x16x32_bf16 v[82:85], v[188:191], v[212:215], v[82:85]
	v_mfma_f32_16x16x32_bf16 v[82:85], v[184:187], v[208:211], v[82:85]
	v_mfma_f32_16x16x32_bf16 v[98:101], v[184:187], v[200:203], v[98:101]
	v_mfma_f32_16x16x32_bf16 v[98:101], v[188:191], v[204:207], v[98:101]
	v_mfma_f32_16x16x32_bf16 v[114:117], v[188:191], v[196:199], v[114:117]
	v_mfma_f32_16x16x32_bf16 v[114:117], v[184:187], v[192:195], v[114:117]
	s_setprio 0
	s_barrier
	s_add_i32 s34, s53, s38
	v_lshl_add_u64 v[150:151], v[150:151], 0, s[10:11]
	s_mov_b32 m0, s34
	ds_read_b128 v[192:195], v159 offset:49152
	ds_read_b128 v[196:199], v159 offset:50176
	ds_read_b128 v[200:203], v159 offset:51200
	ds_read_b128 v[204:207], v159 offset:52224
	ds_read_b128 v[208:211], v159 offset:53248
	ds_read_b128 v[212:215], v159 offset:54272
	ds_read_b128 v[216:219], v159 offset:55296
	ds_read_b128 v[220:223], v159 offset:56320
	global_load_lds_dwordx4 v[150:151], off
	s_add_i32 m0, s34, 0x2000
	s_add_u32 s26, s26, 0x100080
	v_lshl_add_u64 v[150:151], v[160:161], 0, s[10:11]
	s_addc_u32 s27, s27, 0
	s_add_i32 s34, s54, s38
	global_load_lds_dwordx4 v[150:151], off
	v_lshl_add_u64 v[150:151], s[26:27], 0, v[132:133]
	s_mov_b32 m0, s34
	s_nop 0
	global_load_lds_dwordx4 v[150:151], off
	v_lshl_add_u64 v[150:151], s[26:27], 0, v[134:135]
	s_add_i32 m0, s34, 0x2000
	s_nop 0
	global_load_lds_dwordx4 v[150:151], off
	v_lshl_add_u64 v[150:151], v[224:225], 0, s[10:11]
	s_mov_b32 m0, s43
	s_nop 0
	global_load_lds_dwordx4 v[150:151], off
	v_lshl_add_u64 v[150:151], v[226:227], 0, s[10:11]
	s_mov_b32 m0, s44
	s_nop 0
	global_load_lds_dwordx4 v[150:151], off
	s_waitcnt vmcnt(8)
	s_waitcnt lgkmcnt(0)
	s_barrier
	s_setprio 1
	s_waitcnt lgkmcnt(0)
	v_mfma_f32_16x16x32_bf16 v[62:65], v[146:149], v[192:195], v[62:65]
	v_mfma_f32_16x16x32_bf16 v[62:65], v[164:167], v[196:199], v[62:65]
	v_mfma_f32_16x16x32_bf16 v[46:49], v[164:167], v[204:207], v[46:49]
	v_mfma_f32_16x16x32_bf16 v[46:49], v[146:149], v[200:203], v[46:49]
	v_mfma_f32_16x16x32_bf16 v[30:33], v[146:149], v[208:211], v[30:33]
	v_mfma_f32_16x16x32_bf16 v[30:33], v[164:167], v[212:215], v[30:33]
	v_mfma_f32_16x16x32_bf16 v[14:17], v[164:167], v[220:223], v[14:17]
	v_mfma_f32_16x16x32_bf16 v[14:17], v[146:149], v[216:219], v[14:17]
	v_mfma_f32_16x16x32_bf16 v[10:13], v[168:171], v[216:219], v[10:13]
	v_mfma_f32_16x16x32_bf16 v[10:13], v[172:175], v[220:223], v[10:13]
	v_mfma_f32_16x16x32_bf16 v[26:29], v[172:175], v[212:215], v[26:29]
	v_mfma_f32_16x16x32_bf16 v[26:29], v[168:171], v[208:211], v[26:29]
	v_mfma_f32_16x16x32_bf16 v[42:45], v[168:171], v[200:203], v[42:45]
	v_mfma_f32_16x16x32_bf16 v[42:45], v[172:175], v[204:207], v[42:45]
	v_mfma_f32_16x16x32_bf16 v[58:61], v[172:175], v[196:199], v[58:61]
	v_mfma_f32_16x16x32_bf16 v[58:61], v[168:171], v[192:195], v[58:61]
	v_mfma_f32_16x16x32_bf16 v[54:57], v[176:179], v[192:195], v[54:57]
	v_mfma_f32_16x16x32_bf16 v[54:57], v[180:183], v[196:199], v[54:57]
	v_mfma_f32_16x16x32_bf16 v[38:41], v[180:183], v[204:207], v[38:41]
	v_mfma_f32_16x16x32_bf16 v[38:41], v[176:179], v[200:203], v[38:41]
	v_mfma_f32_16x16x32_bf16 v[22:25], v[176:179], v[208:211], v[22:25]
	v_mfma_f32_16x16x32_bf16 v[22:25], v[180:183], v[212:215], v[22:25]
	v_mfma_f32_16x16x32_bf16 v[6:9], v[180:183], v[220:223], v[6:9]
	v_mfma_f32_16x16x32_bf16 v[6:9], v[176:179], v[216:219], v[6:9]
	v_mfma_f32_16x16x32_bf16 v[2:5], v[184:187], v[216:219], v[2:5]
	v_mfma_f32_16x16x32_bf16 v[2:5], v[188:191], v[220:223], v[2:5]
	v_mfma_f32_16x16x32_bf16 v[18:21], v[188:191], v[212:215], v[18:21]
	v_mfma_f32_16x16x32_bf16 v[18:21], v[184:187], v[208:211], v[18:21]
	v_mfma_f32_16x16x32_bf16 v[34:37], v[184:187], v[200:203], v[34:37]
	v_mfma_f32_16x16x32_bf16 v[34:37], v[188:191], v[204:207], v[34:37]
	v_mfma_f32_16x16x32_bf16 v[50:53], v[188:191], v[196:199], v[50:53]
	v_mfma_f32_16x16x32_bf16 v[50:53], v[184:187], v[192:195], v[50:53]
	s_setprio 0
	s_barrier
	s_add_i32 s52, s52, 2
	s_add_u32 s24, s24, 0x100
	s_addc_u32 s25, s25, 0
	s_add_u32 s50, s50, 0x100
	s_addc_u32 s51, s51, 0
	s_cmp_gt_u32 s52, 61
	s_cbranch_scc0 .LBB0_2158
	s_and_b64 vcc, exec, s[12:13]
	s_cbranch_vccz .LBB0_2161
	s_barrier
